# v3 + removed the mid-block s_setprio 0/1 pairs inside the 32-MFMA compute segments of all GEMM K-loops
# speedup vs baseline: 1.0004x; 1.0004x over previous
; #define PG8_STAGE(bufoff, gbase, voff) do { _Pragma("unroll") for (int _i = 0; _i < 2; ++_i) \
;         __builtin_amdgcn_global_load_lds((const unsigned*)((const char*)(gbase) + (voff)[_i]), (PG8_LAS unsigned*)(lds + (bufoff) + ldsw + _i * 8192), 16, 0, 0); } while (0)
; #define PG8_LDA(dst, b, h) do { _Pragma("unroll") for (int m = 0; m < 4; ++m) _Pragma("unroll") for (int k = 0; k < 2; ++k) dst[m][k] = *(const PG8_LAS bf16x8*)(lds + PG8_SA(b, h) + aoff + m * 2048 + k * 1024); } while (0)
; #define PG8_LDB(dst, b, h) do { _Pragma("unroll") for (int n = 0; n < 2; ++n) _Pragma("unroll") for (int k = 0; k < 2; ++k) dst[n][k] = *(const PG8_LAS bf16x8*)(lds + PG8_SB(b, h) + boff + n * 2048 + k * 1024); } while (0)
; #define PG8_MMA(ai, bj, At, Bt) do { __builtin_amdgcn_s_setprio(1); _Pragma("unroll") for (int m = 0; m < 4; ++m) _Pragma("unroll") for (int n = 0; n < 2; ++n) _Pragma("unroll") for (int k = 0; k < 2; ++k) \
;         acc[ai][bj][m][n] = __builtin_amdgcn_mfma_f32_16x16x32_bf16(Bt[n][k], At[m][k], acc[ai][bj][m][n], 0, 0, 0); __builtin_amdgcn_s_setprio(0); } while (0)
; #define PG8_WAIT_V(n) asm volatile("s_waitcnt vmcnt(" #n ")" ::: "memory")
; #define PG8_WAIT_L(n) asm volatile("s_waitcnt lgkmcnt(" #n ")" ::: "memory")
; #define PG8_BAR __builtin_amdgcn_s_barrier()
; #define PG8_SCHED __builtin_amdgcn_sched_barrier(0)
; template <class Epi, class Sched, bool ALIGN_EPI = false, bool SP2 = false>
; __device__ __forceinline__ void gemm_phase(PG8_LAS unsigned char* lds, const Gemm g, const Sched& S, const Epi& E) {
;     ...
;         for (int t = 0; t < nt; t += 2) {
;             const bool last = (t == nt - 2);
;             const char* a1 = cA + (size_t)(t + 1) * kstep;
;             const char* a2 = last ? nA : cA + (size_t)(t + 2) * kstep; const char* b2 = last ? nB : cB + (size_t)(t + 2) * kstep;
;             const char* a3 = a2 + kstep; const char* b3 = b2 + kstep;
;             if (last && has_next) S.a_ready(nxt);
;             if constexpr (SP2) {
;             PG8_LDB(B0, 0, 0); PG8_LDB(B1, 0, 1); PG8_SCHED; PG8_LDA(At, 0, 0); PG8_STAGE(PG8_SA(1, 1), a1 + hstepA, voffA);
;             PG8_WAIT_V(8); PG8_WAIT_L(0); PG8_BAR; PG8_MMA(0, 0, At, B0); PG8_MMA(0, 1, At, B1); PG8_BAR; PG8_SCHED;
;             PG8_LDA(At, 0, 1); PG8_STAGE(PG8_SB(0, 0), b2, voffB); PG8_STAGE(PG8_SB(0, 1), b2 + hstepB, voffB); PG8_STAGE(PG8_SA(0, 0), a2, voffA);
.LBB0_126:
	s_add_u32 s6, s0, 0xfff80080
	s_addc_u32 s7, s1, -1
	s_add_i32 s24, 0, 0x10000
	s_cmp_eq_u32 s41, 28
	s_cselect_b32 s9, s5, s7
	s_cselect_b32 s8, s10, s6
	s_cselect_b32 s7, s11, s39
	s_cselect_b32 s6, s36, s37
	s_add_i32 s26, 0, 0x14000
	v_add_u32_e32 v142, s24, v211
	v_add_u32_e32 v162, s26, v211
	ds_read_b128 v[6:9], v142
	ds_read_b128 v[14:17], v142 offset:1024
	ds_read_b128 v[34:37], v142 offset:2048
	ds_read_b128 v[142:145], v142 offset:3072
	ds_read_b128 v[178:181], v162
	ds_read_b128 v[182:185], v162 offset:1024
	ds_read_b128 v[186:189], v162 offset:2048
	ds_read_b128 v[190:193], v162 offset:3072
	v_lshl_add_u64 v[194:195], s[0:1], 0, v[158:159]
	s_add_i32 m0, s15, 0xc000
	ds_read_b128 v[214:217], v213
	ds_read_b128 v[218:221], v213 offset:1024
	ds_read_b128 v[222:225], v213 offset:2048
	ds_read_b128 v[226:229], v213 offset:3072
	ds_read_b128 v[230:233], v213 offset:4096
	ds_read_b128 v[234:237], v213 offset:5120
	ds_read_b128 v[238:241], v213 offset:6144
	ds_read_b128 v[242:245], v213 offset:7168
	global_load_lds_dwordx4 v[194:195], off
	v_lshl_add_u64 v[194:195], s[0:1], 0, v[160:161]
	s_add_i32 m0, s15, 0xe000
	s_nop 0
	global_load_lds_dwordx4 v[194:195], off
	s_waitcnt vmcnt(8)
	s_waitcnt lgkmcnt(0)
	s_barrier
	s_setprio 1
	s_waitcnt lgkmcnt(0)
	v_mfma_f32_16x16x32_bf16 v[138:141], v[6:9], v[214:217], v[138:141]
	v_mfma_f32_16x16x32_bf16 v[134:137], v[34:37], v[214:217], v[134:137]
	v_mfma_f32_16x16x32_bf16 v[122:125], v[6:9], v[222:225], v[122:125]
	v_mfma_f32_16x16x32_bf16 v[118:121], v[34:37], v[222:225], v[118:121]
	v_mfma_f32_16x16x32_bf16 v[106:109], v[6:9], v[230:233], v[106:109]
	v_mfma_f32_16x16x32_bf16 v[102:105], v[34:37], v[230:233], v[102:105]
	v_mfma_f32_16x16x32_bf16 v[90:93], v[6:9], v[238:241], v[90:93]
	v_mfma_f32_16x16x32_bf16 v[86:89], v[34:37], v[238:241], v[86:89]
	v_mfma_f32_16x16x32_bf16 v[138:141], v[14:17], v[218:221], v[138:141]
	v_mfma_f32_16x16x32_bf16 v[134:137], v[142:145], v[218:221], v[134:137]
	v_mfma_f32_16x16x32_bf16 v[122:125], v[14:17], v[226:229], v[122:125]
	v_mfma_f32_16x16x32_bf16 v[118:121], v[142:145], v[226:229], v[118:121]
	v_mfma_f32_16x16x32_bf16 v[106:109], v[14:17], v[234:237], v[106:109]
	v_mfma_f32_16x16x32_bf16 v[102:105], v[142:145], v[234:237], v[102:105]
	v_mfma_f32_16x16x32_bf16 v[90:93], v[14:17], v[242:245], v[90:93]
	v_mfma_f32_16x16x32_bf16 v[86:89], v[142:145], v[242:245], v[86:89]
	v_mfma_f32_16x16x32_bf16 v[130:133], v[178:181], v[214:217], v[130:133]
	v_mfma_f32_16x16x32_bf16 v[126:129], v[186:189], v[214:217], v[126:129]
	v_mfma_f32_16x16x32_bf16 v[114:117], v[178:181], v[222:225], v[114:117]
	v_mfma_f32_16x16x32_bf16 v[110:113], v[186:189], v[222:225], v[110:113]
	v_mfma_f32_16x16x32_bf16 v[98:101], v[178:181], v[230:233], v[98:101]
	v_mfma_f32_16x16x32_bf16 v[94:97], v[186:189], v[230:233], v[94:97]
	v_mfma_f32_16x16x32_bf16 v[82:85], v[178:181], v[238:241], v[82:85]
	v_mfma_f32_16x16x32_bf16 v[78:81], v[186:189], v[238:241], v[78:81]
	v_mfma_f32_16x16x32_bf16 v[130:133], v[182:185], v[218:221], v[130:133]
	v_mfma_f32_16x16x32_bf16 v[126:129], v[190:193], v[218:221], v[126:129]
	v_mfma_f32_16x16x32_bf16 v[114:117], v[182:185], v[226:229], v[114:117]
	v_mfma_f32_16x16x32_bf16 v[110:113], v[190:193], v[226:229], v[110:113]
	v_mfma_f32_16x16x32_bf16 v[98:101], v[182:185], v[234:237], v[98:101]
	v_mfma_f32_16x16x32_bf16 v[94:97], v[190:193], v[234:237], v[94:97]
	v_mfma_f32_16x16x32_bf16 v[82:85], v[182:185], v[242:245], v[82:85]
	v_mfma_f32_16x16x32_bf16 v[78:81], v[190:193], v[242:245], v[78:81]
	s_setprio 0
	s_barrier
	s_add_i32 s24, s24, s14
	v_lshl_add_u64 v[194:195], s[6:7], 0, v[148:149]
	s_mov_b32 m0, s24
	ds_read_b128 v[214:217], v213 offset:16384
	ds_read_b128 v[218:221], v213 offset:17408
	ds_read_b128 v[222:225], v213 offset:18432
	ds_read_b128 v[226:229], v213 offset:19456
	ds_read_b128 v[230:233], v213 offset:20480
	ds_read_b128 v[234:237], v213 offset:21504
	ds_read_b128 v[238:241], v213 offset:22528
	ds_read_b128 v[242:245], v213 offset:23552
	global_load_lds_dwordx4 v[194:195], off
	s_add_i32 m0, s24, 0x2000
	s_add_u32 s24, s6, 0x80000
	v_lshl_add_u64 v[246:247], s[6:7], 0, v[152:153]
	s_addc_u32 s25, s7, 0
	s_add_i32 s26, s26, s14
	global_load_lds_dwordx4 v[246:247], off
	v_lshl_add_u64 v[168:169], s[24:25], 0, v[148:149]
	s_mov_b32 m0, s26
	v_lshl_add_u64 v[170:171], s[8:9], 0, v[150:151]
	global_load_lds_dwordx4 v[168:169], off
	v_lshl_add_u64 v[168:169], s[24:25], 0, v[152:153]
	s_add_i32 m0, s26, 0x2000
	s_nop 0
	global_load_lds_dwordx4 v[168:169], off
	v_lshl_add_u64 v[168:169], s[8:9], 0, v[146:147]
	s_mov_b32 m0, s15
	s_nop 0
	global_load_lds_dwordx4 v[168:169], off
	s_mov_b32 m0, s16
	s_nop 0
	global_load_lds_dwordx4 v[170:171], off
	s_waitcnt vmcnt(8)
	s_waitcnt lgkmcnt(0)
	s_barrier
; #define PG8_STAGE(bufoff, gbase, voff) do { _Pragma("unroll") for (int _i = 0; _i < 2; ++_i) \
;         __builtin_amdgcn_global_load_lds((const unsigned*)((const char*)(gbase) + (voff)[_i]), (PG8_LAS unsigned*)(lds + (bufoff) + ldsw + _i * 8192), 16, 0, 0); } while (0)
; #define PG8_LDA(dst, b, h) do { _Pragma("unroll") for (int m = 0; m < 4; ++m) _Pragma("unroll") for (int k = 0; k < 2; ++k) dst[m][k] = *(const PG8_LAS bf16x8*)(lds + PG8_SA(b, h) + aoff + m * 2048 + k * 1024); } while (0)
; #define PG8_LDB(dst, b, h) do { _Pragma("unroll") for (int n = 0; n < 2; ++n) _Pragma("unroll") for (int k = 0; k < 2; ++k) dst[n][k] = *(const PG8_LAS bf16x8*)(lds + PG8_SB(b, h) + boff + n * 2048 + k * 1024); } while (0)
; #define PG8_MMA(ai, bj, At, Bt) do { __builtin_amdgcn_s_setprio(1); _Pragma("unroll") for (int m = 0; m < 4; ++m) _Pragma("unroll") for (int n = 0; n < 2; ++n) _Pragma("unroll") for (int k = 0; k < 2; ++k) \
;         acc[ai][bj][m][n] = __builtin_amdgcn_mfma_f32_16x16x32_bf16(Bt[n][k], At[m][k], acc[ai][bj][m][n], 0, 0, 0); __builtin_amdgcn_s_setprio(0); } while (0)
; #define PG8_WAIT_V(n) asm volatile("s_waitcnt vmcnt(" #n ")" ::: "memory")
; #define PG8_WAIT_L(n) asm volatile("s_waitcnt lgkmcnt(" #n ")" ::: "memory")
; #define PG8_BAR __builtin_amdgcn_s_barrier()
; #define PG8_SCHED __builtin_amdgcn_sched_barrier(0)
; template <class Epi, class Sched, bool ALIGN_EPI = false, bool SP2 = false>
; __device__ __forceinline__ void gemm_phase(PG8_LAS unsigned char* lds, const Gemm g, const Sched& S, const Epi& E) {
;     ...
;             PG8_WAIT_V(8); PG8_WAIT_L(0); PG8_BAR; PG8_MMA(1, 0, At, B0); PG8_MMA(1, 1, At, B1); PG8_BAR; PG8_SCHED;
;             PG8_LDB(B0, 1, 0); PG8_LDB(B1, 1, 1); PG8_SCHED; PG8_LDA(At, 1, 0); PG8_STAGE(PG8_SA(0, 1), a2 + hstepA, voffA);
;             PG8_WAIT_V(8); PG8_WAIT_L(0); PG8_BAR; PG8_MMA(0, 0, At, B0); PG8_MMA(0, 1, At, B1); PG8_BAR; PG8_SCHED;
	s_setprio 1
	s_waitcnt lgkmcnt(0)
	v_mfma_f32_16x16x32_bf16 v[74:77], v[6:9], v[214:217], v[74:77]
	v_mfma_f32_16x16x32_bf16 v[70:73], v[34:37], v[214:217], v[70:73]
	v_mfma_f32_16x16x32_bf16 v[58:61], v[6:9], v[222:225], v[58:61]
	v_mfma_f32_16x16x32_bf16 v[54:57], v[34:37], v[222:225], v[54:57]
	v_mfma_f32_16x16x32_bf16 v[42:45], v[6:9], v[230:233], v[42:45]
	v_mfma_f32_16x16x32_bf16 v[38:41], v[34:37], v[230:233], v[38:41]
	v_mfma_f32_16x16x32_bf16 v[10:13], v[34:37], v[238:241], v[10:13]
	v_mfma_f32_16x16x32_bf16 v[74:77], v[14:17], v[218:221], v[74:77]
	v_mfma_f32_16x16x32_bf16 v[70:73], v[142:145], v[218:221], v[70:73]
	v_mfma_f32_16x16x32_bf16 v[58:61], v[14:17], v[226:229], v[58:61]
	v_mfma_f32_16x16x32_bf16 v[54:57], v[142:145], v[226:229], v[54:57]
	v_mfma_f32_16x16x32_bf16 v[42:45], v[14:17], v[234:237], v[42:45]
	v_mfma_f32_16x16x32_bf16 v[38:41], v[142:145], v[234:237], v[38:41]
	v_mfma_f32_16x16x32_bf16 v[6:9], v[6:9], v[238:241], v[22:25]
	v_mfma_f32_16x16x32_bf16 v[10:13], v[142:145], v[242:245], v[10:13]
	v_mfma_f32_16x16x32_bf16 v[6:9], v[14:17], v[242:245], v[6:9]
	v_mfma_f32_16x16x32_bf16 v[22:25], v[186:189], v[214:217], v[62:65]
	v_mfma_f32_16x16x32_bf16 v[34:37], v[190:193], v[218:221], v[22:25]
	v_mfma_f32_16x16x32_bf16 v[22:25], v[178:181], v[222:225], v[50:53]
	v_mfma_f32_16x16x32_bf16 v[50:53], v[182:185], v[226:229], v[22:25]
	v_mfma_f32_16x16x32_bf16 v[22:25], v[186:189], v[222:225], v[46:49]
	v_mfma_f32_16x16x32_bf16 v[46:49], v[190:193], v[226:229], v[22:25]
	v_mfma_f32_16x16x32_bf16 v[22:25], v[178:181], v[230:233], v[30:33]
	v_mfma_f32_16x16x32_bf16 v[30:33], v[182:185], v[234:237], v[22:25]
	v_mfma_f32_16x16x32_bf16 v[22:25], v[186:189], v[230:233], v[26:29]
	v_mfma_f32_16x16x32_bf16 v[2:5], v[178:181], v[238:241], v[2:5]
	v_mfma_f32_16x16x32_bf16 v[18:21], v[186:189], v[238:241], v[18:21]
	v_mfma_f32_16x16x32_bf16 v[14:17], v[178:181], v[214:217], v[66:69]
	v_mfma_f32_16x16x32_bf16 v[26:29], v[190:193], v[234:237], v[22:25]
	v_mfma_f32_16x16x32_bf16 v[2:5], v[182:185], v[242:245], v[2:5]
	v_mfma_f32_16x16x32_bf16 v[18:21], v[190:193], v[242:245], v[18:21]
	v_mfma_f32_16x16x32_bf16 v[14:17], v[182:185], v[218:221], v[14:17]
	s_setprio 0
	s_barrier
	s_add_i32 s24, 0, 0x18000
	s_add_i32 s25, 0, 0x1c000
	v_add_u32_e32 v142, s24, v211
	v_add_u32_e32 v162, s25, v211
	ds_read_b128 v[22:25], v142
	ds_read_b128 v[62:65], v142 offset:1024
	ds_read_b128 v[66:69], v142 offset:2048
	ds_read_b128 v[142:145], v142 offset:3072
	ds_read_b128 v[178:181], v162
	ds_read_b128 v[182:185], v162 offset:1024
	ds_read_b128 v[186:189], v162 offset:2048
	ds_read_b128 v[190:193], v162 offset:3072
	s_add_u32 s8, s8, 0x80000
	s_addc_u32 s9, s9, 0
	s_mov_b32 m0, s17
	v_lshl_add_u64 v[172:173], s[8:9], 0, v[146:147]
	ds_read_b128 v[214:217], v213 offset:32768
	ds_read_b128 v[218:221], v213 offset:33792
	ds_read_b128 v[222:225], v213 offset:34816
	ds_read_b128 v[226:229], v213 offset:35840
	ds_read_b128 v[230:233], v213 offset:36864
	ds_read_b128 v[234:237], v213 offset:37888
	ds_read_b128 v[238:241], v213 offset:38912
	ds_read_b128 v[242:245], v213 offset:39936
	global_load_lds_dwordx4 v[172:173], off
	v_lshl_add_u64 v[172:173], s[8:9], 0, v[150:151]
	s_mov_b32 m0, s18
	s_nop 0
	global_load_lds_dwordx4 v[172:173], off
	s_waitcnt vmcnt(8)
	s_waitcnt lgkmcnt(0)
	s_barrier
	s_setprio 1
	s_waitcnt lgkmcnt(0)
	v_mfma_f32_16x16x32_bf16 v[138:141], v[22:25], v[214:217], v[138:141]
	v_mfma_f32_16x16x32_bf16 v[134:137], v[66:69], v[214:217], v[134:137]
	v_mfma_f32_16x16x32_bf16 v[122:125], v[22:25], v[222:225], v[122:125]
	v_mfma_f32_16x16x32_bf16 v[118:121], v[66:69], v[222:225], v[118:121]
	v_mfma_f32_16x16x32_bf16 v[106:109], v[22:25], v[230:233], v[106:109]
	v_mfma_f32_16x16x32_bf16 v[102:105], v[66:69], v[230:233], v[102:105]
	v_mfma_f32_16x16x32_bf16 v[90:93], v[22:25], v[238:241], v[90:93]
	v_mfma_f32_16x16x32_bf16 v[86:89], v[66:69], v[238:241], v[86:89]
	v_mfma_f32_16x16x32_bf16 v[138:141], v[62:65], v[218:221], v[138:141]
	v_mfma_f32_16x16x32_bf16 v[134:137], v[142:145], v[218:221], v[134:137]
	v_mfma_f32_16x16x32_bf16 v[122:125], v[62:65], v[226:229], v[122:125]
	v_mfma_f32_16x16x32_bf16 v[118:121], v[142:145], v[226:229], v[118:121]
	v_mfma_f32_16x16x32_bf16 v[106:109], v[62:65], v[234:237], v[106:109]
	v_mfma_f32_16x16x32_bf16 v[102:105], v[142:145], v[234:237], v[102:105]
	v_mfma_f32_16x16x32_bf16 v[90:93], v[62:65], v[242:245], v[90:93]
	v_mfma_f32_16x16x32_bf16 v[86:89], v[142:145], v[242:245], v[86:89]
	v_mfma_f32_16x16x32_bf16 v[130:133], v[178:181], v[214:217], v[130:133]
	v_mfma_f32_16x16x32_bf16 v[126:129], v[186:189], v[214:217], v[126:129]
	v_mfma_f32_16x16x32_bf16 v[114:117], v[178:181], v[222:225], v[114:117]
	v_mfma_f32_16x16x32_bf16 v[110:113], v[186:189], v[222:225], v[110:113]
	v_mfma_f32_16x16x32_bf16 v[98:101], v[178:181], v[230:233], v[98:101]
	v_mfma_f32_16x16x32_bf16 v[94:97], v[186:189], v[230:233], v[94:97]
	v_mfma_f32_16x16x32_bf16 v[82:85], v[178:181], v[238:241], v[82:85]
	v_mfma_f32_16x16x32_bf16 v[78:81], v[186:189], v[238:241], v[78:81]
	v_mfma_f32_16x16x32_bf16 v[130:133], v[182:185], v[218:221], v[130:133]
	v_mfma_f32_16x16x32_bf16 v[126:129], v[190:193], v[218:221], v[126:129]
	v_mfma_f32_16x16x32_bf16 v[114:117], v[182:185], v[226:229], v[114:117]
	v_mfma_f32_16x16x32_bf16 v[110:113], v[190:193], v[226:229], v[110:113]
	v_mfma_f32_16x16x32_bf16 v[98:101], v[182:185], v[234:237], v[98:101]
	v_mfma_f32_16x16x32_bf16 v[94:97], v[190:193], v[234:237], v[94:97]
	v_mfma_f32_16x16x32_bf16 v[82:85], v[182:185], v[242:245], v[82:85]
	v_mfma_f32_16x16x32_bf16 v[78:81], v[190:193], v[242:245], v[78:81]
	s_setprio 0
	s_barrier
; #define PG8_STAGE(bufoff, gbase, voff) do { _Pragma("unroll") for (int _i = 0; _i < 2; ++_i) \
;         __builtin_amdgcn_global_load_lds((const unsigned*)((const char*)(gbase) + (voff)[_i]), (PG8_LAS unsigned*)(lds + (bufoff) + ldsw + _i * 8192), 16, 0, 0); } while (0)
; #define PG8_LDA(dst, b, h) do { _Pragma("unroll") for (int m = 0; m < 4; ++m) _Pragma("unroll") for (int k = 0; k < 2; ++k) dst[m][k] = *(const PG8_LAS bf16x8*)(lds + PG8_SA(b, h) + aoff + m * 2048 + k * 1024); } while (0)
; #define PG8_WAIT_V(n) asm volatile("s_waitcnt vmcnt(" #n ")" ::: "memory")
; template <class Epi, class Sched, bool ALIGN_EPI = false, bool SP2 = false>
; __device__ __forceinline__ void gemm_phase(PG8_LAS unsigned char* lds, const Gemm g, const Sched& S, const Epi& E) {
;     ...
;             PG8_LDA(At, 1, 1); PG8_STAGE(PG8_SB(1, 0), b3, voffB); PG8_STAGE(PG8_SB(1, 1), b3 + hstepB, voffB); PG8_STAGE(PG8_SA(1, 0), a3, voffA);
;             PG8_WAIT_V(8); PG8_WAIT_L(0); PG8_BAR; PG8_MMA(1, 0, At, B0); PG8_MMA(1, 1, At, B1); PG8_BAR; PG8_SCHED;
;             } else {
;             PG8_LDB(B0, 0, 0); PG8_SCHED; PG8_LDA(At, 0, 0); PG8_STAGE(PG8_SA(1, 1), a1 + hstepA, voffA);
;             PG8_WAIT_L(8); PG8_BAR; PG8_WAIT_L(0); PG8_MMA(0, 0, At, B0); PG8_BAR; PG8_SCHED;
;             PG8_LDB(B1, 0, 1); PG8_STAGE(PG8_SB(0, 0), b2, voffB);
;             PG8_BAR; PG8_WAIT_L(0); PG8_MMA(0, 1, At, B1); PG8_BAR;
;             PG8_LDA(At, 0, 1); PG8_STAGE(PG8_SA(0, 0), a2, voffA);
;             PG8_BAR; PG8_WAIT_L(0); PG8_MMA(1, 0, At, B0); PG8_BAR; PG8_SCHED;
;             PG8_STAGE(PG8_SB(0, 1), b2 + hstepB, voffB);
;             PG8_WAIT_V(6); PG8_BAR; PG8_MMA(1, 1, At, B1); PG8_BAR;
;             PG8_LDB(B0, 1, 0); PG8_SCHED; PG8_LDA(At, 1, 0); PG8_STAGE(PG8_SA(0, 1), a2 + hstepA, voffA);
;             PG8_WAIT_L(8); PG8_BAR; PG8_WAIT_L(0); PG8_MMA(0, 0, At, B0); PG8_BAR; PG8_SCHED;
;             PG8_LDB(B1, 1, 1); PG8_STAGE(PG8_SB(1, 0), b3, voffB);
;             PG8_BAR; PG8_WAIT_L(0); PG8_MMA(0, 1, At, B1); PG8_BAR;
;             PG8_LDA(At, 1, 1); PG8_STAGE(PG8_SA(1, 0), a3, voffA);
;             PG8_BAR; PG8_WAIT_L(0); PG8_MMA(1, 0, At, B0); PG8_BAR; PG8_SCHED;
;             PG8_STAGE(PG8_SB(1, 1), b3 + hstepB, voffB);
;             PG8_WAIT_V(6); PG8_BAR; PG8_MMA(1, 1, At, B1); PG8_BAR;
;             }
;         }
;         if constexpr (ALIGN_EPI) { if (wr == 0) PG8_BAR; }
	s_add_i32 s8, s24, s14
	v_lshl_add_u64 v[172:173], v[194:195], 0, s[50:51]
	s_mov_b32 m0, s8
	ds_read_b128 v[214:217], v213 offset:49152
	ds_read_b128 v[218:221], v213 offset:50176
	ds_read_b128 v[222:225], v213 offset:51200
	ds_read_b128 v[226:229], v213 offset:52224
	ds_read_b128 v[230:233], v213 offset:53248
	ds_read_b128 v[234:237], v213 offset:54272
	ds_read_b128 v[238:241], v213 offset:55296
	ds_read_b128 v[242:245], v213 offset:56320
	global_load_lds_dwordx4 v[172:173], off
	s_add_i32 m0, s8, 0x2000
	s_add_u32 s6, s6, 0x80080
	v_lshl_add_u64 v[172:173], v[246:247], 0, s[50:51]
	s_addc_u32 s7, s7, 0
	s_add_i32 s8, s25, s14
	global_load_lds_dwordx4 v[172:173], off
	v_lshl_add_u64 v[172:173], s[6:7], 0, v[148:149]
	s_mov_b32 m0, s8
	v_lshl_add_u64 v[168:169], v[168:169], 0, s[50:51]
	global_load_lds_dwordx4 v[172:173], off
	v_lshl_add_u64 v[172:173], s[6:7], 0, v[152:153]
	s_add_i32 m0, s8, 0x2000
	s_nop 0
	global_load_lds_dwordx4 v[172:173], off
	s_mov_b32 m0, s21
	s_nop 0
	global_load_lds_dwordx4 v[168:169], off
	v_lshl_add_u64 v[168:169], v[170:171], 0, s[50:51]
	s_mov_b32 m0, s22
	s_nop 0
	global_load_lds_dwordx4 v[168:169], off
	s_waitcnt vmcnt(8)
	s_waitcnt lgkmcnt(0)
	s_barrier
	s_setprio 1
	s_waitcnt lgkmcnt(0)
	v_mfma_f32_16x16x32_bf16 v[6:9], v[22:25], v[238:241], v[6:9]
	v_mfma_f32_16x16x32_bf16 v[74:77], v[22:25], v[214:217], v[74:77]
	v_mfma_f32_16x16x32_bf16 v[70:73], v[66:69], v[214:217], v[70:73]
	v_mfma_f32_16x16x32_bf16 v[58:61], v[22:25], v[222:225], v[58:61]
	v_mfma_f32_16x16x32_bf16 v[54:57], v[66:69], v[222:225], v[54:57]
	v_mfma_f32_16x16x32_bf16 v[42:45], v[22:25], v[230:233], v[42:45]
	v_mfma_f32_16x16x32_bf16 v[38:41], v[66:69], v[230:233], v[38:41]
	v_mfma_f32_16x16x32_bf16 v[22:25], v[62:65], v[242:245], v[6:9]
	v_mfma_f32_16x16x32_bf16 v[6:9], v[66:69], v[238:241], v[10:13]
	v_mfma_f32_16x16x32_bf16 v[74:77], v[62:65], v[218:221], v[74:77]
	v_mfma_f32_16x16x32_bf16 v[70:73], v[142:145], v[218:221], v[70:73]
	v_mfma_f32_16x16x32_bf16 v[58:61], v[62:65], v[226:229], v[58:61]
	v_mfma_f32_16x16x32_bf16 v[54:57], v[142:145], v[226:229], v[54:57]
	v_mfma_f32_16x16x32_bf16 v[42:45], v[62:65], v[234:237], v[42:45]
	v_mfma_f32_16x16x32_bf16 v[38:41], v[142:145], v[234:237], v[38:41]
	v_mfma_f32_16x16x32_bf16 v[10:13], v[142:145], v[242:245], v[6:9]
	v_mfma_f32_16x16x32_bf16 v[6:9], v[178:181], v[214:217], v[14:17]
	v_mfma_f32_16x16x32_bf16 v[66:69], v[182:185], v[218:221], v[6:9]
	v_mfma_f32_16x16x32_bf16 v[6:9], v[186:189], v[214:217], v[34:37]
	v_mfma_f32_16x16x32_bf16 v[62:65], v[190:193], v[218:221], v[6:9]
	v_mfma_f32_16x16x32_bf16 v[6:9], v[178:181], v[222:225], v[50:53]
	v_mfma_f32_16x16x32_bf16 v[50:53], v[182:185], v[226:229], v[6:9]
	v_mfma_f32_16x16x32_bf16 v[6:9], v[186:189], v[222:225], v[46:49]
	v_mfma_f32_16x16x32_bf16 v[46:49], v[190:193], v[226:229], v[6:9]
	v_mfma_f32_16x16x32_bf16 v[6:9], v[178:181], v[230:233], v[30:33]
	v_mfma_f32_16x16x32_bf16 v[30:33], v[182:185], v[234:237], v[6:9]
	v_mfma_f32_16x16x32_bf16 v[6:9], v[186:189], v[230:233], v[26:29]
	v_mfma_f32_16x16x32_bf16 v[26:29], v[190:193], v[234:237], v[6:9]
	v_mfma_f32_16x16x32_bf16 v[2:5], v[178:181], v[238:241], v[2:5]
	v_mfma_f32_16x16x32_bf16 v[6:9], v[186:189], v[238:241], v[18:21]
	v_mfma_f32_16x16x32_bf16 v[2:5], v[182:185], v[242:245], v[2:5]
	v_mfma_f32_16x16x32_bf16 v[18:21], v[190:193], v[242:245], v[6:9]
	s_setprio 0
	s_barrier
	s_add_i32 s41, s41, 2
	s_add_u32 s0, s0, 0x100
	s_addc_u32 s1, s1, 0
	s_add_u32 s37, s37, 0x100
	s_addc_u32 s39, s39, 0
	s_cmp_gt_u32 s41, 29
	s_cbranch_scc0 .LBB0_126
	s_and_b64 vcc, exec, s[44:45]
	s_cbranch_vccz .LBB0_129
	s_barrier

; #define PG8_STAGE(bufoff, gbase, voff) do { _Pragma("unroll") for (int _i = 0; _i < 2; ++_i) \
;         __builtin_amdgcn_global_load_lds((const unsigned*)((const char*)(gbase) + (voff)[_i]), (PG8_LAS unsigned*)(lds + (bufoff) + ldsw + _i * 8192), 16, 0, 0); } while (0)
; #define PG8_LDA(dst, b, h) do { _Pragma("unroll") for (int m = 0; m < 4; ++m) _Pragma("unroll") for (int k = 0; k < 2; ++k) dst[m][k] = *(const PG8_LAS bf16x8*)(lds + PG8_SA(b, h) + aoff + m * 2048 + k * 1024); } while (0)
; #define PG8_LDB(dst, b, h) do { _Pragma("unroll") for (int n = 0; n < 2; ++n) _Pragma("unroll") for (int k = 0; k < 2; ++k) dst[n][k] = *(const PG8_LAS bf16x8*)(lds + PG8_SB(b, h) + boff + n * 2048 + k * 1024); } while (0)
; #define PG8_MMA(ai, bj, At, Bt) do { __builtin_amdgcn_s_setprio(1); _Pragma("unroll") for (int m = 0; m < 4; ++m) _Pragma("unroll") for (int n = 0; n < 2; ++n) _Pragma("unroll") for (int k = 0; k < 2; ++k) \
;         acc[ai][bj][m][n] = __builtin_amdgcn_mfma_f32_16x16x32_bf16(Bt[n][k], At[m][k], acc[ai][bj][m][n], 0, 0, 0); __builtin_amdgcn_s_setprio(0); } while (0)
; #define PG8_WAIT_V(n) asm volatile("s_waitcnt vmcnt(" #n ")" ::: "memory")
; #define PG8_WAIT_L(n) asm volatile("s_waitcnt lgkmcnt(" #n ")" ::: "memory")
; #define PG8_BAR __builtin_amdgcn_s_barrier()
; #define PG8_SCHED __builtin_amdgcn_sched_barrier(0)
; template <class Epi, class Sched, bool ALIGN_EPI = false, bool SP2 = false>
; __device__ __forceinline__ void gemm_phase(PG8_LAS unsigned char* lds, const Gemm g, const Sched& S, const Epi& E) {
;     ...
;         for (int t = 0; t < nt; t += 2) {
;             const bool last = (t == nt - 2);
;             const char* a1 = cA + (size_t)(t + 1) * kstep;
;             const char* a2 = last ? nA : cA + (size_t)(t + 2) * kstep; const char* b2 = last ? nB : cB + (size_t)(t + 2) * kstep;
;             const char* a3 = a2 + kstep; const char* b3 = b2 + kstep;
;             if (last && has_next) S.a_ready(nxt);
;             if constexpr (SP2) {
;             PG8_LDB(B0, 0, 0); PG8_LDB(B1, 0, 1); PG8_SCHED; PG8_LDA(At, 0, 0); PG8_STAGE(PG8_SA(1, 1), a1 + hstepA, voffA);
;             PG8_WAIT_V(8); PG8_WAIT_L(0); PG8_BAR; PG8_MMA(0, 0, At, B0); PG8_MMA(0, 1, At, B1); PG8_BAR; PG8_SCHED;
;             PG8_LDA(At, 0, 1); PG8_STAGE(PG8_SB(0, 0), b2, voffB); PG8_STAGE(PG8_SB(0, 1), b2 + hstepB, voffB); PG8_STAGE(PG8_SA(0, 0), a2, voffA);
.LBB0_1693:
	s_add_u32 s8, s4, 0xfffc0080
	s_addc_u32 s9, s5, -1
	s_add_i32 s24, 0, 0x10000
	s_cmp_eq_u32 s23, 12
	s_cselect_b32 s11, s57, s9
	s_cselect_b32 s10, s56, s8
	v_add_u32_e32 v148, s24, v150
	s_cselect_b32 s9, s93, s22
	s_cselect_b32 s8, s92, s21
	s_add_i32 s26, 0, 0x14000
	ds_read_b128 v[140:143], v148
	ds_read_b128 v[144:147], v148 offset:1024
	ds_read_b128 v[154:157], v148 offset:2048
	ds_read_b128 v[158:161], v148 offset:3072
	v_add_u32_e32 v148, s26, v150
	ds_read_b128 v[178:181], v148
	ds_read_b128 v[182:185], v148 offset:1024
	ds_read_b128 v[186:189], v148 offset:2048
	ds_read_b128 v[190:193], v148 offset:3072
	v_lshl_add_u64 v[148:149], s[4:5], 0, v[136:137]
	s_add_i32 m0, s13, 0xc000
	ds_read_b128 v[210:213], v152
	ds_read_b128 v[214:217], v152 offset:1024
	ds_read_b128 v[218:221], v152 offset:2048
	ds_read_b128 v[222:225], v152 offset:3072
	ds_read_b128 v[226:229], v152 offset:4096
	ds_read_b128 v[230:233], v152 offset:5120
	ds_read_b128 v[234:237], v152 offset:6144
	ds_read_b128 v[238:241], v152 offset:7168
	global_load_lds_dwordx4 v[148:149], off
	v_lshl_add_u64 v[148:149], s[4:5], 0, v[138:139]
	s_add_i32 m0, s13, 0xe000
	s_nop 0
	global_load_lds_dwordx4 v[148:149], off
	s_waitcnt vmcnt(8)
	s_waitcnt lgkmcnt(0)
	s_barrier
	s_setprio 1
	s_waitcnt lgkmcnt(0)
	v_mfma_f32_16x16x32_bf16 v[126:129], v[140:143], v[210:213], v[126:129]
	v_mfma_f32_16x16x32_bf16 v[122:125], v[154:157], v[210:213], v[122:125]
	v_mfma_f32_16x16x32_bf16 v[110:113], v[140:143], v[218:221], v[110:113]
	v_mfma_f32_16x16x32_bf16 v[106:109], v[154:157], v[218:221], v[106:109]
	v_mfma_f32_16x16x32_bf16 v[94:97], v[140:143], v[226:229], v[94:97]
	v_mfma_f32_16x16x32_bf16 v[90:93], v[154:157], v[226:229], v[90:93]
	v_mfma_f32_16x16x32_bf16 v[78:81], v[140:143], v[234:237], v[78:81]
	v_mfma_f32_16x16x32_bf16 v[74:77], v[154:157], v[234:237], v[74:77]
	v_mfma_f32_16x16x32_bf16 v[126:129], v[144:147], v[214:217], v[126:129]
	v_mfma_f32_16x16x32_bf16 v[122:125], v[158:161], v[214:217], v[122:125]
	v_mfma_f32_16x16x32_bf16 v[110:113], v[144:147], v[222:225], v[110:113]
	v_mfma_f32_16x16x32_bf16 v[106:109], v[158:161], v[222:225], v[106:109]
	v_mfma_f32_16x16x32_bf16 v[94:97], v[144:147], v[230:233], v[94:97]
	v_mfma_f32_16x16x32_bf16 v[90:93], v[158:161], v[230:233], v[90:93]
	v_mfma_f32_16x16x32_bf16 v[78:81], v[144:147], v[238:241], v[78:81]
	v_mfma_f32_16x16x32_bf16 v[74:77], v[158:161], v[238:241], v[74:77]
	v_mfma_f32_16x16x32_bf16 v[118:121], v[178:181], v[210:213], v[118:121]
	v_mfma_f32_16x16x32_bf16 v[114:117], v[186:189], v[210:213], v[114:117]
	v_mfma_f32_16x16x32_bf16 v[102:105], v[178:181], v[218:221], v[102:105]
	v_mfma_f32_16x16x32_bf16 v[98:101], v[186:189], v[218:221], v[98:101]
	v_mfma_f32_16x16x32_bf16 v[86:89], v[178:181], v[226:229], v[86:89]
	v_mfma_f32_16x16x32_bf16 v[82:85], v[186:189], v[226:229], v[82:85]
	v_mfma_f32_16x16x32_bf16 v[70:73], v[178:181], v[234:237], v[70:73]
	v_mfma_f32_16x16x32_bf16 v[66:69], v[186:189], v[234:237], v[66:69]
	v_mfma_f32_16x16x32_bf16 v[118:121], v[182:185], v[214:217], v[118:121]
	v_mfma_f32_16x16x32_bf16 v[114:117], v[190:193], v[214:217], v[114:117]
	v_mfma_f32_16x16x32_bf16 v[102:105], v[182:185], v[222:225], v[102:105]
	v_mfma_f32_16x16x32_bf16 v[98:101], v[190:193], v[222:225], v[98:101]
	v_mfma_f32_16x16x32_bf16 v[86:89], v[182:185], v[230:233], v[86:89]
	v_mfma_f32_16x16x32_bf16 v[82:85], v[190:193], v[230:233], v[82:85]
	v_mfma_f32_16x16x32_bf16 v[70:73], v[182:185], v[238:241], v[70:73]
	v_mfma_f32_16x16x32_bf16 v[66:69], v[190:193], v[238:241], v[66:69]
	s_setprio 0
	s_barrier
	s_add_i32 s24, s24, s12
	v_lshl_add_u64 v[148:149], s[8:9], 0, v[162:163]
	s_mov_b32 m0, s24
	ds_read_b128 v[210:213], v152 offset:16384
	ds_read_b128 v[214:217], v152 offset:17408
	ds_read_b128 v[218:221], v152 offset:18432
	ds_read_b128 v[222:225], v152 offset:19456
	ds_read_b128 v[226:229], v152 offset:20480
	ds_read_b128 v[230:233], v152 offset:21504
	ds_read_b128 v[234:237], v152 offset:22528
	ds_read_b128 v[238:241], v152 offset:23552
	global_load_lds_dwordx4 v[148:149], off
	s_add_i32 m0, s24, 0x2000
	s_add_u32 s24, s8, 0x40000
	v_lshl_add_u64 v[168:169], s[8:9], 0, v[130:131]
	s_addc_u32 s25, s9, 0
	s_add_i32 s26, s26, s12
	global_load_lds_dwordx4 v[168:169], off
	v_lshl_add_u64 v[170:171], s[24:25], 0, v[162:163]
	s_mov_b32 m0, s26
	v_lshl_add_u64 v[172:173], s[10:11], 0, v[132:133]
	global_load_lds_dwordx4 v[170:171], off
	v_lshl_add_u64 v[170:171], s[24:25], 0, v[130:131]
	s_add_i32 m0, s26, 0x2000
	s_nop 0
	global_load_lds_dwordx4 v[170:171], off
	v_lshl_add_u64 v[170:171], s[10:11], 0, v[134:135]
	s_mov_b32 m0, s13
	s_nop 0
	global_load_lds_dwordx4 v[170:171], off
	s_mov_b32 m0, s14
	s_nop 0
	global_load_lds_dwordx4 v[172:173], off
	s_waitcnt vmcnt(8)
	s_waitcnt lgkmcnt(0)
	s_barrier
; #define PG8_STAGE(bufoff, gbase, voff) do { _Pragma("unroll") for (int _i = 0; _i < 2; ++_i) \
;         __builtin_amdgcn_global_load_lds((const unsigned*)((const char*)(gbase) + (voff)[_i]), (PG8_LAS unsigned*)(lds + (bufoff) + ldsw + _i * 8192), 16, 0, 0); } while (0)
; #define PG8_LDA(dst, b, h) do { _Pragma("unroll") for (int m = 0; m < 4; ++m) _Pragma("unroll") for (int k = 0; k < 2; ++k) dst[m][k] = *(const PG8_LAS bf16x8*)(lds + PG8_SA(b, h) + aoff + m * 2048 + k * 1024); } while (0)
; #define PG8_LDB(dst, b, h) do { _Pragma("unroll") for (int n = 0; n < 2; ++n) _Pragma("unroll") for (int k = 0; k < 2; ++k) dst[n][k] = *(const PG8_LAS bf16x8*)(lds + PG8_SB(b, h) + boff + n * 2048 + k * 1024); } while (0)
; #define PG8_MMA(ai, bj, At, Bt) do { __builtin_amdgcn_s_setprio(1); _Pragma("unroll") for (int m = 0; m < 4; ++m) _Pragma("unroll") for (int n = 0; n < 2; ++n) _Pragma("unroll") for (int k = 0; k < 2; ++k) \
;         acc[ai][bj][m][n] = __builtin_amdgcn_mfma_f32_16x16x32_bf16(Bt[n][k], At[m][k], acc[ai][bj][m][n], 0, 0, 0); __builtin_amdgcn_s_setprio(0); } while (0)
; #define PG8_WAIT_V(n) asm volatile("s_waitcnt vmcnt(" #n ")" ::: "memory")
; #define PG8_WAIT_L(n) asm volatile("s_waitcnt lgkmcnt(" #n ")" ::: "memory")
; #define PG8_BAR __builtin_amdgcn_s_barrier()
; #define PG8_SCHED __builtin_amdgcn_sched_barrier(0)
; template <class Epi, class Sched, bool ALIGN_EPI = false, bool SP2 = false>
; __device__ __forceinline__ void gemm_phase(PG8_LAS unsigned char* lds, const Gemm g, const Sched& S, const Epi& E) {
;     ...
;             PG8_WAIT_V(8); PG8_WAIT_L(0); PG8_BAR; PG8_MMA(1, 0, At, B0); PG8_MMA(1, 1, At, B1); PG8_BAR; PG8_SCHED;
;             PG8_LDB(B0, 1, 0); PG8_LDB(B1, 1, 1); PG8_SCHED; PG8_LDA(At, 1, 0); PG8_STAGE(PG8_SA(0, 1), a2 + hstepA, voffA);
;             PG8_WAIT_V(8); PG8_WAIT_L(0); PG8_BAR; PG8_MMA(0, 0, At, B0); PG8_MMA(0, 1, At, B1); PG8_BAR; PG8_SCHED;
	s_setprio 1
	s_waitcnt lgkmcnt(0)
	v_mfma_f32_16x16x32_bf16 v[62:65], v[140:143], v[210:213], v[62:65]
	v_mfma_f32_16x16x32_bf16 v[58:61], v[154:157], v[210:213], v[58:61]
	v_mfma_f32_16x16x32_bf16 v[46:49], v[140:143], v[218:221], v[46:49]
	v_mfma_f32_16x16x32_bf16 v[42:45], v[154:157], v[218:221], v[42:45]
	v_mfma_f32_16x16x32_bf16 v[30:33], v[140:143], v[226:229], v[30:33]
	v_mfma_f32_16x16x32_bf16 v[26:29], v[154:157], v[226:229], v[26:29]
	v_mfma_f32_16x16x32_bf16 v[14:17], v[140:143], v[234:237], v[14:17]
	v_mfma_f32_16x16x32_bf16 v[10:13], v[154:157], v[234:237], v[10:13]
	v_mfma_f32_16x16x32_bf16 v[62:65], v[144:147], v[214:217], v[62:65]
	v_mfma_f32_16x16x32_bf16 v[58:61], v[158:161], v[214:217], v[58:61]
	v_mfma_f32_16x16x32_bf16 v[46:49], v[144:147], v[222:225], v[46:49]
	v_mfma_f32_16x16x32_bf16 v[42:45], v[158:161], v[222:225], v[42:45]
	v_mfma_f32_16x16x32_bf16 v[30:33], v[144:147], v[230:233], v[30:33]
	v_mfma_f32_16x16x32_bf16 v[26:29], v[158:161], v[230:233], v[26:29]
	v_mfma_f32_16x16x32_bf16 v[14:17], v[144:147], v[238:241], v[14:17]
	v_mfma_f32_16x16x32_bf16 v[10:13], v[158:161], v[238:241], v[10:13]
	v_mfma_f32_16x16x32_bf16 v[54:57], v[178:181], v[210:213], v[54:57]
	v_mfma_f32_16x16x32_bf16 v[50:53], v[186:189], v[210:213], v[50:53]
	v_mfma_f32_16x16x32_bf16 v[38:41], v[178:181], v[218:221], v[38:41]
	v_mfma_f32_16x16x32_bf16 v[34:37], v[186:189], v[218:221], v[34:37]
	v_mfma_f32_16x16x32_bf16 v[22:25], v[178:181], v[226:229], v[22:25]
	v_mfma_f32_16x16x32_bf16 v[18:21], v[186:189], v[226:229], v[18:21]
	v_mfma_f32_16x16x32_bf16 v[6:9], v[178:181], v[234:237], v[6:9]
	v_mfma_f32_16x16x32_bf16 v[2:5], v[186:189], v[234:237], v[2:5]
	v_mfma_f32_16x16x32_bf16 v[54:57], v[182:185], v[214:217], v[54:57]
	v_mfma_f32_16x16x32_bf16 v[50:53], v[190:193], v[214:217], v[50:53]
	v_mfma_f32_16x16x32_bf16 v[38:41], v[182:185], v[222:225], v[38:41]
	v_mfma_f32_16x16x32_bf16 v[34:37], v[190:193], v[222:225], v[34:37]
	v_mfma_f32_16x16x32_bf16 v[22:25], v[182:185], v[230:233], v[22:25]
	v_mfma_f32_16x16x32_bf16 v[18:21], v[190:193], v[230:233], v[18:21]
	v_mfma_f32_16x16x32_bf16 v[6:9], v[182:185], v[238:241], v[6:9]
	v_mfma_f32_16x16x32_bf16 v[2:5], v[190:193], v[238:241], v[2:5]
	s_setprio 0
	s_barrier
	s_add_i32 s24, 0, 0x18000
	v_add_u32_e32 v153, s24, v150
	s_add_i32 s25, 0, 0x1c000
	ds_read_b128 v[140:143], v153
	ds_read_b128 v[144:147], v153 offset:1024
	ds_read_b128 v[154:157], v153 offset:2048
	ds_read_b128 v[158:161], v153 offset:3072
	v_add_u32_e32 v153, s25, v150
	ds_read_b128 v[178:181], v153
	ds_read_b128 v[182:185], v153 offset:1024
	ds_read_b128 v[186:189], v153 offset:2048
	ds_read_b128 v[190:193], v153 offset:3072
	s_add_u32 s10, s10, 0x40000
	s_addc_u32 s11, s11, 0
	s_mov_b32 m0, s15
	v_lshl_add_u64 v[194:195], s[10:11], 0, v[134:135]
	ds_read_b128 v[210:213], v152 offset:32768
	ds_read_b128 v[214:217], v152 offset:33792
	ds_read_b128 v[218:221], v152 offset:34816
	ds_read_b128 v[222:225], v152 offset:35840
	ds_read_b128 v[226:229], v152 offset:36864
	ds_read_b128 v[230:233], v152 offset:37888
	ds_read_b128 v[234:237], v152 offset:38912
	ds_read_b128 v[238:241], v152 offset:39936
	global_load_lds_dwordx4 v[194:195], off
	v_lshl_add_u64 v[194:195], s[10:11], 0, v[132:133]
	s_mov_b32 m0, s16
	s_nop 0
	global_load_lds_dwordx4 v[194:195], off
	s_waitcnt vmcnt(8)
	s_waitcnt lgkmcnt(0)
	s_barrier
	s_setprio 1
	s_waitcnt lgkmcnt(0)
	v_mfma_f32_16x16x32_bf16 v[126:129], v[140:143], v[210:213], v[126:129]
	v_mfma_f32_16x16x32_bf16 v[122:125], v[154:157], v[210:213], v[122:125]
	v_mfma_f32_16x16x32_bf16 v[110:113], v[140:143], v[218:221], v[110:113]
	v_mfma_f32_16x16x32_bf16 v[106:109], v[154:157], v[218:221], v[106:109]
	v_mfma_f32_16x16x32_bf16 v[94:97], v[140:143], v[226:229], v[94:97]
	v_mfma_f32_16x16x32_bf16 v[90:93], v[154:157], v[226:229], v[90:93]
	v_mfma_f32_16x16x32_bf16 v[78:81], v[140:143], v[234:237], v[78:81]
	v_mfma_f32_16x16x32_bf16 v[74:77], v[154:157], v[234:237], v[74:77]
	v_mfma_f32_16x16x32_bf16 v[126:129], v[144:147], v[214:217], v[126:129]
	v_mfma_f32_16x16x32_bf16 v[122:125], v[158:161], v[214:217], v[122:125]
	v_mfma_f32_16x16x32_bf16 v[110:113], v[144:147], v[222:225], v[110:113]
	v_mfma_f32_16x16x32_bf16 v[106:109], v[158:161], v[222:225], v[106:109]
	v_mfma_f32_16x16x32_bf16 v[94:97], v[144:147], v[230:233], v[94:97]
	v_mfma_f32_16x16x32_bf16 v[90:93], v[158:161], v[230:233], v[90:93]
	v_mfma_f32_16x16x32_bf16 v[78:81], v[144:147], v[238:241], v[78:81]
	v_mfma_f32_16x16x32_bf16 v[74:77], v[158:161], v[238:241], v[74:77]
	v_mfma_f32_16x16x32_bf16 v[118:121], v[178:181], v[210:213], v[118:121]
	v_mfma_f32_16x16x32_bf16 v[114:117], v[186:189], v[210:213], v[114:117]
	v_mfma_f32_16x16x32_bf16 v[102:105], v[178:181], v[218:221], v[102:105]
	v_mfma_f32_16x16x32_bf16 v[98:101], v[186:189], v[218:221], v[98:101]
	v_mfma_f32_16x16x32_bf16 v[86:89], v[178:181], v[226:229], v[86:89]
	v_mfma_f32_16x16x32_bf16 v[82:85], v[186:189], v[226:229], v[82:85]
	v_mfma_f32_16x16x32_bf16 v[70:73], v[178:181], v[234:237], v[70:73]
	v_mfma_f32_16x16x32_bf16 v[66:69], v[186:189], v[234:237], v[66:69]
	v_mfma_f32_16x16x32_bf16 v[118:121], v[182:185], v[214:217], v[118:121]
	v_mfma_f32_16x16x32_bf16 v[114:117], v[190:193], v[214:217], v[114:117]
	v_mfma_f32_16x16x32_bf16 v[102:105], v[182:185], v[222:225], v[102:105]
	v_mfma_f32_16x16x32_bf16 v[98:101], v[190:193], v[222:225], v[98:101]
	v_mfma_f32_16x16x32_bf16 v[86:89], v[182:185], v[230:233], v[86:89]
	v_mfma_f32_16x16x32_bf16 v[82:85], v[190:193], v[230:233], v[82:85]
	v_mfma_f32_16x16x32_bf16 v[70:73], v[182:185], v[238:241], v[70:73]
	v_mfma_f32_16x16x32_bf16 v[66:69], v[190:193], v[238:241], v[66:69]
	s_setprio 0
	s_barrier
; #define PG8_STAGE(bufoff, gbase, voff) do { _Pragma("unroll") for (int _i = 0; _i < 2; ++_i) \
;         __builtin_amdgcn_global_load_lds((const unsigned*)((const char*)(gbase) + (voff)[_i]), (PG8_LAS unsigned*)(lds + (bufoff) + ldsw + _i * 8192), 16, 0, 0); } while (0)
; #define PG8_LDA(dst, b, h) do { _Pragma("unroll") for (int m = 0; m < 4; ++m) _Pragma("unroll") for (int k = 0; k < 2; ++k) dst[m][k] = *(const PG8_LAS bf16x8*)(lds + PG8_SA(b, h) + aoff + m * 2048 + k * 1024); } while (0)
; #define PG8_WAIT_V(n) asm volatile("s_waitcnt vmcnt(" #n ")" ::: "memory")
; template <class Epi, class Sched, bool ALIGN_EPI = false, bool SP2 = false>
; __device__ __forceinline__ void gemm_phase(PG8_LAS unsigned char* lds, const Gemm g, const Sched& S, const Epi& E) {
;     ...
;             PG8_LDA(At, 1, 1); PG8_STAGE(PG8_SB(1, 0), b3, voffB); PG8_STAGE(PG8_SB(1, 1), b3 + hstepB, voffB); PG8_STAGE(PG8_SA(1, 0), a3, voffA);
;             PG8_WAIT_V(8); PG8_WAIT_L(0); PG8_BAR; PG8_MMA(1, 0, At, B0); PG8_MMA(1, 1, At, B1); PG8_BAR; PG8_SCHED;
;             } else {
;             PG8_LDB(B0, 0, 0); PG8_SCHED; PG8_LDA(At, 0, 0); PG8_STAGE(PG8_SA(1, 1), a1 + hstepA, voffA);
;             PG8_WAIT_L(8); PG8_BAR; PG8_WAIT_L(0); PG8_MMA(0, 0, At, B0); PG8_BAR; PG8_SCHED;
;             PG8_LDB(B1, 0, 1); PG8_STAGE(PG8_SB(0, 0), b2, voffB);
;             PG8_BAR; PG8_WAIT_L(0); PG8_MMA(0, 1, At, B1); PG8_BAR;
;             PG8_LDA(At, 0, 1); PG8_STAGE(PG8_SA(0, 0), a2, voffA);
;             PG8_BAR; PG8_WAIT_L(0); PG8_MMA(1, 0, At, B0); PG8_BAR; PG8_SCHED;
;             PG8_STAGE(PG8_SB(0, 1), b2 + hstepB, voffB);
;             PG8_WAIT_V(6); PG8_BAR; PG8_MMA(1, 1, At, B1); PG8_BAR;
;             PG8_LDB(B0, 1, 0); PG8_SCHED; PG8_LDA(At, 1, 0); PG8_STAGE(PG8_SA(0, 1), a2 + hstepA, voffA);
;             PG8_WAIT_L(8); PG8_BAR; PG8_WAIT_L(0); PG8_MMA(0, 0, At, B0); PG8_BAR; PG8_SCHED;
;             PG8_LDB(B1, 1, 1); PG8_STAGE(PG8_SB(1, 0), b3, voffB);
;             PG8_BAR; PG8_WAIT_L(0); PG8_MMA(0, 1, At, B1); PG8_BAR;
;             PG8_LDA(At, 1, 1); PG8_STAGE(PG8_SA(1, 0), a3, voffA);
;             PG8_BAR; PG8_WAIT_L(0); PG8_MMA(1, 0, At, B0); PG8_BAR; PG8_SCHED;
;             PG8_STAGE(PG8_SB(1, 1), b3 + hstepB, voffB);
;             PG8_WAIT_V(6); PG8_BAR; PG8_MMA(1, 1, At, B1); PG8_BAR;
;             }
;         }
;         if constexpr (ALIGN_EPI) { if (wr == 0) PG8_BAR; }
	s_add_i32 s10, s24, s12
	v_lshl_add_u64 v[148:149], v[148:149], 0, s[50:51]
	s_mov_b32 m0, s10
	ds_read_b128 v[210:213], v152 offset:49152
	ds_read_b128 v[214:217], v152 offset:50176
	ds_read_b128 v[218:221], v152 offset:51200
	ds_read_b128 v[222:225], v152 offset:52224
	ds_read_b128 v[226:229], v152 offset:53248
	ds_read_b128 v[230:233], v152 offset:54272
	ds_read_b128 v[234:237], v152 offset:55296
	ds_read_b128 v[238:241], v152 offset:56320
	global_load_lds_dwordx4 v[148:149], off
	s_add_i32 m0, s10, 0x2000
	s_add_u32 s8, s8, 0x40080
	v_lshl_add_u64 v[148:149], v[168:169], 0, s[50:51]
	s_addc_u32 s9, s9, 0
	s_add_i32 s10, s25, s12
	global_load_lds_dwordx4 v[148:149], off
	v_lshl_add_u64 v[148:149], s[8:9], 0, v[162:163]
	s_mov_b32 m0, s10
	s_nop 0
	global_load_lds_dwordx4 v[148:149], off
	v_lshl_add_u64 v[148:149], s[8:9], 0, v[130:131]
	s_add_i32 m0, s10, 0x2000
	s_nop 0
	global_load_lds_dwordx4 v[148:149], off
	v_lshl_add_u64 v[148:149], v[170:171], 0, s[50:51]
	s_mov_b32 m0, s17
	s_nop 0
	global_load_lds_dwordx4 v[148:149], off
	v_lshl_add_u64 v[148:149], v[172:173], 0, s[50:51]
	s_mov_b32 m0, s18
	s_nop 0
	global_load_lds_dwordx4 v[148:149], off
	s_waitcnt vmcnt(8)
	s_waitcnt lgkmcnt(0)
	s_barrier
	s_setprio 1
	s_waitcnt lgkmcnt(0)
	v_mfma_f32_16x16x32_bf16 v[62:65], v[140:143], v[210:213], v[62:65]
	v_mfma_f32_16x16x32_bf16 v[58:61], v[154:157], v[210:213], v[58:61]
	v_mfma_f32_16x16x32_bf16 v[46:49], v[140:143], v[218:221], v[46:49]
	v_mfma_f32_16x16x32_bf16 v[42:45], v[154:157], v[218:221], v[42:45]
	v_mfma_f32_16x16x32_bf16 v[30:33], v[140:143], v[226:229], v[30:33]
	v_mfma_f32_16x16x32_bf16 v[26:29], v[154:157], v[226:229], v[26:29]
	v_mfma_f32_16x16x32_bf16 v[14:17], v[140:143], v[234:237], v[14:17]
	v_mfma_f32_16x16x32_bf16 v[10:13], v[154:157], v[234:237], v[10:13]
	v_mfma_f32_16x16x32_bf16 v[62:65], v[144:147], v[214:217], v[62:65]
	v_mfma_f32_16x16x32_bf16 v[58:61], v[158:161], v[214:217], v[58:61]
	v_mfma_f32_16x16x32_bf16 v[46:49], v[144:147], v[222:225], v[46:49]
	v_mfma_f32_16x16x32_bf16 v[42:45], v[158:161], v[222:225], v[42:45]
	v_mfma_f32_16x16x32_bf16 v[30:33], v[144:147], v[230:233], v[30:33]
	v_mfma_f32_16x16x32_bf16 v[26:29], v[158:161], v[230:233], v[26:29]
	v_mfma_f32_16x16x32_bf16 v[14:17], v[144:147], v[238:241], v[14:17]
	v_mfma_f32_16x16x32_bf16 v[10:13], v[158:161], v[238:241], v[10:13]
	v_mfma_f32_16x16x32_bf16 v[54:57], v[178:181], v[210:213], v[54:57]
	v_mfma_f32_16x16x32_bf16 v[50:53], v[186:189], v[210:213], v[50:53]
	v_mfma_f32_16x16x32_bf16 v[38:41], v[178:181], v[218:221], v[38:41]
	v_mfma_f32_16x16x32_bf16 v[34:37], v[186:189], v[218:221], v[34:37]
	v_mfma_f32_16x16x32_bf16 v[22:25], v[178:181], v[226:229], v[22:25]
	v_mfma_f32_16x16x32_bf16 v[18:21], v[186:189], v[226:229], v[18:21]
	v_mfma_f32_16x16x32_bf16 v[6:9], v[178:181], v[234:237], v[6:9]
	v_mfma_f32_16x16x32_bf16 v[2:5], v[186:189], v[234:237], v[2:5]
	v_mfma_f32_16x16x32_bf16 v[54:57], v[182:185], v[214:217], v[54:57]
	v_mfma_f32_16x16x32_bf16 v[50:53], v[190:193], v[214:217], v[50:53]
	v_mfma_f32_16x16x32_bf16 v[38:41], v[182:185], v[222:225], v[38:41]
	v_mfma_f32_16x16x32_bf16 v[34:37], v[190:193], v[222:225], v[34:37]
	v_mfma_f32_16x16x32_bf16 v[22:25], v[182:185], v[230:233], v[22:25]
	v_mfma_f32_16x16x32_bf16 v[18:21], v[190:193], v[230:233], v[18:21]
	v_mfma_f32_16x16x32_bf16 v[6:9], v[182:185], v[238:241], v[6:9]
	v_mfma_f32_16x16x32_bf16 v[2:5], v[190:193], v[238:241], v[2:5]
	s_setprio 0
	s_barrier
	s_add_i32 s23, s23, 2
	s_add_u32 s4, s4, 0x100
	s_addc_u32 s5, s5, 0
	s_add_u32 s21, s21, 0x100
	s_addc_u32 s22, s22, 0
	s_cmp_gt_u32 s23, 13
	s_cbranch_scc0 .LBB0_1693
	s_and_b64 vcc, exec, s[42:43]
	s_cbranch_vccz .LBB0_1696
	s_barrier

; #define PG8_STAGE(bufoff, gbase, voff) do { _Pragma("unroll") for (int _i = 0; _i < 2; ++_i) \
;         __builtin_amdgcn_global_load_lds((const unsigned*)((const char*)(gbase) + (voff)[_i]), (PG8_LAS unsigned*)(lds + (bufoff) + ldsw + _i * 8192), 16, 0, 0); } while (0)
; #define PG8_LDA(dst, b, h) do { _Pragma("unroll") for (int m = 0; m < 4; ++m) _Pragma("unroll") for (int k = 0; k < 2; ++k) dst[m][k] = *(const PG8_LAS bf16x8*)(lds + PG8_SA(b, h) + aoff + m * 2048 + k * 1024); } while (0)
; #define PG8_LDB(dst, b, h) do { _Pragma("unroll") for (int n = 0; n < 2; ++n) _Pragma("unroll") for (int k = 0; k < 2; ++k) dst[n][k] = *(const PG8_LAS bf16x8*)(lds + PG8_SB(b, h) + boff + n * 2048 + k * 1024); } while (0)
; #define PG8_MMA(ai, bj, At, Bt) do { __builtin_amdgcn_s_setprio(1); _Pragma("unroll") for (int m = 0; m < 4; ++m) _Pragma("unroll") for (int n = 0; n < 2; ++n) _Pragma("unroll") for (int k = 0; k < 2; ++k) \
;         acc[ai][bj][m][n] = __builtin_amdgcn_mfma_f32_16x16x32_bf16(Bt[n][k], At[m][k], acc[ai][bj][m][n], 0, 0, 0); __builtin_amdgcn_s_setprio(0); } while (0)
; #define PG8_WAIT_V(n) asm volatile("s_waitcnt vmcnt(" #n ")" ::: "memory")
; #define PG8_WAIT_L(n) asm volatile("s_waitcnt lgkmcnt(" #n ")" ::: "memory")
; #define PG8_BAR __builtin_amdgcn_s_barrier()
; #define PG8_SCHED __builtin_amdgcn_sched_barrier(0)
; template <class Epi, class Sched, bool ALIGN_EPI = false, bool SP2 = false>
; __device__ __forceinline__ void gemm_phase(PG8_LAS unsigned char* lds, const Gemm g, const Sched& S, const Epi& E) {
;     ...
;         for (int t = 0; t < nt; t += 2) {
;             const bool last = (t == nt - 2);
;             const char* a1 = cA + (size_t)(t + 1) * kstep;
;             const char* a2 = last ? nA : cA + (size_t)(t + 2) * kstep; const char* b2 = last ? nB : cB + (size_t)(t + 2) * kstep;
;             const char* a3 = a2 + kstep; const char* b3 = b2 + kstep;
;             if (last && has_next) S.a_ready(nxt);
;             if constexpr (SP2) {
;             PG8_LDB(B0, 0, 0); PG8_LDB(B1, 0, 1); PG8_SCHED; PG8_LDA(At, 0, 0); PG8_STAGE(PG8_SA(1, 1), a1 + hstepA, voffA);
;             PG8_WAIT_V(8); PG8_WAIT_L(0); PG8_BAR; PG8_MMA(0, 0, At, B0); PG8_MMA(0, 1, At, B1); PG8_BAR; PG8_SCHED;
;             PG8_LDA(At, 0, 1); PG8_STAGE(PG8_SB(0, 0), b2, voffB); PG8_STAGE(PG8_SB(0, 1), b2 + hstepB, voffB); PG8_STAGE(PG8_SA(0, 0), a2, voffA);
.LBB0_1809:
	s_add_u32 s15, s18, s13
	s_addc_u32 s26, s19, 0
	s_add_u32 s27, s15, 0x100
	s_addc_u32 s28, s26, 0
	s_and_b64 s[24:25], s[36:37], exec
	s_cselect_b32 s41, s5, s28
	s_cselect_b32 s40, s4, s27
	s_add_u32 s13, s6, s13
	s_addc_u32 s24, s7, 0
	s_add_u32 s13, s13, 0x100
	s_addc_u32 s27, s24, 0
	s_add_i32 s28, 0, 0x10000
	s_and_b64 s[24:25], s[36:37], exec
	s_cselect_b32 s43, s21, s27
	s_cselect_b32 s42, s20, s13
	s_add_i32 s24, 0, 0x14000
	s_add_u32 s46, s15, 0x40080
	s_addc_u32 s47, s26, 0
	s_add_i32 s26, s28, s48
	s_add_i32 m0, s49, 0xc000
	s_add_i32 s25, s49, 0xe000
	s_add_i32 s27, s26, 0x2000
	s_add_u32 s44, s42, 0x40000
	v_add_u32_e32 v90, s28, v1
	v_add_u32_e32 v106, s24, v1
	s_addc_u32 s45, s43, 0
	s_add_i32 s29, s24, s48
	ds_read_b128 v[78:81], v90
	ds_read_b128 v[82:85], v90 offset:1024
	ds_read_b128 v[86:89], v90 offset:2048
	ds_read_b128 v[90:93], v90 offset:3072
	ds_read_b128 v[94:97], v106
	ds_read_b128 v[98:101], v106 offset:1024
	ds_read_b128 v[102:105], v106 offset:2048
	ds_read_b128 v[106:109], v106 offset:3072
	s_add_i32 s30, s29, 0x2000
	s_add_i32 s31, 0, 0x18000
	s_add_i32 s95, 0, 0x1c000
	s_add_u32 s38, s40, 0x40000
	s_addc_u32 s39, s41, 0
	s_add_i32 s15, s31, s48
	s_add_i32 s13, s15, 0x2000
	s_add_u32 s36, s42, 0x40080
	s_addc_u32 s37, s43, 0
	s_add_i32 s24, s95, s48
	s_add_i32 s28, s24, 0x2000
	v_lshl_add_u64 v[142:143], s[46:47], 0, v[162:163]
	ds_read_b128 v[110:113], v77
	ds_read_b128 v[114:117], v77 offset:1024
	ds_read_b128 v[118:121], v77 offset:2048
	ds_read_b128 v[122:125], v77 offset:3072
	ds_read_b128 v[126:129], v77 offset:4096
	ds_read_b128 v[130:133], v77 offset:5120
	ds_read_b128 v[134:137], v77 offset:6144
	ds_read_b128 v[138:141], v77 offset:7168
	global_load_lds_dwordx4 v[142:143], off
	v_lshl_add_u64 v[142:143], s[46:47], 0, v[66:67]
	s_mov_b32 m0, s25
	s_nop 0
	global_load_lds_dwordx4 v[142:143], off
	s_waitcnt vmcnt(8)
	s_waitcnt lgkmcnt(0)
	s_barrier
	s_setprio 1
	s_waitcnt lgkmcnt(0)
	v_mfma_f32_16x16x32_bf16 v[62:65], v[78:81], v[110:113], v[62:65]
	v_mfma_f32_16x16x32_bf16 v[58:61], v[86:89], v[110:113], v[58:61]
	v_mfma_f32_16x16x32_bf16 v[54:57], v[78:81], v[118:121], v[54:57]
	v_mfma_f32_16x16x32_bf16 v[50:53], v[86:89], v[118:121], v[50:53]
	v_mfma_f32_16x16x32_bf16 v[46:49], v[78:81], v[126:129], v[46:49]
	v_mfma_f32_16x16x32_bf16 v[42:45], v[86:89], v[126:129], v[42:45]
	v_mfma_f32_16x16x32_bf16 v[30:33], v[78:81], v[134:137], v[30:33]
	v_mfma_f32_16x16x32_bf16 v[26:29], v[86:89], v[134:137], v[26:29]
	v_mfma_f32_16x16x32_bf16 v[62:65], v[82:85], v[114:117], v[62:65]
	v_mfma_f32_16x16x32_bf16 v[58:61], v[90:93], v[114:117], v[58:61]
	v_mfma_f32_16x16x32_bf16 v[54:57], v[82:85], v[122:125], v[54:57]
	v_mfma_f32_16x16x32_bf16 v[50:53], v[90:93], v[122:125], v[50:53]
	v_mfma_f32_16x16x32_bf16 v[46:49], v[82:85], v[130:133], v[46:49]
	v_mfma_f32_16x16x32_bf16 v[42:45], v[90:93], v[130:133], v[42:45]
	v_mfma_f32_16x16x32_bf16 v[30:33], v[82:85], v[138:141], v[30:33]
	v_mfma_f32_16x16x32_bf16 v[26:29], v[90:93], v[138:141], v[26:29]
	v_mfma_f32_16x16x32_bf16 v[38:41], v[94:97], v[110:113], v[38:41]
	v_mfma_f32_16x16x32_bf16 v[34:37], v[102:105], v[110:113], v[34:37]
	v_mfma_f32_16x16x32_bf16 v[22:25], v[94:97], v[118:121], v[22:25]
	v_mfma_f32_16x16x32_bf16 v[18:21], v[102:105], v[118:121], v[18:21]
	v_mfma_f32_16x16x32_bf16 v[14:17], v[94:97], v[126:129], v[14:17]
	v_mfma_f32_16x16x32_bf16 v[10:13], v[102:105], v[126:129], v[10:13]
	v_mfma_f32_16x16x32_bf16 v[6:9], v[94:97], v[134:137], v[6:9]
	v_mfma_f32_16x16x32_bf16 v[2:5], v[102:105], v[134:137], v[2:5]
	v_mfma_f32_16x16x32_bf16 v[38:41], v[98:101], v[114:117], v[38:41]
	v_mfma_f32_16x16x32_bf16 v[34:37], v[106:109], v[114:117], v[34:37]
	v_mfma_f32_16x16x32_bf16 v[22:25], v[98:101], v[122:125], v[22:25]
	v_mfma_f32_16x16x32_bf16 v[18:21], v[106:109], v[122:125], v[18:21]
	v_mfma_f32_16x16x32_bf16 v[14:17], v[98:101], v[130:133], v[14:17]
	v_mfma_f32_16x16x32_bf16 v[10:13], v[106:109], v[130:133], v[10:13]
	v_mfma_f32_16x16x32_bf16 v[6:9], v[98:101], v[138:141], v[6:9]
	v_mfma_f32_16x16x32_bf16 v[2:5], v[106:109], v[138:141], v[2:5]
	s_setprio 0
	s_barrier
	s_mov_b32 m0, s26
	v_lshl_add_u64 v[142:143], s[42:43], 0, v[162:163]
	global_load_lds_dwordx4 v[142:143], off
	v_lshl_add_u64 v[144:145], s[42:43], 0, v[66:67]
	s_mov_b32 m0, s27
	v_lshl_add_u64 v[78:79], s[44:45], 0, v[162:163]
	global_load_lds_dwordx4 v[144:145], off
	s_mov_b32 m0, s29
	v_lshl_add_u64 v[146:147], s[40:41], 0, v[162:163]
	global_load_lds_dwordx4 v[78:79], off
	v_lshl_add_u64 v[78:79], s[44:45], 0, v[66:67]
	s_mov_b32 m0, s30
	v_lshl_add_u64 v[148:149], s[40:41], 0, v[66:67]
	global_load_lds_dwordx4 v[78:79], off
	s_mov_b32 m0, s49
	s_nop 0
	global_load_lds_dwordx4 v[146:147], off
	s_mov_b32 m0, s55
	s_nop 0
	global_load_lds_dwordx4 v[148:149], off
	s_waitcnt vmcnt(8)
	s_waitcnt lgkmcnt(0)
	s_barrier
; #define PG8_WAIT_V(n) asm volatile("s_waitcnt vmcnt(" #n ")" ::: "memory")
; #define PG8_WAIT_L(n) asm volatile("s_waitcnt lgkmcnt(" #n ")" ::: "memory")
; #define PG8_BAR __builtin_amdgcn_s_barrier()
; template <class Epi, class Sched, bool ALIGN_EPI = false, bool SP2 = false>
; __device__ __forceinline__ void gemm_phase(PG8_LAS unsigned char* lds, const Gemm g, const Sched& S, const Epi& E) {
;     ...
;             PG8_WAIT_V(8); PG8_WAIT_L(0); PG8_BAR; PG8_MMA(1, 0, At, B0); PG8_MMA(1, 1, At, B1); PG8_BAR; PG8_SCHED;
;             PG8_LDB(B0, 1, 0); PG8_LDB(B1, 1, 1); PG8_SCHED; PG8_LDA(At, 1, 0); PG8_STAGE(PG8_SA(0, 1), a2 + hstepA, voffA);
;             PG8_WAIT_V(8); PG8_WAIT_L(0); PG8_BAR; PG8_MMA(0, 0, At, B0); PG8_MMA(0, 1, At, B1); PG8_BAR; PG8_SCHED;
;             PG8_LDA(At, 1, 1); PG8_STAGE(PG8_SB(1, 0), b3, voffB); PG8_STAGE(PG8_SB(1, 1), b3 + hstepB, voffB); PG8_STAGE(PG8_SA(1, 0), a3, voffA);
;             PG8_WAIT_V(8); PG8_WAIT_L(0); PG8_BAR; PG8_MMA(1, 0, At, B0); PG8_MMA(1, 1, At, B1); PG8_BAR; PG8_SCHED;
;             } else {
;             PG8_LDB(B0, 0, 0); PG8_SCHED; PG8_LDA(At, 0, 0); PG8_STAGE(PG8_SA(1, 1), a1 + hstepA, voffA);
;             PG8_WAIT_L(8); PG8_BAR; PG8_WAIT_L(0); PG8_MMA(0, 0, At, B0); PG8_BAR; PG8_SCHED;
;             PG8_LDB(B1, 0, 1); PG8_STAGE(PG8_SB(0, 0), b2, voffB);
;             PG8_BAR; PG8_WAIT_L(0); PG8_MMA(0, 1, At, B1); PG8_BAR;
;             PG8_LDA(At, 0, 1); PG8_STAGE(PG8_SA(0, 0), a2, voffA);
;             PG8_BAR; PG8_WAIT_L(0); PG8_MMA(1, 0, At, B0); PG8_BAR; PG8_SCHED;
;             PG8_STAGE(PG8_SB(0, 1), b2 + hstepB, voffB);
;             PG8_WAIT_V(6); PG8_BAR; PG8_MMA(1, 1, At, B1); PG8_BAR;
;             PG8_LDB(B0, 1, 0); PG8_SCHED; PG8_LDA(At, 1, 0); PG8_STAGE(PG8_SA(0, 1), a2 + hstepA, voffA);
;             PG8_WAIT_L(8); PG8_BAR; PG8_WAIT_L(0); PG8_MMA(0, 0, At, B0); PG8_BAR; PG8_SCHED;
;             PG8_LDB(B1, 1, 1); PG8_STAGE(PG8_SB(1, 0), b3, voffB);
;             PG8_BAR; PG8_WAIT_L(0); PG8_MMA(0, 1, At, B1); PG8_BAR;
;             PG8_LDA(At, 1, 1); PG8_STAGE(PG8_SA(1, 0), a3, voffA);
;             PG8_BAR; PG8_WAIT_L(0); PG8_MMA(1, 0, At, B0); PG8_BAR; PG8_SCHED;
;             PG8_STAGE(PG8_SB(1, 1), b3 + hstepB, voffB);
;             PG8_WAIT_V(6); PG8_BAR; PG8_MMA(1, 1, At, B1); PG8_BAR;
;             }
;         }
;         if constexpr (ALIGN_EPI) { if (wr == 0) PG8_BAR; }
	s_setprio 1
	s_setprio 0
	s_barrier
	v_add_u32_e32 v90, s31, v1
	v_add_u32_e32 v106, s95, v1
	ds_read_b128 v[78:81], v90
	ds_read_b128 v[82:85], v90 offset:1024
	ds_read_b128 v[86:89], v90 offset:2048
	ds_read_b128 v[90:93], v90 offset:3072
	ds_read_b128 v[94:97], v106
	ds_read_b128 v[98:101], v106 offset:1024
	ds_read_b128 v[102:105], v106 offset:2048
	ds_read_b128 v[106:109], v106 offset:3072
	s_mov_b32 m0, s56
	v_lshl_add_u64 v[150:151], s[38:39], 0, v[162:163]
	ds_read_b128 v[110:113], v77 offset:32768
	ds_read_b128 v[114:117], v77 offset:33792
	ds_read_b128 v[118:121], v77 offset:34816
	ds_read_b128 v[122:125], v77 offset:35840
	ds_read_b128 v[126:129], v77 offset:36864
	ds_read_b128 v[130:133], v77 offset:37888
	ds_read_b128 v[134:137], v77 offset:38912
	ds_read_b128 v[138:141], v77 offset:39936
	global_load_lds_dwordx4 v[150:151], off
	v_lshl_add_u64 v[150:151], s[38:39], 0, v[66:67]
	s_mov_b32 m0, s57
	s_nop 0
	global_load_lds_dwordx4 v[150:151], off
	s_waitcnt vmcnt(8)
	s_waitcnt lgkmcnt(0)
	s_barrier
	s_setprio 1
	s_waitcnt lgkmcnt(0)
	v_mfma_f32_16x16x32_bf16 v[62:65], v[78:81], v[110:113], v[62:65]
	v_mfma_f32_16x16x32_bf16 v[58:61], v[86:89], v[110:113], v[58:61]
	v_mfma_f32_16x16x32_bf16 v[54:57], v[78:81], v[118:121], v[54:57]
	v_mfma_f32_16x16x32_bf16 v[50:53], v[86:89], v[118:121], v[50:53]
	v_mfma_f32_16x16x32_bf16 v[46:49], v[78:81], v[126:129], v[46:49]
	v_mfma_f32_16x16x32_bf16 v[42:45], v[86:89], v[126:129], v[42:45]
	v_mfma_f32_16x16x32_bf16 v[30:33], v[78:81], v[134:137], v[30:33]
	v_mfma_f32_16x16x32_bf16 v[26:29], v[86:89], v[134:137], v[26:29]
	v_mfma_f32_16x16x32_bf16 v[62:65], v[82:85], v[114:117], v[62:65]
	v_mfma_f32_16x16x32_bf16 v[58:61], v[90:93], v[114:117], v[58:61]
	v_mfma_f32_16x16x32_bf16 v[54:57], v[82:85], v[122:125], v[54:57]
	v_mfma_f32_16x16x32_bf16 v[50:53], v[90:93], v[122:125], v[50:53]
	v_mfma_f32_16x16x32_bf16 v[46:49], v[82:85], v[130:133], v[46:49]
	v_mfma_f32_16x16x32_bf16 v[42:45], v[90:93], v[130:133], v[42:45]
	v_mfma_f32_16x16x32_bf16 v[30:33], v[82:85], v[138:141], v[30:33]
	v_mfma_f32_16x16x32_bf16 v[26:29], v[90:93], v[138:141], v[26:29]
	v_mfma_f32_16x16x32_bf16 v[38:41], v[94:97], v[110:113], v[38:41]
	v_mfma_f32_16x16x32_bf16 v[34:37], v[102:105], v[110:113], v[34:37]
	v_mfma_f32_16x16x32_bf16 v[22:25], v[94:97], v[118:121], v[22:25]
	v_mfma_f32_16x16x32_bf16 v[18:21], v[102:105], v[118:121], v[18:21]
	v_mfma_f32_16x16x32_bf16 v[14:17], v[94:97], v[126:129], v[14:17]
	v_mfma_f32_16x16x32_bf16 v[10:13], v[102:105], v[126:129], v[10:13]
	v_mfma_f32_16x16x32_bf16 v[6:9], v[94:97], v[134:137], v[6:9]
	v_mfma_f32_16x16x32_bf16 v[2:5], v[102:105], v[134:137], v[2:5]
	v_mfma_f32_16x16x32_bf16 v[38:41], v[98:101], v[114:117], v[38:41]
	v_mfma_f32_16x16x32_bf16 v[34:37], v[106:109], v[114:117], v[34:37]
	v_mfma_f32_16x16x32_bf16 v[22:25], v[98:101], v[122:125], v[22:25]
	v_mfma_f32_16x16x32_bf16 v[18:21], v[106:109], v[122:125], v[18:21]
	v_mfma_f32_16x16x32_bf16 v[14:17], v[98:101], v[130:133], v[14:17]
	v_mfma_f32_16x16x32_bf16 v[10:13], v[106:109], v[130:133], v[10:13]
	v_mfma_f32_16x16x32_bf16 v[6:9], v[98:101], v[138:141], v[6:9]
	v_mfma_f32_16x16x32_bf16 v[2:5], v[106:109], v[138:141], v[2:5]
	s_setprio 0
	s_barrier
	s_mov_b32 m0, s15
	v_lshl_add_u64 v[78:79], v[142:143], 0, s[50:51]
	global_load_lds_dwordx4 v[78:79], off
	v_lshl_add_u64 v[78:79], v[144:145], 0, s[50:51]
	s_mov_b32 m0, s13
	s_nop 0
	global_load_lds_dwordx4 v[78:79], off
	v_lshl_add_u64 v[78:79], s[36:37], 0, v[162:163]
	s_mov_b32 m0, s24
	s_nop 0
	global_load_lds_dwordx4 v[78:79], off
	v_lshl_add_u64 v[78:79], s[36:37], 0, v[66:67]
	s_mov_b32 m0, s28
	s_nop 0
	global_load_lds_dwordx4 v[78:79], off
	v_lshl_add_u64 v[78:79], v[146:147], 0, s[50:51]
	s_mov_b32 m0, s92
	s_nop 0
	global_load_lds_dwordx4 v[78:79], off
	v_lshl_add_u64 v[78:79], v[148:149], 0, s[50:51]
	s_mov_b32 m0, s93
	s_nop 0
	global_load_lds_dwordx4 v[78:79], off
	s_waitcnt vmcnt(8)
	s_waitcnt lgkmcnt(0)
	s_barrier
	s_setprio 1
	s_setprio 0
	s_barrier
	s_movk_i32 s13, 0x100
	s_andn2_b64 vcc, exec, s[22:23]
	s_mov_b64 s[36:37], -1
	s_mov_b64 s[22:23], 0
	s_cbranch_vccz .LBB0_1809
	s_and_b64 vcc, exec, s[10:11]
	s_cbranch_vccz .LBB0_1812
	s_barrier

; #define PG8_STAGE(bufoff, gbase, voff) do { _Pragma("unroll") for (int _i = 0; _i < 2; ++_i) \
;         __builtin_amdgcn_global_load_lds((const unsigned*)((const char*)(gbase) + (voff)[_i]), (PG8_LAS unsigned*)(lds + (bufoff) + ldsw + _i * 8192), 16, 0, 0); } while (0)
; #define PG8_LDA(dst, b, h) do { _Pragma("unroll") for (int m = 0; m < 4; ++m) _Pragma("unroll") for (int k = 0; k < 2; ++k) dst[m][k] = *(const PG8_LAS bf16x8*)(lds + PG8_SA(b, h) + aoff + m * 2048 + k * 1024); } while (0)
; #define PG8_LDB(dst, b, h) do { _Pragma("unroll") for (int n = 0; n < 2; ++n) _Pragma("unroll") for (int k = 0; k < 2; ++k) dst[n][k] = *(const PG8_LAS bf16x8*)(lds + PG8_SB(b, h) + boff + n * 2048 + k * 1024); } while (0)
; #define PG8_MMA(ai, bj, At, Bt) do { __builtin_amdgcn_s_setprio(1); _Pragma("unroll") for (int m = 0; m < 4; ++m) _Pragma("unroll") for (int n = 0; n < 2; ++n) _Pragma("unroll") for (int k = 0; k < 2; ++k) \
;         acc[ai][bj][m][n] = __builtin_amdgcn_mfma_f32_16x16x32_bf16(Bt[n][k], At[m][k], acc[ai][bj][m][n], 0, 0, 0); __builtin_amdgcn_s_setprio(0); } while (0)
; #define PG8_WAIT_V(n) asm volatile("s_waitcnt vmcnt(" #n ")" ::: "memory")
; #define PG8_WAIT_L(n) asm volatile("s_waitcnt lgkmcnt(" #n ")" ::: "memory")
; #define PG8_BAR __builtin_amdgcn_s_barrier()
; #define PG8_SCHED __builtin_amdgcn_sched_barrier(0)
; template <class Epi, class Sched, bool ALIGN_EPI = false, bool SP2 = false>
; __device__ __forceinline__ void gemm_phase(PG8_LAS unsigned char* lds, const Gemm g, const Sched& S, const Epi& E) {
;     ...
;         for (int t = 0; t < nt; t += 2) {
;             const bool last = (t == nt - 2);
;             const char* a1 = cA + (size_t)(t + 1) * kstep;
;             const char* a2 = last ? nA : cA + (size_t)(t + 2) * kstep; const char* b2 = last ? nB : cB + (size_t)(t + 2) * kstep;
;             const char* a3 = a2 + kstep; const char* b3 = b2 + kstep;
;             if (last && has_next) S.a_ready(nxt);
;             if constexpr (SP2) {
;             PG8_LDB(B0, 0, 0); PG8_LDB(B1, 0, 1); PG8_SCHED; PG8_LDA(At, 0, 0); PG8_STAGE(PG8_SA(1, 1), a1 + hstepA, voffA);
;             PG8_WAIT_V(8); PG8_WAIT_L(0); PG8_BAR; PG8_MMA(0, 0, At, B0); PG8_MMA(0, 1, At, B1); PG8_BAR; PG8_SCHED;
;             PG8_LDA(At, 0, 1); PG8_STAGE(PG8_SB(0, 0), b2, voffB); PG8_STAGE(PG8_SB(0, 1), b2 + hstepB, voffB); PG8_STAGE(PG8_SA(0, 0), a2, voffA);
.LBB0_1938:
	s_add_u32 s24, s4, 0xfff80080
	s_addc_u32 s25, s5, -1
	s_add_i32 s26, 0, 0x10000
	s_cmp_eq_u32 s93, 28
	s_cselect_b32 s39, s19, s25
	s_cselect_b32 s38, s55, s24
	s_cselect_b32 s37, s17, s92
	s_cselect_b32 s36, s56, s57
	s_add_i32 s27, 0, 0x14000
	v_add_u32_e32 v58, s26, v191
	v_add_u32_e32 v86, s27, v191
	ds_read_b128 v[42:45], v58
	ds_read_b128 v[46:49], v58 offset:1024
	ds_read_b128 v[50:53], v58 offset:2048
	ds_read_b128 v[58:61], v58 offset:3072
	ds_read_b128 v[74:77], v86
	ds_read_b128 v[78:81], v86 offset:1024
	ds_read_b128 v[82:85], v86 offset:2048
	ds_read_b128 v[86:89], v86 offset:3072
	v_lshl_add_u64 v[168:169], s[4:5], 0, v[180:181]
	s_add_i32 m0, s41, 0xc000
	ds_read_b128 v[184:187], v209
	ds_read_b128 v[210:213], v209 offset:1024
	ds_read_b128 v[214:217], v209 offset:2048
	ds_read_b128 v[218:221], v209 offset:3072
	ds_read_b128 v[222:225], v209 offset:4096
	ds_read_b128 v[226:229], v209 offset:5120
	ds_read_b128 v[230:233], v209 offset:6144
	ds_read_b128 v[234:237], v209 offset:7168
	global_load_lds_dwordx4 v[168:169], off
	v_lshl_add_u64 v[168:169], s[4:5], 0, v[182:183]
	s_add_i32 m0, s41, 0xe000
	s_nop 0
	global_load_lds_dwordx4 v[168:169], off
	s_waitcnt vmcnt(8)
	s_waitcnt lgkmcnt(0)
	s_barrier
	s_setprio 1
	s_waitcnt lgkmcnt(0)
	v_mfma_f32_16x16x32_bf16 v[158:161], v[42:45], v[184:187], v[158:161]
	v_mfma_f32_16x16x32_bf16 v[154:157], v[50:53], v[184:187], v[154:157]
	v_mfma_f32_16x16x32_bf16 v[142:145], v[42:45], v[214:217], v[142:145]
	v_mfma_f32_16x16x32_bf16 v[138:141], v[50:53], v[214:217], v[138:141]
	v_mfma_f32_16x16x32_bf16 v[126:129], v[42:45], v[222:225], v[126:129]
	v_mfma_f32_16x16x32_bf16 v[122:125], v[50:53], v[222:225], v[122:125]
	v_mfma_f32_16x16x32_bf16 v[110:113], v[42:45], v[230:233], v[110:113]
	v_mfma_f32_16x16x32_bf16 v[106:109], v[50:53], v[230:233], v[106:109]
	v_mfma_f32_16x16x32_bf16 v[158:161], v[46:49], v[210:213], v[158:161]
	v_mfma_f32_16x16x32_bf16 v[154:157], v[58:61], v[210:213], v[154:157]
	v_mfma_f32_16x16x32_bf16 v[142:145], v[46:49], v[218:221], v[142:145]
	v_mfma_f32_16x16x32_bf16 v[138:141], v[58:61], v[218:221], v[138:141]
	v_mfma_f32_16x16x32_bf16 v[126:129], v[46:49], v[226:229], v[126:129]
	v_mfma_f32_16x16x32_bf16 v[122:125], v[58:61], v[226:229], v[122:125]
	v_mfma_f32_16x16x32_bf16 v[110:113], v[46:49], v[234:237], v[110:113]
	v_mfma_f32_16x16x32_bf16 v[106:109], v[58:61], v[234:237], v[106:109]
	v_mfma_f32_16x16x32_bf16 v[150:153], v[74:77], v[184:187], v[150:153]
	v_mfma_f32_16x16x32_bf16 v[146:149], v[82:85], v[184:187], v[146:149]
	v_mfma_f32_16x16x32_bf16 v[134:137], v[74:77], v[214:217], v[134:137]
	v_mfma_f32_16x16x32_bf16 v[130:133], v[82:85], v[214:217], v[130:133]
	v_mfma_f32_16x16x32_bf16 v[118:121], v[74:77], v[222:225], v[118:121]
	v_mfma_f32_16x16x32_bf16 v[114:117], v[82:85], v[222:225], v[114:117]
	v_mfma_f32_16x16x32_bf16 v[102:105], v[74:77], v[230:233], v[102:105]
	v_mfma_f32_16x16x32_bf16 v[98:101], v[82:85], v[230:233], v[98:101]
	v_mfma_f32_16x16x32_bf16 v[150:153], v[78:81], v[210:213], v[150:153]
	v_mfma_f32_16x16x32_bf16 v[146:149], v[86:89], v[210:213], v[146:149]
	v_mfma_f32_16x16x32_bf16 v[134:137], v[78:81], v[218:221], v[134:137]
	v_mfma_f32_16x16x32_bf16 v[130:133], v[86:89], v[218:221], v[130:133]
	v_mfma_f32_16x16x32_bf16 v[118:121], v[78:81], v[226:229], v[118:121]
	v_mfma_f32_16x16x32_bf16 v[114:117], v[86:89], v[226:229], v[114:117]
	v_mfma_f32_16x16x32_bf16 v[102:105], v[78:81], v[234:237], v[102:105]
	v_mfma_f32_16x16x32_bf16 v[98:101], v[86:89], v[234:237], v[98:101]
	s_setprio 0
	s_barrier
	s_add_i32 s24, s26, s40
	v_lshl_add_u64 v[168:169], s[36:37], 0, v[162:163]
	s_mov_b32 m0, s24
	ds_read_b128 v[184:187], v209 offset:16384
	ds_read_b128 v[210:213], v209 offset:17408
	ds_read_b128 v[214:217], v209 offset:18432
	ds_read_b128 v[218:221], v209 offset:19456
	ds_read_b128 v[222:225], v209 offset:20480
	ds_read_b128 v[226:229], v209 offset:21504
	ds_read_b128 v[230:233], v209 offset:22528
	ds_read_b128 v[234:237], v209 offset:23552
	global_load_lds_dwordx4 v[168:169], off
	s_add_i32 m0, s24, 0x2000
	s_add_u32 s24, s36, 0x80000
	v_lshl_add_u64 v[170:171], s[36:37], 0, v[178:179]
	s_addc_u32 s25, s37, 0
	s_add_i32 s26, s27, s40
	global_load_lds_dwordx4 v[170:171], off
	v_lshl_add_u64 v[172:173], s[24:25], 0, v[162:163]
	s_mov_b32 m0, s26
	v_lshl_add_u64 v[188:189], s[38:39], 0, v[178:179]
	global_load_lds_dwordx4 v[172:173], off
	v_lshl_add_u64 v[172:173], s[24:25], 0, v[178:179]
	s_add_i32 m0, s26, 0x2000
	s_nop 0
	global_load_lds_dwordx4 v[172:173], off
	v_lshl_add_u64 v[172:173], s[38:39], 0, v[162:163]
	s_mov_b32 m0, s41
	s_nop 0
	global_load_lds_dwordx4 v[172:173], off
	s_mov_b32 m0, s42
	s_nop 0
	global_load_lds_dwordx4 v[188:189], off
	s_waitcnt vmcnt(8)
	s_waitcnt lgkmcnt(0)
	s_barrier
; #define PG8_STAGE(bufoff, gbase, voff) do { _Pragma("unroll") for (int _i = 0; _i < 2; ++_i) \
;         __builtin_amdgcn_global_load_lds((const unsigned*)((const char*)(gbase) + (voff)[_i]), (PG8_LAS unsigned*)(lds + (bufoff) + ldsw + _i * 8192), 16, 0, 0); } while (0)
; #define PG8_LDA(dst, b, h) do { _Pragma("unroll") for (int m = 0; m < 4; ++m) _Pragma("unroll") for (int k = 0; k < 2; ++k) dst[m][k] = *(const PG8_LAS bf16x8*)(lds + PG8_SA(b, h) + aoff + m * 2048 + k * 1024); } while (0)
; #define PG8_LDB(dst, b, h) do { _Pragma("unroll") for (int n = 0; n < 2; ++n) _Pragma("unroll") for (int k = 0; k < 2; ++k) dst[n][k] = *(const PG8_LAS bf16x8*)(lds + PG8_SB(b, h) + boff + n * 2048 + k * 1024); } while (0)
; #define PG8_MMA(ai, bj, At, Bt) do { __builtin_amdgcn_s_setprio(1); _Pragma("unroll") for (int m = 0; m < 4; ++m) _Pragma("unroll") for (int n = 0; n < 2; ++n) _Pragma("unroll") for (int k = 0; k < 2; ++k) \
;         acc[ai][bj][m][n] = __builtin_amdgcn_mfma_f32_16x16x32_bf16(Bt[n][k], At[m][k], acc[ai][bj][m][n], 0, 0, 0); __builtin_amdgcn_s_setprio(0); } while (0)
; #define PG8_WAIT_V(n) asm volatile("s_waitcnt vmcnt(" #n ")" ::: "memory")
; #define PG8_WAIT_L(n) asm volatile("s_waitcnt lgkmcnt(" #n ")" ::: "memory")
; #define PG8_BAR __builtin_amdgcn_s_barrier()
; #define PG8_SCHED __builtin_amdgcn_sched_barrier(0)
; template <class Epi, class Sched, bool ALIGN_EPI = false, bool SP2 = false>
; __device__ __forceinline__ void gemm_phase(PG8_LAS unsigned char* lds, const Gemm g, const Sched& S, const Epi& E) {
;     ...
;             PG8_WAIT_V(8); PG8_WAIT_L(0); PG8_BAR; PG8_MMA(1, 0, At, B0); PG8_MMA(1, 1, At, B1); PG8_BAR; PG8_SCHED;
;             PG8_LDB(B0, 1, 0); PG8_LDB(B1, 1, 1); PG8_SCHED; PG8_LDA(At, 1, 0); PG8_STAGE(PG8_SA(0, 1), a2 + hstepA, voffA);
;             PG8_WAIT_V(8); PG8_WAIT_L(0); PG8_BAR; PG8_MMA(0, 0, At, B0); PG8_MMA(0, 1, At, B1); PG8_BAR; PG8_SCHED;
	s_setprio 1
	s_waitcnt lgkmcnt(0)
	v_mfma_f32_16x16x32_bf16 v[94:97], v[42:45], v[184:187], v[94:97]
	v_mfma_f32_16x16x32_bf16 v[90:93], v[50:53], v[184:187], v[90:93]
	v_mfma_f32_16x16x32_bf16 v[62:65], v[42:45], v[214:217], v[62:65]
	v_mfma_f32_16x16x32_bf16 v[54:57], v[50:53], v[214:217], v[54:57]
	v_mfma_f32_16x16x32_bf16 v[30:33], v[42:45], v[222:225], v[30:33]
	v_mfma_f32_16x16x32_bf16 v[26:29], v[50:53], v[222:225], v[26:29]
	v_mfma_f32_16x16x32_bf16 v[14:17], v[42:45], v[230:233], v[14:17]
	v_mfma_f32_16x16x32_bf16 v[10:13], v[50:53], v[230:233], v[10:13]
	v_mfma_f32_16x16x32_bf16 v[94:97], v[46:49], v[210:213], v[94:97]
	v_mfma_f32_16x16x32_bf16 v[90:93], v[58:61], v[210:213], v[90:93]
	v_mfma_f32_16x16x32_bf16 v[62:65], v[46:49], v[218:221], v[62:65]
	v_mfma_f32_16x16x32_bf16 v[54:57], v[58:61], v[218:221], v[54:57]
	v_mfma_f32_16x16x32_bf16 v[30:33], v[46:49], v[226:229], v[30:33]
	v_mfma_f32_16x16x32_bf16 v[26:29], v[58:61], v[226:229], v[26:29]
	v_mfma_f32_16x16x32_bf16 v[14:17], v[46:49], v[234:237], v[14:17]
	v_mfma_f32_16x16x32_bf16 v[10:13], v[58:61], v[234:237], v[10:13]
	v_mfma_f32_16x16x32_bf16 v[38:41], v[74:77], v[214:217], v[38:41]
	v_mfma_f32_16x16x32_bf16 v[34:37], v[82:85], v[214:217], v[34:37]
	v_mfma_f32_16x16x32_bf16 v[22:25], v[74:77], v[222:225], v[22:25]
	v_mfma_f32_16x16x32_bf16 v[18:21], v[82:85], v[222:225], v[18:21]
	v_mfma_f32_16x16x32_bf16 v[6:9], v[74:77], v[230:233], v[6:9]
	v_mfma_f32_16x16x32_bf16 v[2:5], v[82:85], v[230:233], v[2:5]
	v_mfma_f32_16x16x32_bf16 v[42:45], v[74:77], v[184:187], v[70:73]
	v_mfma_f32_16x16x32_bf16 v[46:49], v[82:85], v[184:187], v[66:69]
	v_mfma_f32_16x16x32_bf16 v[38:41], v[78:81], v[218:221], v[38:41]
	v_mfma_f32_16x16x32_bf16 v[34:37], v[86:89], v[218:221], v[34:37]
	v_mfma_f32_16x16x32_bf16 v[22:25], v[78:81], v[226:229], v[22:25]
	v_mfma_f32_16x16x32_bf16 v[18:21], v[86:89], v[226:229], v[18:21]
	v_mfma_f32_16x16x32_bf16 v[6:9], v[78:81], v[234:237], v[6:9]
	v_mfma_f32_16x16x32_bf16 v[2:5], v[86:89], v[234:237], v[2:5]
	v_mfma_f32_16x16x32_bf16 v[42:45], v[78:81], v[210:213], v[42:45]
	v_mfma_f32_16x16x32_bf16 v[46:49], v[86:89], v[210:213], v[46:49]
	s_setprio 0
	s_barrier
	s_add_i32 s26, 0, 0x18000
	s_add_i32 s27, 0, 0x1c000
	v_add_u32_e32 v70, s26, v191
	v_add_u32_e32 v86, s27, v191
	ds_read_b128 v[50:53], v70
	ds_read_b128 v[58:61], v70 offset:1024
	ds_read_b128 v[66:69], v70 offset:2048
	ds_read_b128 v[70:73], v70 offset:3072
	ds_read_b128 v[74:77], v86
	ds_read_b128 v[78:81], v86 offset:1024
	ds_read_b128 v[82:85], v86 offset:2048
	ds_read_b128 v[86:89], v86 offset:3072
	s_add_u32 s24, s38, 0x80000
	s_addc_u32 s25, s39, 0
	s_mov_b32 m0, s43
	v_lshl_add_u64 v[192:193], s[24:25], 0, v[162:163]
	ds_read_b128 v[184:187], v209 offset:32768
	ds_read_b128 v[210:213], v209 offset:33792
	ds_read_b128 v[214:217], v209 offset:34816
	ds_read_b128 v[218:221], v209 offset:35840
	ds_read_b128 v[222:225], v209 offset:36864
	ds_read_b128 v[226:229], v209 offset:37888
	ds_read_b128 v[230:233], v209 offset:38912
	ds_read_b128 v[234:237], v209 offset:39936
	global_load_lds_dwordx4 v[192:193], off
	v_lshl_add_u64 v[192:193], s[24:25], 0, v[178:179]
	s_mov_b32 m0, s44
	s_nop 0
	global_load_lds_dwordx4 v[192:193], off
	s_waitcnt vmcnt(8)
	s_waitcnt lgkmcnt(0)
	s_barrier
	s_setprio 1
	s_waitcnt lgkmcnt(0)
	v_mfma_f32_16x16x32_bf16 v[158:161], v[50:53], v[184:187], v[158:161]
	v_mfma_f32_16x16x32_bf16 v[154:157], v[66:69], v[184:187], v[154:157]
	v_mfma_f32_16x16x32_bf16 v[142:145], v[50:53], v[214:217], v[142:145]
	v_mfma_f32_16x16x32_bf16 v[138:141], v[66:69], v[214:217], v[138:141]
	v_mfma_f32_16x16x32_bf16 v[126:129], v[50:53], v[222:225], v[126:129]
	v_mfma_f32_16x16x32_bf16 v[122:125], v[66:69], v[222:225], v[122:125]
	v_mfma_f32_16x16x32_bf16 v[110:113], v[50:53], v[230:233], v[110:113]
	v_mfma_f32_16x16x32_bf16 v[106:109], v[66:69], v[230:233], v[106:109]
	v_mfma_f32_16x16x32_bf16 v[158:161], v[58:61], v[210:213], v[158:161]
	v_mfma_f32_16x16x32_bf16 v[154:157], v[70:73], v[210:213], v[154:157]
	v_mfma_f32_16x16x32_bf16 v[142:145], v[58:61], v[218:221], v[142:145]
	v_mfma_f32_16x16x32_bf16 v[138:141], v[70:73], v[218:221], v[138:141]
	v_mfma_f32_16x16x32_bf16 v[126:129], v[58:61], v[226:229], v[126:129]
	v_mfma_f32_16x16x32_bf16 v[122:125], v[70:73], v[226:229], v[122:125]
	v_mfma_f32_16x16x32_bf16 v[110:113], v[58:61], v[234:237], v[110:113]
	v_mfma_f32_16x16x32_bf16 v[106:109], v[70:73], v[234:237], v[106:109]
	v_mfma_f32_16x16x32_bf16 v[150:153], v[74:77], v[184:187], v[150:153]
	v_mfma_f32_16x16x32_bf16 v[146:149], v[82:85], v[184:187], v[146:149]
	v_mfma_f32_16x16x32_bf16 v[134:137], v[74:77], v[214:217], v[134:137]
	v_mfma_f32_16x16x32_bf16 v[130:133], v[82:85], v[214:217], v[130:133]
	v_mfma_f32_16x16x32_bf16 v[118:121], v[74:77], v[222:225], v[118:121]
	v_mfma_f32_16x16x32_bf16 v[114:117], v[82:85], v[222:225], v[114:117]
	v_mfma_f32_16x16x32_bf16 v[102:105], v[74:77], v[230:233], v[102:105]
	v_mfma_f32_16x16x32_bf16 v[98:101], v[82:85], v[230:233], v[98:101]
	v_mfma_f32_16x16x32_bf16 v[150:153], v[78:81], v[210:213], v[150:153]
	v_mfma_f32_16x16x32_bf16 v[146:149], v[86:89], v[210:213], v[146:149]
	v_mfma_f32_16x16x32_bf16 v[134:137], v[78:81], v[218:221], v[134:137]
	v_mfma_f32_16x16x32_bf16 v[130:133], v[86:89], v[218:221], v[130:133]
	v_mfma_f32_16x16x32_bf16 v[118:121], v[78:81], v[226:229], v[118:121]
	v_mfma_f32_16x16x32_bf16 v[114:117], v[86:89], v[226:229], v[114:117]
	v_mfma_f32_16x16x32_bf16 v[102:105], v[78:81], v[234:237], v[102:105]
	v_mfma_f32_16x16x32_bf16 v[98:101], v[86:89], v[234:237], v[98:101]
	s_setprio 0
	s_barrier
; #define PG8_STAGE(bufoff, gbase, voff) do { _Pragma("unroll") for (int _i = 0; _i < 2; ++_i) \
;         __builtin_amdgcn_global_load_lds((const unsigned*)((const char*)(gbase) + (voff)[_i]), (PG8_LAS unsigned*)(lds + (bufoff) + ldsw + _i * 8192), 16, 0, 0); } while (0)
; #define PG8_LDA(dst, b, h) do { _Pragma("unroll") for (int m = 0; m < 4; ++m) _Pragma("unroll") for (int k = 0; k < 2; ++k) dst[m][k] = *(const PG8_LAS bf16x8*)(lds + PG8_SA(b, h) + aoff + m * 2048 + k * 1024); } while (0)
; #define PG8_WAIT_V(n) asm volatile("s_waitcnt vmcnt(" #n ")" ::: "memory")
; template <class Epi, class Sched, bool ALIGN_EPI = false, bool SP2 = false>
; __device__ __forceinline__ void gemm_phase(PG8_LAS unsigned char* lds, const Gemm g, const Sched& S, const Epi& E) {
;     ...
;             PG8_LDA(At, 1, 1); PG8_STAGE(PG8_SB(1, 0), b3, voffB); PG8_STAGE(PG8_SB(1, 1), b3 + hstepB, voffB); PG8_STAGE(PG8_SA(1, 0), a3, voffA);
;             PG8_WAIT_V(8); PG8_WAIT_L(0); PG8_BAR; PG8_MMA(1, 0, At, B0); PG8_MMA(1, 1, At, B1); PG8_BAR; PG8_SCHED;
;             } else {
;             PG8_LDB(B0, 0, 0); PG8_SCHED; PG8_LDA(At, 0, 0); PG8_STAGE(PG8_SA(1, 1), a1 + hstepA, voffA);
;             PG8_WAIT_L(8); PG8_BAR; PG8_WAIT_L(0); PG8_MMA(0, 0, At, B0); PG8_BAR; PG8_SCHED;
;             PG8_LDB(B1, 0, 1); PG8_STAGE(PG8_SB(0, 0), b2, voffB);
;             PG8_BAR; PG8_WAIT_L(0); PG8_MMA(0, 1, At, B1); PG8_BAR;
;             PG8_LDA(At, 0, 1); PG8_STAGE(PG8_SA(0, 0), a2, voffA);
;             PG8_BAR; PG8_WAIT_L(0); PG8_MMA(1, 0, At, B0); PG8_BAR; PG8_SCHED;
;             PG8_STAGE(PG8_SB(0, 1), b2 + hstepB, voffB);
;             PG8_WAIT_V(6); PG8_BAR; PG8_MMA(1, 1, At, B1); PG8_BAR;
;             PG8_LDB(B0, 1, 0); PG8_SCHED; PG8_LDA(At, 1, 0); PG8_STAGE(PG8_SA(0, 1), a2 + hstepA, voffA);
;             PG8_WAIT_L(8); PG8_BAR; PG8_WAIT_L(0); PG8_MMA(0, 0, At, B0); PG8_BAR; PG8_SCHED;
;             PG8_LDB(B1, 1, 1); PG8_STAGE(PG8_SB(1, 0), b3, voffB);
;             PG8_BAR; PG8_WAIT_L(0); PG8_MMA(0, 1, At, B1); PG8_BAR;
;             PG8_LDA(At, 1, 1); PG8_STAGE(PG8_SA(1, 0), a3, voffA);
;             PG8_BAR; PG8_WAIT_L(0); PG8_MMA(1, 0, At, B0); PG8_BAR; PG8_SCHED;
;             PG8_STAGE(PG8_SB(1, 1), b3 + hstepB, voffB);
;             PG8_WAIT_V(6); PG8_BAR; PG8_MMA(1, 1, At, B1); PG8_BAR;
;             }
;         }
;         if constexpr (ALIGN_EPI) { if (wr == 0) PG8_BAR; }
	s_add_i32 s24, s26, s40
	v_lshl_add_u64 v[168:169], v[168:169], 0, s[50:51]
	s_mov_b32 m0, s24
	ds_read_b128 v[184:187], v209 offset:49152
	ds_read_b128 v[210:213], v209 offset:50176
	ds_read_b128 v[214:217], v209 offset:51200
	ds_read_b128 v[218:221], v209 offset:52224
	ds_read_b128 v[222:225], v209 offset:53248
	ds_read_b128 v[226:229], v209 offset:54272
	ds_read_b128 v[230:233], v209 offset:55296
	ds_read_b128 v[234:237], v209 offset:56320
	global_load_lds_dwordx4 v[168:169], off
	s_add_i32 m0, s24, 0x2000
	s_add_u32 s24, s36, 0x80080
	v_lshl_add_u64 v[168:169], v[170:171], 0, s[50:51]
	s_addc_u32 s25, s37, 0
	s_add_i32 s26, s27, s40
	global_load_lds_dwordx4 v[168:169], off
	v_lshl_add_u64 v[168:169], s[24:25], 0, v[162:163]
	s_mov_b32 m0, s26
	s_nop 0
	global_load_lds_dwordx4 v[168:169], off
	v_lshl_add_u64 v[168:169], s[24:25], 0, v[178:179]
	s_add_i32 m0, s26, 0x2000
	s_nop 0
	global_load_lds_dwordx4 v[168:169], off
	v_lshl_add_u64 v[168:169], v[172:173], 0, s[50:51]
	s_mov_b32 m0, s46
	s_nop 0
	global_load_lds_dwordx4 v[168:169], off
	v_lshl_add_u64 v[168:169], v[188:189], 0, s[50:51]
	s_mov_b32 m0, s47
	s_nop 0
	global_load_lds_dwordx4 v[168:169], off
	s_waitcnt vmcnt(8)
	s_waitcnt lgkmcnt(0)
	s_barrier
	s_setprio 1
	s_waitcnt lgkmcnt(0)
	v_mfma_f32_16x16x32_bf16 v[94:97], v[50:53], v[184:187], v[94:97]
	v_mfma_f32_16x16x32_bf16 v[90:93], v[66:69], v[184:187], v[90:93]
	v_mfma_f32_16x16x32_bf16 v[62:65], v[50:53], v[214:217], v[62:65]
	v_mfma_f32_16x16x32_bf16 v[54:57], v[66:69], v[214:217], v[54:57]
	v_mfma_f32_16x16x32_bf16 v[30:33], v[50:53], v[222:225], v[30:33]
	v_mfma_f32_16x16x32_bf16 v[26:29], v[66:69], v[222:225], v[26:29]
	v_mfma_f32_16x16x32_bf16 v[14:17], v[50:53], v[230:233], v[14:17]
	v_mfma_f32_16x16x32_bf16 v[10:13], v[66:69], v[230:233], v[10:13]
	v_mfma_f32_16x16x32_bf16 v[94:97], v[58:61], v[210:213], v[94:97]
	v_mfma_f32_16x16x32_bf16 v[90:93], v[70:73], v[210:213], v[90:93]
	v_mfma_f32_16x16x32_bf16 v[62:65], v[58:61], v[218:221], v[62:65]
	v_mfma_f32_16x16x32_bf16 v[54:57], v[70:73], v[218:221], v[54:57]
	v_mfma_f32_16x16x32_bf16 v[30:33], v[58:61], v[226:229], v[30:33]
	v_mfma_f32_16x16x32_bf16 v[26:29], v[70:73], v[226:229], v[26:29]
	v_mfma_f32_16x16x32_bf16 v[14:17], v[58:61], v[234:237], v[14:17]
	v_mfma_f32_16x16x32_bf16 v[10:13], v[70:73], v[234:237], v[10:13]
	v_mfma_f32_16x16x32_bf16 v[42:45], v[74:77], v[184:187], v[42:45]
	v_mfma_f32_16x16x32_bf16 v[70:73], v[78:81], v[210:213], v[42:45]
	v_mfma_f32_16x16x32_bf16 v[42:45], v[82:85], v[184:187], v[46:49]
	v_mfma_f32_16x16x32_bf16 v[38:41], v[74:77], v[214:217], v[38:41]
	v_mfma_f32_16x16x32_bf16 v[34:37], v[82:85], v[214:217], v[34:37]
	v_mfma_f32_16x16x32_bf16 v[22:25], v[74:77], v[222:225], v[22:25]
	v_mfma_f32_16x16x32_bf16 v[18:21], v[82:85], v[222:225], v[18:21]
	v_mfma_f32_16x16x32_bf16 v[6:9], v[74:77], v[230:233], v[6:9]
	v_mfma_f32_16x16x32_bf16 v[2:5], v[82:85], v[230:233], v[2:5]
	v_mfma_f32_16x16x32_bf16 v[66:69], v[86:89], v[210:213], v[42:45]
	v_mfma_f32_16x16x32_bf16 v[38:41], v[78:81], v[218:221], v[38:41]
	v_mfma_f32_16x16x32_bf16 v[34:37], v[86:89], v[218:221], v[34:37]
	v_mfma_f32_16x16x32_bf16 v[22:25], v[78:81], v[226:229], v[22:25]
	v_mfma_f32_16x16x32_bf16 v[18:21], v[86:89], v[226:229], v[18:21]
	v_mfma_f32_16x16x32_bf16 v[6:9], v[78:81], v[234:237], v[6:9]
	v_mfma_f32_16x16x32_bf16 v[2:5], v[86:89], v[234:237], v[2:5]
	s_setprio 0
	s_barrier
	s_add_i32 s93, s93, 2
	s_add_u32 s4, s4, 0x100
	s_addc_u32 s5, s5, 0
	s_add_u32 s57, s57, 0x100
	s_addc_u32 s92, s92, 0
	s_cmp_gt_u32 s93, 29
	s_cbranch_scc0 .LBB0_1938
	s_and_b64 vcc, exec, s[14:15]
	s_cbranch_vccz .LBB0_1941
	s_barrier

; #define PG8_STAGE(bufoff, gbase, voff) do { _Pragma("unroll") for (int _i = 0; _i < 2; ++_i) \
;         __builtin_amdgcn_global_load_lds((const unsigned*)((const char*)(gbase) + (voff)[_i]), (PG8_LAS unsigned*)(lds + (bufoff) + ldsw + _i * 8192), 16, 0, 0); } while (0)
; #define PG8_LDA(dst, b, h) do { _Pragma("unroll") for (int m = 0; m < 4; ++m) _Pragma("unroll") for (int k = 0; k < 2; ++k) dst[m][k] = *(const PG8_LAS bf16x8*)(lds + PG8_SA(b, h) + aoff + m * 2048 + k * 1024); } while (0)
; #define PG8_LDB(dst, b, h) do { _Pragma("unroll") for (int n = 0; n < 2; ++n) _Pragma("unroll") for (int k = 0; k < 2; ++k) dst[n][k] = *(const PG8_LAS bf16x8*)(lds + PG8_SB(b, h) + boff + n * 2048 + k * 1024); } while (0)
; #define PG8_MMA(ai, bj, At, Bt) do { __builtin_amdgcn_s_setprio(1); _Pragma("unroll") for (int m = 0; m < 4; ++m) _Pragma("unroll") for (int n = 0; n < 2; ++n) _Pragma("unroll") for (int k = 0; k < 2; ++k) \
;         acc[ai][bj][m][n] = __builtin_amdgcn_mfma_f32_16x16x32_bf16(Bt[n][k], At[m][k], acc[ai][bj][m][n], 0, 0, 0); __builtin_amdgcn_s_setprio(0); } while (0)
; #define PG8_WAIT_V(n) asm volatile("s_waitcnt vmcnt(" #n ")" ::: "memory")
; #define PG8_WAIT_L(n) asm volatile("s_waitcnt lgkmcnt(" #n ")" ::: "memory")
; #define PG8_BAR __builtin_amdgcn_s_barrier()
; #define PG8_SCHED __builtin_amdgcn_sched_barrier(0)
; template <class Epi, class Sched, bool ALIGN_EPI = false, bool SP2 = false>
; __device__ __forceinline__ void gemm_phase(PG8_LAS unsigned char* lds, const Gemm g, const Sched& S, const Epi& E) {
;     ...
;         for (int t = 0; t < nt; t += 2) {
;             const bool last = (t == nt - 2);
;             const char* a1 = cA + (size_t)(t + 1) * kstep;
;             const char* a2 = last ? nA : cA + (size_t)(t + 2) * kstep; const char* b2 = last ? nB : cB + (size_t)(t + 2) * kstep;
;             const char* a3 = a2 + kstep; const char* b3 = b2 + kstep;
;             if (last && has_next) S.a_ready(nxt);
;             if constexpr (SP2) {
;             PG8_LDB(B0, 0, 0); PG8_LDB(B1, 0, 1); PG8_SCHED; PG8_LDA(At, 0, 0); PG8_STAGE(PG8_SA(1, 1), a1 + hstepA, voffA);
;             PG8_WAIT_V(8); PG8_WAIT_L(0); PG8_BAR; PG8_MMA(0, 0, At, B0); PG8_MMA(0, 1, At, B1); PG8_BAR; PG8_SCHED;
;             PG8_LDA(At, 0, 1); PG8_STAGE(PG8_SB(0, 0), b2, voffB); PG8_STAGE(PG8_SB(0, 1), b2 + hstepB, voffB); PG8_STAGE(PG8_SA(0, 0), a2, voffA);
.LBB0_1982:
	s_add_u32 s13, s18, s11
	s_addc_u32 s26, s19, 0
	s_add_u32 s27, s13, 0x100
	s_addc_u32 s28, s26, 0
	s_and_b64 s[24:25], s[36:37], exec
	s_cselect_b32 s41, s17, s28
	s_cselect_b32 s40, s16, s27
	s_add_u32 s11, s4, s11
	s_addc_u32 s24, s5, 0
	s_add_u32 s11, s11, 0x100
	s_addc_u32 s27, s24, 0
	s_add_i32 s28, 0, 0x10000
	s_and_b64 s[24:25], s[36:37], exec
	s_cselect_b32 s43, s21, s27
	s_cselect_b32 s42, s20, s11
	s_add_i32 s24, 0, 0x14000
	s_add_u32 s46, s13, 0x80080
	s_addc_u32 s47, s26, 0
	s_add_i32 s26, s28, s49
	s_add_i32 m0, s54, 0xc000
	s_add_i32 s25, s54, 0xe000
	s_add_i32 s27, s26, 0x2000
	s_add_u32 s44, s42, 0x80000
	v_add_u32_e32 v90, s28, v1
	v_add_u32_e32 v106, s24, v1
	s_addc_u32 s45, s43, 0
	s_add_i32 s29, s24, s49
	ds_read_b128 v[78:81], v90
	ds_read_b128 v[82:85], v90 offset:1024
	ds_read_b128 v[86:89], v90 offset:2048
	ds_read_b128 v[90:93], v90 offset:3072
	ds_read_b128 v[94:97], v106
	ds_read_b128 v[98:101], v106 offset:1024
	ds_read_b128 v[102:105], v106 offset:2048
	ds_read_b128 v[106:109], v106 offset:3072
	s_add_i32 s30, s29, 0x2000
	s_add_i32 s31, 0, 0x18000
	s_add_i32 s95, 0, 0x1c000
	s_add_u32 s38, s40, 0x80000
	s_addc_u32 s39, s41, 0
	s_add_i32 s13, s31, s49
	s_add_i32 s11, s13, 0x2000
	s_add_u32 s36, s42, 0x80080
	s_addc_u32 s37, s43, 0
	s_add_i32 s24, s95, s49
	s_add_i32 s28, s24, 0x2000
	v_lshl_add_u64 v[142:143], s[46:47], 0, v[162:163]
	ds_read_b128 v[110:113], v77
	ds_read_b128 v[114:117], v77 offset:1024
	ds_read_b128 v[118:121], v77 offset:2048
	ds_read_b128 v[122:125], v77 offset:3072
	ds_read_b128 v[126:129], v77 offset:4096
	ds_read_b128 v[130:133], v77 offset:5120
	ds_read_b128 v[134:137], v77 offset:6144
	ds_read_b128 v[138:141], v77 offset:7168
	global_load_lds_dwordx4 v[142:143], off
	v_lshl_add_u64 v[142:143], s[46:47], 0, v[66:67]
	s_mov_b32 m0, s25
	s_nop 0
	global_load_lds_dwordx4 v[142:143], off
	s_waitcnt vmcnt(8)
	s_waitcnt lgkmcnt(0)
	s_barrier
	s_setprio 1
	s_waitcnt lgkmcnt(0)
	v_mfma_f32_16x16x32_bf16 v[62:65], v[78:81], v[110:113], v[62:65]
	v_mfma_f32_16x16x32_bf16 v[58:61], v[86:89], v[110:113], v[58:61]
	v_mfma_f32_16x16x32_bf16 v[54:57], v[78:81], v[118:121], v[54:57]
	v_mfma_f32_16x16x32_bf16 v[50:53], v[86:89], v[118:121], v[50:53]
	v_mfma_f32_16x16x32_bf16 v[46:49], v[78:81], v[126:129], v[46:49]
	v_mfma_f32_16x16x32_bf16 v[42:45], v[86:89], v[126:129], v[42:45]
	v_mfma_f32_16x16x32_bf16 v[30:33], v[78:81], v[134:137], v[30:33]
	v_mfma_f32_16x16x32_bf16 v[26:29], v[86:89], v[134:137], v[26:29]
	v_mfma_f32_16x16x32_bf16 v[62:65], v[82:85], v[114:117], v[62:65]
	v_mfma_f32_16x16x32_bf16 v[58:61], v[90:93], v[114:117], v[58:61]
	v_mfma_f32_16x16x32_bf16 v[54:57], v[82:85], v[122:125], v[54:57]
	v_mfma_f32_16x16x32_bf16 v[50:53], v[90:93], v[122:125], v[50:53]
	v_mfma_f32_16x16x32_bf16 v[46:49], v[82:85], v[130:133], v[46:49]
	v_mfma_f32_16x16x32_bf16 v[42:45], v[90:93], v[130:133], v[42:45]
	v_mfma_f32_16x16x32_bf16 v[30:33], v[82:85], v[138:141], v[30:33]
	v_mfma_f32_16x16x32_bf16 v[26:29], v[90:93], v[138:141], v[26:29]
	v_mfma_f32_16x16x32_bf16 v[38:41], v[94:97], v[110:113], v[38:41]
	v_mfma_f32_16x16x32_bf16 v[34:37], v[102:105], v[110:113], v[34:37]
	v_mfma_f32_16x16x32_bf16 v[22:25], v[94:97], v[118:121], v[22:25]
	v_mfma_f32_16x16x32_bf16 v[18:21], v[102:105], v[118:121], v[18:21]
	v_mfma_f32_16x16x32_bf16 v[14:17], v[94:97], v[126:129], v[14:17]
	v_mfma_f32_16x16x32_bf16 v[10:13], v[102:105], v[126:129], v[10:13]
	v_mfma_f32_16x16x32_bf16 v[6:9], v[94:97], v[134:137], v[6:9]
	v_mfma_f32_16x16x32_bf16 v[2:5], v[102:105], v[134:137], v[2:5]
	v_mfma_f32_16x16x32_bf16 v[38:41], v[98:101], v[114:117], v[38:41]
	v_mfma_f32_16x16x32_bf16 v[34:37], v[106:109], v[114:117], v[34:37]
	v_mfma_f32_16x16x32_bf16 v[22:25], v[98:101], v[122:125], v[22:25]
	v_mfma_f32_16x16x32_bf16 v[18:21], v[106:109], v[122:125], v[18:21]
	v_mfma_f32_16x16x32_bf16 v[14:17], v[98:101], v[130:133], v[14:17]
	v_mfma_f32_16x16x32_bf16 v[10:13], v[106:109], v[130:133], v[10:13]
	v_mfma_f32_16x16x32_bf16 v[6:9], v[98:101], v[138:141], v[6:9]
	v_mfma_f32_16x16x32_bf16 v[2:5], v[106:109], v[138:141], v[2:5]
	s_setprio 0
	s_barrier
	s_mov_b32 m0, s26
	v_lshl_add_u64 v[142:143], s[42:43], 0, v[162:163]
	global_load_lds_dwordx4 v[142:143], off
	v_lshl_add_u64 v[144:145], s[42:43], 0, v[66:67]
	s_mov_b32 m0, s27
	v_lshl_add_u64 v[78:79], s[44:45], 0, v[162:163]
	global_load_lds_dwordx4 v[144:145], off
	s_mov_b32 m0, s29
	v_lshl_add_u64 v[146:147], s[40:41], 0, v[162:163]
	global_load_lds_dwordx4 v[78:79], off
	v_lshl_add_u64 v[78:79], s[44:45], 0, v[66:67]
	s_mov_b32 m0, s30
	v_lshl_add_u64 v[148:149], s[40:41], 0, v[66:67]
	global_load_lds_dwordx4 v[78:79], off
	s_mov_b32 m0, s54
	s_nop 0
	global_load_lds_dwordx4 v[146:147], off
	s_mov_b32 m0, s55
	s_nop 0
	global_load_lds_dwordx4 v[148:149], off
	s_waitcnt vmcnt(8)
	s_waitcnt lgkmcnt(0)
	s_barrier
; #define PG8_WAIT_V(n) asm volatile("s_waitcnt vmcnt(" #n ")" ::: "memory")
; #define PG8_WAIT_L(n) asm volatile("s_waitcnt lgkmcnt(" #n ")" ::: "memory")
; #define PG8_BAR __builtin_amdgcn_s_barrier()
; template <class Epi, class Sched, bool ALIGN_EPI = false, bool SP2 = false>
; __device__ __forceinline__ void gemm_phase(PG8_LAS unsigned char* lds, const Gemm g, const Sched& S, const Epi& E) {
;     ...
;             PG8_WAIT_V(8); PG8_WAIT_L(0); PG8_BAR; PG8_MMA(1, 0, At, B0); PG8_MMA(1, 1, At, B1); PG8_BAR; PG8_SCHED;
;             PG8_LDB(B0, 1, 0); PG8_LDB(B1, 1, 1); PG8_SCHED; PG8_LDA(At, 1, 0); PG8_STAGE(PG8_SA(0, 1), a2 + hstepA, voffA);
;             PG8_WAIT_V(8); PG8_WAIT_L(0); PG8_BAR; PG8_MMA(0, 0, At, B0); PG8_MMA(0, 1, At, B1); PG8_BAR; PG8_SCHED;
;             PG8_LDA(At, 1, 1); PG8_STAGE(PG8_SB(1, 0), b3, voffB); PG8_STAGE(PG8_SB(1, 1), b3 + hstepB, voffB); PG8_STAGE(PG8_SA(1, 0), a3, voffA);
;             PG8_WAIT_V(8); PG8_WAIT_L(0); PG8_BAR; PG8_MMA(1, 0, At, B0); PG8_MMA(1, 1, At, B1); PG8_BAR; PG8_SCHED;
;             } else {
;             PG8_LDB(B0, 0, 0); PG8_SCHED; PG8_LDA(At, 0, 0); PG8_STAGE(PG8_SA(1, 1), a1 + hstepA, voffA);
;             PG8_WAIT_L(8); PG8_BAR; PG8_WAIT_L(0); PG8_MMA(0, 0, At, B0); PG8_BAR; PG8_SCHED;
;             PG8_LDB(B1, 0, 1); PG8_STAGE(PG8_SB(0, 0), b2, voffB);
;             PG8_BAR; PG8_WAIT_L(0); PG8_MMA(0, 1, At, B1); PG8_BAR;
;             PG8_LDA(At, 0, 1); PG8_STAGE(PG8_SA(0, 0), a2, voffA);
;             PG8_BAR; PG8_WAIT_L(0); PG8_MMA(1, 0, At, B0); PG8_BAR; PG8_SCHED;
;             PG8_STAGE(PG8_SB(0, 1), b2 + hstepB, voffB);
;             PG8_WAIT_V(6); PG8_BAR; PG8_MMA(1, 1, At, B1); PG8_BAR;
;             PG8_LDB(B0, 1, 0); PG8_SCHED; PG8_LDA(At, 1, 0); PG8_STAGE(PG8_SA(0, 1), a2 + hstepA, voffA);
;             PG8_WAIT_L(8); PG8_BAR; PG8_WAIT_L(0); PG8_MMA(0, 0, At, B0); PG8_BAR; PG8_SCHED;
;             PG8_LDB(B1, 1, 1); PG8_STAGE(PG8_SB(1, 0), b3, voffB);
;             PG8_BAR; PG8_WAIT_L(0); PG8_MMA(0, 1, At, B1); PG8_BAR;
;             PG8_LDA(At, 1, 1); PG8_STAGE(PG8_SA(1, 0), a3, voffA);
;             PG8_BAR; PG8_WAIT_L(0); PG8_MMA(1, 0, At, B0); PG8_BAR; PG8_SCHED;
;             PG8_STAGE(PG8_SB(1, 1), b3 + hstepB, voffB);
;             PG8_WAIT_V(6); PG8_BAR; PG8_MMA(1, 1, At, B1); PG8_BAR;
;             }
;         }
;         if constexpr (ALIGN_EPI) { if (wr == 0) PG8_BAR; }
	s_setprio 1
	s_setprio 0
	s_barrier
	v_add_u32_e32 v90, s31, v1
	v_add_u32_e32 v106, s95, v1
	ds_read_b128 v[78:81], v90
	ds_read_b128 v[82:85], v90 offset:1024
	ds_read_b128 v[86:89], v90 offset:2048
	ds_read_b128 v[90:93], v90 offset:3072
	ds_read_b128 v[94:97], v106
	ds_read_b128 v[98:101], v106 offset:1024
	ds_read_b128 v[102:105], v106 offset:2048
	ds_read_b128 v[106:109], v106 offset:3072
	s_mov_b32 m0, s56
	v_lshl_add_u64 v[150:151], s[38:39], 0, v[162:163]
	ds_read_b128 v[110:113], v77 offset:32768
	ds_read_b128 v[114:117], v77 offset:33792
	ds_read_b128 v[118:121], v77 offset:34816
	ds_read_b128 v[122:125], v77 offset:35840
	ds_read_b128 v[126:129], v77 offset:36864
	ds_read_b128 v[130:133], v77 offset:37888
	ds_read_b128 v[134:137], v77 offset:38912
	ds_read_b128 v[138:141], v77 offset:39936
	global_load_lds_dwordx4 v[150:151], off
	v_lshl_add_u64 v[150:151], s[38:39], 0, v[66:67]
	s_mov_b32 m0, s57
	s_nop 0
	global_load_lds_dwordx4 v[150:151], off
	s_waitcnt vmcnt(8)
	s_waitcnt lgkmcnt(0)
	s_barrier
	s_setprio 1
	s_waitcnt lgkmcnt(0)
	v_mfma_f32_16x16x32_bf16 v[62:65], v[78:81], v[110:113], v[62:65]
	v_mfma_f32_16x16x32_bf16 v[58:61], v[86:89], v[110:113], v[58:61]
	v_mfma_f32_16x16x32_bf16 v[54:57], v[78:81], v[118:121], v[54:57]
	v_mfma_f32_16x16x32_bf16 v[50:53], v[86:89], v[118:121], v[50:53]
	v_mfma_f32_16x16x32_bf16 v[46:49], v[78:81], v[126:129], v[46:49]
	v_mfma_f32_16x16x32_bf16 v[42:45], v[86:89], v[126:129], v[42:45]
	v_mfma_f32_16x16x32_bf16 v[30:33], v[78:81], v[134:137], v[30:33]
	v_mfma_f32_16x16x32_bf16 v[26:29], v[86:89], v[134:137], v[26:29]
	v_mfma_f32_16x16x32_bf16 v[62:65], v[82:85], v[114:117], v[62:65]
	v_mfma_f32_16x16x32_bf16 v[58:61], v[90:93], v[114:117], v[58:61]
	v_mfma_f32_16x16x32_bf16 v[54:57], v[82:85], v[122:125], v[54:57]
	v_mfma_f32_16x16x32_bf16 v[50:53], v[90:93], v[122:125], v[50:53]
	v_mfma_f32_16x16x32_bf16 v[46:49], v[82:85], v[130:133], v[46:49]
	v_mfma_f32_16x16x32_bf16 v[42:45], v[90:93], v[130:133], v[42:45]
	v_mfma_f32_16x16x32_bf16 v[30:33], v[82:85], v[138:141], v[30:33]
	v_mfma_f32_16x16x32_bf16 v[26:29], v[90:93], v[138:141], v[26:29]
	v_mfma_f32_16x16x32_bf16 v[38:41], v[94:97], v[110:113], v[38:41]
	v_mfma_f32_16x16x32_bf16 v[34:37], v[102:105], v[110:113], v[34:37]
	v_mfma_f32_16x16x32_bf16 v[22:25], v[94:97], v[118:121], v[22:25]
	v_mfma_f32_16x16x32_bf16 v[18:21], v[102:105], v[118:121], v[18:21]
	v_mfma_f32_16x16x32_bf16 v[14:17], v[94:97], v[126:129], v[14:17]
	v_mfma_f32_16x16x32_bf16 v[10:13], v[102:105], v[126:129], v[10:13]
	v_mfma_f32_16x16x32_bf16 v[6:9], v[94:97], v[134:137], v[6:9]
	v_mfma_f32_16x16x32_bf16 v[2:5], v[102:105], v[134:137], v[2:5]
	v_mfma_f32_16x16x32_bf16 v[38:41], v[98:101], v[114:117], v[38:41]
	v_mfma_f32_16x16x32_bf16 v[34:37], v[106:109], v[114:117], v[34:37]
	v_mfma_f32_16x16x32_bf16 v[22:25], v[98:101], v[122:125], v[22:25]
	v_mfma_f32_16x16x32_bf16 v[18:21], v[106:109], v[122:125], v[18:21]
	v_mfma_f32_16x16x32_bf16 v[14:17], v[98:101], v[130:133], v[14:17]
	v_mfma_f32_16x16x32_bf16 v[10:13], v[106:109], v[130:133], v[10:13]
	v_mfma_f32_16x16x32_bf16 v[6:9], v[98:101], v[138:141], v[6:9]
	v_mfma_f32_16x16x32_bf16 v[2:5], v[106:109], v[138:141], v[2:5]
	s_setprio 0
	s_barrier
	s_mov_b32 m0, s13
	v_lshl_add_u64 v[78:79], v[142:143], 0, s[50:51]
	global_load_lds_dwordx4 v[78:79], off
	v_lshl_add_u64 v[78:79], v[144:145], 0, s[50:51]
	s_mov_b32 m0, s11
	s_nop 0
	global_load_lds_dwordx4 v[78:79], off
	v_lshl_add_u64 v[78:79], s[36:37], 0, v[162:163]
	s_mov_b32 m0, s24
	s_nop 0
	global_load_lds_dwordx4 v[78:79], off
	v_lshl_add_u64 v[78:79], s[36:37], 0, v[66:67]
	s_mov_b32 m0, s28
	s_nop 0
	global_load_lds_dwordx4 v[78:79], off
	v_lshl_add_u64 v[78:79], v[146:147], 0, s[50:51]
	s_mov_b32 m0, s92
	s_nop 0
	global_load_lds_dwordx4 v[78:79], off
	v_lshl_add_u64 v[78:79], v[148:149], 0, s[50:51]
	s_mov_b32 m0, s93
	s_nop 0
	global_load_lds_dwordx4 v[78:79], off
	s_waitcnt vmcnt(8)
	s_waitcnt lgkmcnt(0)
	s_barrier
	s_setprio 1
	s_setprio 0
	s_barrier
	s_movk_i32 s11, 0x100
	s_andn2_b64 vcc, exec, s[22:23]
	s_mov_b64 s[36:37], -1
	s_mov_b64 s[22:23], 0
	s_cbranch_vccz .LBB0_1982
	s_and_b64 vcc, exec, s[8:9]
	s_cbranch_vccz .LBB0_1985
	s_barrier

; #define PG8_STAGE(bufoff, gbase, voff) do { _Pragma("unroll") for (int _i = 0; _i < 2; ++_i) \
;         __builtin_amdgcn_global_load_lds((const unsigned*)((const char*)(gbase) + (voff)[_i]), (PG8_LAS unsigned*)(lds + (bufoff) + ldsw + _i * 8192), 16, 0, 0); } while (0)
; #define PG8_LDA(dst, b, h) do { _Pragma("unroll") for (int m = 0; m < 4; ++m) _Pragma("unroll") for (int k = 0; k < 2; ++k) dst[m][k] = *(const PG8_LAS bf16x8*)(lds + PG8_SA(b, h) + aoff + m * 2048 + k * 1024); } while (0)
; #define PG8_LDB(dst, b, h) do { _Pragma("unroll") for (int n = 0; n < 2; ++n) _Pragma("unroll") for (int k = 0; k < 2; ++k) dst[n][k] = *(const PG8_LAS bf16x8*)(lds + PG8_SB(b, h) + boff + n * 2048 + k * 1024); } while (0)
; #define PG8_MMA(ai, bj, At, Bt) do { __builtin_amdgcn_s_setprio(1); _Pragma("unroll") for (int m = 0; m < 4; ++m) _Pragma("unroll") for (int n = 0; n < 2; ++n) _Pragma("unroll") for (int k = 0; k < 2; ++k) \
;         acc[ai][bj][m][n] = __builtin_amdgcn_mfma_f32_16x16x32_bf16(Bt[n][k], At[m][k], acc[ai][bj][m][n], 0, 0, 0); __builtin_amdgcn_s_setprio(0); } while (0)
; #define PG8_WAIT_V(n) asm volatile("s_waitcnt vmcnt(" #n ")" ::: "memory")
; #define PG8_WAIT_L(n) asm volatile("s_waitcnt lgkmcnt(" #n ")" ::: "memory")
; #define PG8_BAR __builtin_amdgcn_s_barrier()
; #define PG8_SCHED __builtin_amdgcn_sched_barrier(0)
; template <class Epi, class Sched, bool ALIGN_EPI = false, bool SP2 = false>
; __device__ __forceinline__ void gemm_phase(PG8_LAS unsigned char* lds, const Gemm g, const Sched& S, const Epi& E) {
;     ...
;         for (int t = 0; t < nt; t += 2) {
;             const bool last = (t == nt - 2);
;             const char* a1 = cA + (size_t)(t + 1) * kstep;
;             const char* a2 = last ? nA : cA + (size_t)(t + 2) * kstep; const char* b2 = last ? nB : cB + (size_t)(t + 2) * kstep;
;             const char* a3 = a2 + kstep; const char* b3 = b2 + kstep;
;             if (last && has_next) S.a_ready(nxt);
;             if constexpr (SP2) {
;             PG8_LDB(B0, 0, 0); PG8_LDB(B1, 0, 1); PG8_SCHED; PG8_LDA(At, 0, 0); PG8_STAGE(PG8_SA(1, 1), a1 + hstepA, voffA);
;             PG8_WAIT_V(8); PG8_WAIT_L(0); PG8_BAR; PG8_MMA(0, 0, At, B0); PG8_MMA(0, 1, At, B1); PG8_BAR; PG8_SCHED;
;             PG8_LDA(At, 0, 1); PG8_STAGE(PG8_SB(0, 0), b2, voffB); PG8_STAGE(PG8_SB(0, 1), b2 + hstepB, voffB); PG8_STAGE(PG8_SA(0, 0), a2, voffA);
.LBB0_2127:
	s_add_u32 s24, s22, 0xfff80080
	s_addc_u32 s25, s23, -1
	s_add_i32 s26, 0, 0x10000
	s_cmp_eq_u32 s57, 28
	s_cselect_b32 s39, s13, s25
	s_cselect_b32 s38, s19, s24
	v_add_u32_e32 v151, s26, v148
	s_cselect_b32 s37, s11, s56
	s_cselect_b32 s36, s21, s55
	s_add_i32 s27, 0, 0x14000
	ds_read_b128 v[144:147], v151
	ds_read_b128 v[152:155], v151 offset:1024
	ds_read_b128 v[156:159], v151 offset:2048
	ds_read_b128 v[178:181], v151 offset:3072
	v_add_u32_e32 v151, s27, v148
	ds_read_b128 v[182:185], v151
	ds_read_b128 v[186:189], v151 offset:1024
	ds_read_b128 v[190:193], v151 offset:2048
	ds_read_b128 v[210:213], v151 offset:3072
	v_lshl_add_u64 v[160:161], s[22:23], 0, v[140:141]
	s_add_i32 m0, s42, 0xc000
	ds_read_b128 v[214:217], v150
	ds_read_b128 v[218:221], v150 offset:1024
	ds_read_b128 v[222:225], v150 offset:2048
	ds_read_b128 v[226:229], v150 offset:3072
	ds_read_b128 v[230:233], v150 offset:4096
	ds_read_b128 v[234:237], v150 offset:5120
	ds_read_b128 v[238:241], v150 offset:6144
	ds_read_b128 v[242:245], v150 offset:7168
	global_load_lds_dwordx4 v[160:161], off
	v_lshl_add_u64 v[160:161], s[22:23], 0, v[142:143]
	s_add_i32 m0, s42, 0xe000
	s_nop 0
	global_load_lds_dwordx4 v[160:161], off
	s_waitcnt vmcnt(8)
	s_waitcnt lgkmcnt(0)
	s_barrier
	s_setprio 1
	s_waitcnt lgkmcnt(0)
	v_mfma_f32_16x16x32_bf16 v[126:129], v[144:147], v[214:217], v[126:129]
	v_mfma_f32_16x16x32_bf16 v[122:125], v[156:159], v[214:217], v[122:125]
	v_mfma_f32_16x16x32_bf16 v[110:113], v[144:147], v[222:225], v[110:113]
	v_mfma_f32_16x16x32_bf16 v[106:109], v[156:159], v[222:225], v[106:109]
	v_mfma_f32_16x16x32_bf16 v[94:97], v[144:147], v[230:233], v[94:97]
	v_mfma_f32_16x16x32_bf16 v[90:93], v[156:159], v[230:233], v[90:93]
	v_mfma_f32_16x16x32_bf16 v[78:81], v[144:147], v[238:241], v[78:81]
	v_mfma_f32_16x16x32_bf16 v[74:77], v[156:159], v[238:241], v[74:77]
	v_mfma_f32_16x16x32_bf16 v[126:129], v[152:155], v[218:221], v[126:129]
	v_mfma_f32_16x16x32_bf16 v[122:125], v[178:181], v[218:221], v[122:125]
	v_mfma_f32_16x16x32_bf16 v[110:113], v[152:155], v[226:229], v[110:113]
	v_mfma_f32_16x16x32_bf16 v[106:109], v[178:181], v[226:229], v[106:109]
	v_mfma_f32_16x16x32_bf16 v[94:97], v[152:155], v[234:237], v[94:97]
	v_mfma_f32_16x16x32_bf16 v[90:93], v[178:181], v[234:237], v[90:93]
	v_mfma_f32_16x16x32_bf16 v[78:81], v[152:155], v[242:245], v[78:81]
	v_mfma_f32_16x16x32_bf16 v[74:77], v[178:181], v[242:245], v[74:77]
	v_mfma_f32_16x16x32_bf16 v[118:121], v[182:185], v[214:217], v[118:121]
	v_mfma_f32_16x16x32_bf16 v[114:117], v[190:193], v[214:217], v[114:117]
	v_mfma_f32_16x16x32_bf16 v[102:105], v[182:185], v[222:225], v[102:105]
	v_mfma_f32_16x16x32_bf16 v[98:101], v[190:193], v[222:225], v[98:101]
	v_mfma_f32_16x16x32_bf16 v[86:89], v[182:185], v[230:233], v[86:89]
	v_mfma_f32_16x16x32_bf16 v[82:85], v[190:193], v[230:233], v[82:85]
	v_mfma_f32_16x16x32_bf16 v[70:73], v[182:185], v[238:241], v[70:73]
	v_mfma_f32_16x16x32_bf16 v[66:69], v[190:193], v[238:241], v[66:69]
	v_mfma_f32_16x16x32_bf16 v[118:121], v[186:189], v[218:221], v[118:121]
	v_mfma_f32_16x16x32_bf16 v[114:117], v[210:213], v[218:221], v[114:117]
	v_mfma_f32_16x16x32_bf16 v[102:105], v[186:189], v[226:229], v[102:105]
	v_mfma_f32_16x16x32_bf16 v[98:101], v[210:213], v[226:229], v[98:101]
	v_mfma_f32_16x16x32_bf16 v[86:89], v[186:189], v[234:237], v[86:89]
	v_mfma_f32_16x16x32_bf16 v[82:85], v[210:213], v[234:237], v[82:85]
	v_mfma_f32_16x16x32_bf16 v[70:73], v[186:189], v[242:245], v[70:73]
	v_mfma_f32_16x16x32_bf16 v[66:69], v[210:213], v[242:245], v[66:69]
	s_setprio 0
	s_barrier
	s_add_i32 s24, s26, s41
	v_lshl_add_u64 v[160:161], s[36:37], 0, v[132:133]
	s_mov_b32 m0, s24
	ds_read_b128 v[214:217], v150 offset:16384
	ds_read_b128 v[218:221], v150 offset:17408
	ds_read_b128 v[222:225], v150 offset:18432
	ds_read_b128 v[226:229], v150 offset:19456
	ds_read_b128 v[230:233], v150 offset:20480
	ds_read_b128 v[234:237], v150 offset:21504
	ds_read_b128 v[238:241], v150 offset:22528
	ds_read_b128 v[242:245], v150 offset:23552
	global_load_lds_dwordx4 v[160:161], off
	s_add_i32 m0, s24, 0x2000
	s_add_u32 s24, s36, 0x80000
	v_lshl_add_u64 v[168:169], s[36:37], 0, v[136:137]
	s_addc_u32 s25, s37, 0
	s_add_i32 s26, s27, s41
	global_load_lds_dwordx4 v[168:169], off
	v_lshl_add_u64 v[170:171], s[24:25], 0, v[132:133]
	s_mov_b32 m0, s26
	v_lshl_add_u64 v[172:173], s[38:39], 0, v[134:135]
	global_load_lds_dwordx4 v[170:171], off
	v_lshl_add_u64 v[170:171], s[24:25], 0, v[136:137]
	s_add_i32 m0, s26, 0x2000
	s_nop 0
	global_load_lds_dwordx4 v[170:171], off
	v_lshl_add_u64 v[170:171], s[38:39], 0, v[130:131]
	s_mov_b32 m0, s42
	s_nop 0
	global_load_lds_dwordx4 v[170:171], off
	s_mov_b32 m0, s43
	s_nop 0
	global_load_lds_dwordx4 v[172:173], off
	s_waitcnt vmcnt(8)
	s_waitcnt lgkmcnt(0)
	s_barrier
; #define PG8_STAGE(bufoff, gbase, voff) do { _Pragma("unroll") for (int _i = 0; _i < 2; ++_i) \
;         __builtin_amdgcn_global_load_lds((const unsigned*)((const char*)(gbase) + (voff)[_i]), (PG8_LAS unsigned*)(lds + (bufoff) + ldsw + _i * 8192), 16, 0, 0); } while (0)
; #define PG8_LDA(dst, b, h) do { _Pragma("unroll") for (int m = 0; m < 4; ++m) _Pragma("unroll") for (int k = 0; k < 2; ++k) dst[m][k] = *(const PG8_LAS bf16x8*)(lds + PG8_SA(b, h) + aoff + m * 2048 + k * 1024); } while (0)
; #define PG8_LDB(dst, b, h) do { _Pragma("unroll") for (int n = 0; n < 2; ++n) _Pragma("unroll") for (int k = 0; k < 2; ++k) dst[n][k] = *(const PG8_LAS bf16x8*)(lds + PG8_SB(b, h) + boff + n * 2048 + k * 1024); } while (0)
; #define PG8_MMA(ai, bj, At, Bt) do { __builtin_amdgcn_s_setprio(1); _Pragma("unroll") for (int m = 0; m < 4; ++m) _Pragma("unroll") for (int n = 0; n < 2; ++n) _Pragma("unroll") for (int k = 0; k < 2; ++k) \
;         acc[ai][bj][m][n] = __builtin_amdgcn_mfma_f32_16x16x32_bf16(Bt[n][k], At[m][k], acc[ai][bj][m][n], 0, 0, 0); __builtin_amdgcn_s_setprio(0); } while (0)
; #define PG8_WAIT_V(n) asm volatile("s_waitcnt vmcnt(" #n ")" ::: "memory")
; #define PG8_WAIT_L(n) asm volatile("s_waitcnt lgkmcnt(" #n ")" ::: "memory")
; #define PG8_BAR __builtin_amdgcn_s_barrier()
; #define PG8_SCHED __builtin_amdgcn_sched_barrier(0)
; template <class Epi, class Sched, bool ALIGN_EPI = false, bool SP2 = false>
; __device__ __forceinline__ void gemm_phase(PG8_LAS unsigned char* lds, const Gemm g, const Sched& S, const Epi& E) {
;     ...
;             PG8_WAIT_V(8); PG8_WAIT_L(0); PG8_BAR; PG8_MMA(1, 0, At, B0); PG8_MMA(1, 1, At, B1); PG8_BAR; PG8_SCHED;
;             PG8_LDB(B0, 1, 0); PG8_LDB(B1, 1, 1); PG8_SCHED; PG8_LDA(At, 1, 0); PG8_STAGE(PG8_SA(0, 1), a2 + hstepA, voffA);
;             PG8_WAIT_V(8); PG8_WAIT_L(0); PG8_BAR; PG8_MMA(0, 0, At, B0); PG8_MMA(0, 1, At, B1); PG8_BAR; PG8_SCHED;
	s_setprio 1
	s_waitcnt lgkmcnt(0)
	v_mfma_f32_16x16x32_bf16 v[62:65], v[144:147], v[214:217], v[62:65]
	v_mfma_f32_16x16x32_bf16 v[58:61], v[156:159], v[214:217], v[58:61]
	v_mfma_f32_16x16x32_bf16 v[46:49], v[144:147], v[222:225], v[46:49]
	v_mfma_f32_16x16x32_bf16 v[42:45], v[156:159], v[222:225], v[42:45]
	v_mfma_f32_16x16x32_bf16 v[30:33], v[144:147], v[230:233], v[30:33]
	v_mfma_f32_16x16x32_bf16 v[26:29], v[156:159], v[230:233], v[26:29]
	v_mfma_f32_16x16x32_bf16 v[14:17], v[144:147], v[238:241], v[14:17]
	v_mfma_f32_16x16x32_bf16 v[10:13], v[156:159], v[238:241], v[10:13]
	v_mfma_f32_16x16x32_bf16 v[62:65], v[152:155], v[218:221], v[62:65]
	v_mfma_f32_16x16x32_bf16 v[58:61], v[178:181], v[218:221], v[58:61]
	v_mfma_f32_16x16x32_bf16 v[46:49], v[152:155], v[226:229], v[46:49]
	v_mfma_f32_16x16x32_bf16 v[42:45], v[178:181], v[226:229], v[42:45]
	v_mfma_f32_16x16x32_bf16 v[30:33], v[152:155], v[234:237], v[30:33]
	v_mfma_f32_16x16x32_bf16 v[26:29], v[178:181], v[234:237], v[26:29]
	v_mfma_f32_16x16x32_bf16 v[14:17], v[152:155], v[242:245], v[14:17]
	v_mfma_f32_16x16x32_bf16 v[10:13], v[178:181], v[242:245], v[10:13]
	v_mfma_f32_16x16x32_bf16 v[54:57], v[182:185], v[214:217], v[54:57]
	v_mfma_f32_16x16x32_bf16 v[50:53], v[190:193], v[214:217], v[50:53]
	v_mfma_f32_16x16x32_bf16 v[38:41], v[182:185], v[222:225], v[38:41]
	v_mfma_f32_16x16x32_bf16 v[34:37], v[190:193], v[222:225], v[34:37]
	v_mfma_f32_16x16x32_bf16 v[22:25], v[182:185], v[230:233], v[22:25]
	v_mfma_f32_16x16x32_bf16 v[18:21], v[190:193], v[230:233], v[18:21]
	v_mfma_f32_16x16x32_bf16 v[6:9], v[182:185], v[238:241], v[6:9]
	v_mfma_f32_16x16x32_bf16 v[2:5], v[190:193], v[238:241], v[2:5]
	v_mfma_f32_16x16x32_bf16 v[54:57], v[186:189], v[218:221], v[54:57]
	v_mfma_f32_16x16x32_bf16 v[50:53], v[210:213], v[218:221], v[50:53]
	v_mfma_f32_16x16x32_bf16 v[38:41], v[186:189], v[226:229], v[38:41]
	v_mfma_f32_16x16x32_bf16 v[34:37], v[210:213], v[226:229], v[34:37]
	v_mfma_f32_16x16x32_bf16 v[22:25], v[186:189], v[234:237], v[22:25]
	v_mfma_f32_16x16x32_bf16 v[18:21], v[210:213], v[234:237], v[18:21]
	v_mfma_f32_16x16x32_bf16 v[6:9], v[186:189], v[242:245], v[6:9]
	v_mfma_f32_16x16x32_bf16 v[2:5], v[210:213], v[242:245], v[2:5]
	s_setprio 0
	s_barrier
	s_add_i32 s26, 0, 0x18000
	v_add_u32_e32 v151, s26, v148
	s_add_i32 s27, 0, 0x1c000
	ds_read_b128 v[144:147], v151
	ds_read_b128 v[152:155], v151 offset:1024
	ds_read_b128 v[156:159], v151 offset:2048
	ds_read_b128 v[178:181], v151 offset:3072
	v_add_u32_e32 v151, s27, v148
	ds_read_b128 v[182:185], v151
	ds_read_b128 v[186:189], v151 offset:1024
	ds_read_b128 v[190:193], v151 offset:2048
	ds_read_b128 v[210:213], v151 offset:3072
	s_add_u32 s24, s38, 0x80000
	s_addc_u32 s25, s39, 0
	s_mov_b32 m0, s44
	v_lshl_add_u64 v[194:195], s[24:25], 0, v[130:131]
	ds_read_b128 v[214:217], v150 offset:32768
	ds_read_b128 v[218:221], v150 offset:33792
	ds_read_b128 v[222:225], v150 offset:34816
	ds_read_b128 v[226:229], v150 offset:35840
	ds_read_b128 v[230:233], v150 offset:36864
	ds_read_b128 v[234:237], v150 offset:37888
	ds_read_b128 v[238:241], v150 offset:38912
	ds_read_b128 v[242:245], v150 offset:39936
	global_load_lds_dwordx4 v[194:195], off
	v_lshl_add_u64 v[194:195], s[24:25], 0, v[134:135]
	s_mov_b32 m0, s45
	s_nop 0
	global_load_lds_dwordx4 v[194:195], off
	s_waitcnt vmcnt(8)
	s_waitcnt lgkmcnt(0)
	s_barrier
	s_setprio 1
	s_waitcnt lgkmcnt(0)
	v_mfma_f32_16x16x32_bf16 v[126:129], v[144:147], v[214:217], v[126:129]
	v_mfma_f32_16x16x32_bf16 v[122:125], v[156:159], v[214:217], v[122:125]
	v_mfma_f32_16x16x32_bf16 v[110:113], v[144:147], v[222:225], v[110:113]
	v_mfma_f32_16x16x32_bf16 v[106:109], v[156:159], v[222:225], v[106:109]
	v_mfma_f32_16x16x32_bf16 v[94:97], v[144:147], v[230:233], v[94:97]
	v_mfma_f32_16x16x32_bf16 v[90:93], v[156:159], v[230:233], v[90:93]
	v_mfma_f32_16x16x32_bf16 v[78:81], v[144:147], v[238:241], v[78:81]
	v_mfma_f32_16x16x32_bf16 v[74:77], v[156:159], v[238:241], v[74:77]
	v_mfma_f32_16x16x32_bf16 v[126:129], v[152:155], v[218:221], v[126:129]
	v_mfma_f32_16x16x32_bf16 v[122:125], v[178:181], v[218:221], v[122:125]
	v_mfma_f32_16x16x32_bf16 v[110:113], v[152:155], v[226:229], v[110:113]
	v_mfma_f32_16x16x32_bf16 v[106:109], v[178:181], v[226:229], v[106:109]
	v_mfma_f32_16x16x32_bf16 v[94:97], v[152:155], v[234:237], v[94:97]
	v_mfma_f32_16x16x32_bf16 v[90:93], v[178:181], v[234:237], v[90:93]
	v_mfma_f32_16x16x32_bf16 v[78:81], v[152:155], v[242:245], v[78:81]
	v_mfma_f32_16x16x32_bf16 v[74:77], v[178:181], v[242:245], v[74:77]
	v_mfma_f32_16x16x32_bf16 v[118:121], v[182:185], v[214:217], v[118:121]
	v_mfma_f32_16x16x32_bf16 v[114:117], v[190:193], v[214:217], v[114:117]
	v_mfma_f32_16x16x32_bf16 v[102:105], v[182:185], v[222:225], v[102:105]
	v_mfma_f32_16x16x32_bf16 v[98:101], v[190:193], v[222:225], v[98:101]
	v_mfma_f32_16x16x32_bf16 v[86:89], v[182:185], v[230:233], v[86:89]
	v_mfma_f32_16x16x32_bf16 v[82:85], v[190:193], v[230:233], v[82:85]
	v_mfma_f32_16x16x32_bf16 v[70:73], v[182:185], v[238:241], v[70:73]
	v_mfma_f32_16x16x32_bf16 v[66:69], v[190:193], v[238:241], v[66:69]
	v_mfma_f32_16x16x32_bf16 v[118:121], v[186:189], v[218:221], v[118:121]
	v_mfma_f32_16x16x32_bf16 v[114:117], v[210:213], v[218:221], v[114:117]
	v_mfma_f32_16x16x32_bf16 v[102:105], v[186:189], v[226:229], v[102:105]
	v_mfma_f32_16x16x32_bf16 v[98:101], v[210:213], v[226:229], v[98:101]
	v_mfma_f32_16x16x32_bf16 v[86:89], v[186:189], v[234:237], v[86:89]
	v_mfma_f32_16x16x32_bf16 v[82:85], v[210:213], v[234:237], v[82:85]
	v_mfma_f32_16x16x32_bf16 v[70:73], v[186:189], v[242:245], v[70:73]
	v_mfma_f32_16x16x32_bf16 v[66:69], v[210:213], v[242:245], v[66:69]
	s_setprio 0
	s_barrier
; #define PG8_STAGE(bufoff, gbase, voff) do { _Pragma("unroll") for (int _i = 0; _i < 2; ++_i) \
;         __builtin_amdgcn_global_load_lds((const unsigned*)((const char*)(gbase) + (voff)[_i]), (PG8_LAS unsigned*)(lds + (bufoff) + ldsw + _i * 8192), 16, 0, 0); } while (0)
; #define PG8_LDA(dst, b, h) do { _Pragma("unroll") for (int m = 0; m < 4; ++m) _Pragma("unroll") for (int k = 0; k < 2; ++k) dst[m][k] = *(const PG8_LAS bf16x8*)(lds + PG8_SA(b, h) + aoff + m * 2048 + k * 1024); } while (0)
; #define PG8_WAIT_V(n) asm volatile("s_waitcnt vmcnt(" #n ")" ::: "memory")
; template <class Epi, class Sched, bool ALIGN_EPI = false, bool SP2 = false>
; __device__ __forceinline__ void gemm_phase(PG8_LAS unsigned char* lds, const Gemm g, const Sched& S, const Epi& E) {
;     ...
;             PG8_LDA(At, 1, 1); PG8_STAGE(PG8_SB(1, 0), b3, voffB); PG8_STAGE(PG8_SB(1, 1), b3 + hstepB, voffB); PG8_STAGE(PG8_SA(1, 0), a3, voffA);
;             PG8_WAIT_V(8); PG8_WAIT_L(0); PG8_BAR; PG8_MMA(1, 0, At, B0); PG8_MMA(1, 1, At, B1); PG8_BAR; PG8_SCHED;
;             } else {
;             PG8_LDB(B0, 0, 0); PG8_SCHED; PG8_LDA(At, 0, 0); PG8_STAGE(PG8_SA(1, 1), a1 + hstepA, voffA);
;             PG8_WAIT_L(8); PG8_BAR; PG8_WAIT_L(0); PG8_MMA(0, 0, At, B0); PG8_BAR; PG8_SCHED;
;             PG8_LDB(B1, 0, 1); PG8_STAGE(PG8_SB(0, 0), b2, voffB);
;             PG8_BAR; PG8_WAIT_L(0); PG8_MMA(0, 1, At, B1); PG8_BAR;
;             PG8_LDA(At, 0, 1); PG8_STAGE(PG8_SA(0, 0), a2, voffA);
;             PG8_BAR; PG8_WAIT_L(0); PG8_MMA(1, 0, At, B0); PG8_BAR; PG8_SCHED;
;             PG8_STAGE(PG8_SB(0, 1), b2 + hstepB, voffB);
;             PG8_WAIT_V(6); PG8_BAR; PG8_MMA(1, 1, At, B1); PG8_BAR;
;             PG8_LDB(B0, 1, 0); PG8_SCHED; PG8_LDA(At, 1, 0); PG8_STAGE(PG8_SA(0, 1), a2 + hstepA, voffA);
;             PG8_WAIT_L(8); PG8_BAR; PG8_WAIT_L(0); PG8_MMA(0, 0, At, B0); PG8_BAR; PG8_SCHED;
;             PG8_LDB(B1, 1, 1); PG8_STAGE(PG8_SB(1, 0), b3, voffB);
;             PG8_BAR; PG8_WAIT_L(0); PG8_MMA(0, 1, At, B1); PG8_BAR;
;             PG8_LDA(At, 1, 1); PG8_STAGE(PG8_SA(1, 0), a3, voffA);
;             PG8_BAR; PG8_WAIT_L(0); PG8_MMA(1, 0, At, B0); PG8_BAR; PG8_SCHED;
;             PG8_STAGE(PG8_SB(1, 1), b3 + hstepB, voffB);
;             PG8_WAIT_V(6); PG8_BAR; PG8_MMA(1, 1, At, B1); PG8_BAR;
;             }
;         }
;         if constexpr (ALIGN_EPI) { if (wr == 0) PG8_BAR; }
	s_add_i32 s24, s26, s41
	v_lshl_add_u64 v[160:161], v[160:161], 0, s[50:51]
	s_mov_b32 m0, s24
	ds_read_b128 v[214:217], v150 offset:49152
	ds_read_b128 v[218:221], v150 offset:50176
	ds_read_b128 v[222:225], v150 offset:51200
	ds_read_b128 v[226:229], v150 offset:52224
	ds_read_b128 v[230:233], v150 offset:53248
	ds_read_b128 v[234:237], v150 offset:54272
	ds_read_b128 v[238:241], v150 offset:55296
	ds_read_b128 v[242:245], v150 offset:56320
	global_load_lds_dwordx4 v[160:161], off
	s_add_i32 m0, s24, 0x2000
	s_add_u32 s24, s36, 0x80080
	v_lshl_add_u64 v[160:161], v[168:169], 0, s[50:51]
	s_addc_u32 s25, s37, 0
	s_add_i32 s26, s27, s41
	global_load_lds_dwordx4 v[160:161], off
	v_lshl_add_u64 v[160:161], s[24:25], 0, v[132:133]
	s_mov_b32 m0, s26
	s_nop 0
	global_load_lds_dwordx4 v[160:161], off
	v_lshl_add_u64 v[160:161], s[24:25], 0, v[136:137]
	s_add_i32 m0, s26, 0x2000
	s_nop 0
	global_load_lds_dwordx4 v[160:161], off
	v_lshl_add_u64 v[160:161], v[170:171], 0, s[50:51]
	s_mov_b32 m0, s48
	s_nop 0
	global_load_lds_dwordx4 v[160:161], off
	v_lshl_add_u64 v[160:161], v[172:173], 0, s[50:51]
	s_mov_b32 m0, s49
	s_nop 0
	global_load_lds_dwordx4 v[160:161], off
	s_waitcnt vmcnt(8)
	s_waitcnt lgkmcnt(0)
	s_barrier
	s_setprio 1
	s_waitcnt lgkmcnt(0)
	v_mfma_f32_16x16x32_bf16 v[62:65], v[144:147], v[214:217], v[62:65]
	v_mfma_f32_16x16x32_bf16 v[58:61], v[156:159], v[214:217], v[58:61]
	v_mfma_f32_16x16x32_bf16 v[46:49], v[144:147], v[222:225], v[46:49]
	v_mfma_f32_16x16x32_bf16 v[42:45], v[156:159], v[222:225], v[42:45]
	v_mfma_f32_16x16x32_bf16 v[30:33], v[144:147], v[230:233], v[30:33]
	v_mfma_f32_16x16x32_bf16 v[26:29], v[156:159], v[230:233], v[26:29]
	v_mfma_f32_16x16x32_bf16 v[14:17], v[144:147], v[238:241], v[14:17]
	v_mfma_f32_16x16x32_bf16 v[10:13], v[156:159], v[238:241], v[10:13]
	v_mfma_f32_16x16x32_bf16 v[62:65], v[152:155], v[218:221], v[62:65]
	v_mfma_f32_16x16x32_bf16 v[58:61], v[178:181], v[218:221], v[58:61]
	v_mfma_f32_16x16x32_bf16 v[46:49], v[152:155], v[226:229], v[46:49]
	v_mfma_f32_16x16x32_bf16 v[42:45], v[178:181], v[226:229], v[42:45]
	v_mfma_f32_16x16x32_bf16 v[30:33], v[152:155], v[234:237], v[30:33]
	v_mfma_f32_16x16x32_bf16 v[26:29], v[178:181], v[234:237], v[26:29]
	v_mfma_f32_16x16x32_bf16 v[14:17], v[152:155], v[242:245], v[14:17]
	v_mfma_f32_16x16x32_bf16 v[10:13], v[178:181], v[242:245], v[10:13]
	v_mfma_f32_16x16x32_bf16 v[54:57], v[182:185], v[214:217], v[54:57]
	v_mfma_f32_16x16x32_bf16 v[50:53], v[190:193], v[214:217], v[50:53]
	v_mfma_f32_16x16x32_bf16 v[38:41], v[182:185], v[222:225], v[38:41]
	v_mfma_f32_16x16x32_bf16 v[34:37], v[190:193], v[222:225], v[34:37]
	v_mfma_f32_16x16x32_bf16 v[22:25], v[182:185], v[230:233], v[22:25]
	v_mfma_f32_16x16x32_bf16 v[18:21], v[190:193], v[230:233], v[18:21]
	v_mfma_f32_16x16x32_bf16 v[6:9], v[182:185], v[238:241], v[6:9]
	v_mfma_f32_16x16x32_bf16 v[2:5], v[190:193], v[238:241], v[2:5]
	v_mfma_f32_16x16x32_bf16 v[54:57], v[186:189], v[218:221], v[54:57]
	v_mfma_f32_16x16x32_bf16 v[50:53], v[210:213], v[218:221], v[50:53]
	v_mfma_f32_16x16x32_bf16 v[38:41], v[186:189], v[226:229], v[38:41]
	v_mfma_f32_16x16x32_bf16 v[34:37], v[210:213], v[226:229], v[34:37]
	v_mfma_f32_16x16x32_bf16 v[22:25], v[186:189], v[234:237], v[22:25]
	v_mfma_f32_16x16x32_bf16 v[18:21], v[210:213], v[234:237], v[18:21]
	v_mfma_f32_16x16x32_bf16 v[6:9], v[186:189], v[242:245], v[6:9]
	v_mfma_f32_16x16x32_bf16 v[2:5], v[210:213], v[242:245], v[2:5]
	s_setprio 0
	s_barrier
	s_add_i32 s57, s57, 2
	s_add_u32 s22, s22, 0x100
	s_addc_u32 s23, s23, 0
	s_add_u32 s55, s55, 0x100
	s_addc_u32 s56, s56, 0
	s_cmp_gt_u32 s57, 29
	s_cbranch_scc0 .LBB0_2127
	v_readlane_b32 s76, v250, 46
	s_and_b64 vcc, exec, s[8:9]
	v_readlane_b32 s77, v250, 47
	v_readlane_b32 s80, v250, 50
	v_readlane_b32 s81, v250, 51
	v_readlane_b32 s84, v250, 54
	v_readlane_b32 s85, v250, 55
	v_readlane_b32 s86, v250, 56
	v_readlane_b32 s87, v250, 57
	v_readlane_b32 s88, v250, 58
	v_readlane_b32 s89, v250, 59
	v_readlane_b32 s90, v250, 60
	v_readlane_b32 s91, v250, 61
	v_readlane_b32 s78, v250, 48
	v_readlane_b32 s79, v250, 49
	v_readlane_b32 s82, v250, 52
	v_readlane_b32 s83, v250, 53
	s_cbranch_vccz .LBB0_2130
	s_barrier

; #define PG8_STAGE(bufoff, gbase, voff) do { _Pragma("unroll") for (int _i = 0; _i < 2; ++_i) \
;         __builtin_amdgcn_global_load_lds((const unsigned*)((const char*)(gbase) + (voff)[_i]), (PG8_LAS unsigned*)(lds + (bufoff) + ldsw + _i * 8192), 16, 0, 0); } while (0)
; #define PG8_LDA(dst, b, h) do { _Pragma("unroll") for (int m = 0; m < 4; ++m) _Pragma("unroll") for (int k = 0; k < 2; ++k) dst[m][k] = *(const PG8_LAS bf16x8*)(lds + PG8_SA(b, h) + aoff + m * 2048 + k * 1024); } while (0)
; #define PG8_LDB(dst, b, h) do { _Pragma("unroll") for (int n = 0; n < 2; ++n) _Pragma("unroll") for (int k = 0; k < 2; ++k) dst[n][k] = *(const PG8_LAS bf16x8*)(lds + PG8_SB(b, h) + boff + n * 2048 + k * 1024); } while (0)
; #define PG8_MMA(ai, bj, At, Bt) do { __builtin_amdgcn_s_setprio(1); _Pragma("unroll") for (int m = 0; m < 4; ++m) _Pragma("unroll") for (int n = 0; n < 2; ++n) _Pragma("unroll") for (int k = 0; k < 2; ++k) \
;         acc[ai][bj][m][n] = __builtin_amdgcn_mfma_f32_16x16x32_bf16(Bt[n][k], At[m][k], acc[ai][bj][m][n], 0, 0, 0); __builtin_amdgcn_s_setprio(0); } while (0)
; #define PG8_WAIT_V(n) asm volatile("s_waitcnt vmcnt(" #n ")" ::: "memory")
; #define PG8_WAIT_L(n) asm volatile("s_waitcnt lgkmcnt(" #n ")" ::: "memory")
; #define PG8_BAR __builtin_amdgcn_s_barrier()
; #define PG8_SCHED __builtin_amdgcn_sched_barrier(0)
; template <class Epi, class Sched, bool ALIGN_EPI = false, bool SP2 = false>
; __device__ __forceinline__ void gemm_phase(PG8_LAS unsigned char* lds, const Gemm g, const Sched& S, const Epi& E) {
;     ...
;         for (int t = 0; t < nt; t += 2) {
;             const bool last = (t == nt - 2);
;             const char* a1 = cA + (size_t)(t + 1) * kstep;
;             const char* a2 = last ? nA : cA + (size_t)(t + 2) * kstep; const char* b2 = last ? nB : cB + (size_t)(t + 2) * kstep;
;             const char* a3 = a2 + kstep; const char* b3 = b2 + kstep;
;             if (last && has_next) S.a_ready(nxt);
;             if constexpr (SP2) {
;             PG8_LDB(B0, 0, 0); PG8_LDB(B1, 0, 1); PG8_SCHED; PG8_LDA(At, 0, 0); PG8_STAGE(PG8_SA(1, 1), a1 + hstepA, voffA);
;             PG8_WAIT_V(8); PG8_WAIT_L(0); PG8_BAR; PG8_MMA(0, 0, At, B0); PG8_MMA(0, 1, At, B1); PG8_BAR; PG8_SCHED;
;             PG8_LDA(At, 0, 1); PG8_STAGE(PG8_SB(0, 0), b2, voffB); PG8_STAGE(PG8_SB(0, 1), b2 + hstepB, voffB); PG8_STAGE(PG8_SA(0, 0), a2, voffA);
.LBB0_2340:
	s_add_u32 s8, s6, 0x100
	s_addc_u32 s9, s7, 0
	s_add_i32 s24, 0, 0x10000
	s_cmpk_eq_i32 s55, 0x54
	s_cselect_b32 s13, s5, s9
	s_cselect_b32 s12, s4, s8
	s_cselect_b32 s11, s47, s54
	s_cselect_b32 s10, s46, s37
	s_add_i32 s25, 0, 0x14000
	v_add_u32_e32 v46, s24, v188
	v_add_u32_e32 v62, s25, v188
	ds_read_b128 v[34:37], v46
	ds_read_b128 v[38:41], v46 offset:1024
	ds_read_b128 v[42:45], v46 offset:2048
	ds_read_b128 v[46:49], v46 offset:3072
	ds_read_b128 v[50:53], v62
	ds_read_b128 v[54:57], v62 offset:1024
	ds_read_b128 v[58:61], v62 offset:2048
	ds_read_b128 v[62:65], v62 offset:3072
	v_lshl_add_u64 v[168:169], s[6:7], 0, v[180:181]
	s_add_i32 m0, s15, 0xc000
	ds_read_b128 v[184:187], v190
	ds_read_b128 v[192:195], v190 offset:1024
	ds_read_b128 v[210:213], v190 offset:2048
	ds_read_b128 v[214:217], v190 offset:3072
	ds_read_b128 v[218:221], v190 offset:4096
	ds_read_b128 v[222:225], v190 offset:5120
	ds_read_b128 v[226:229], v190 offset:6144
	ds_read_b128 v[230:233], v190 offset:7168
	global_load_lds_dwordx4 v[168:169], off
	v_lshl_add_u64 v[168:169], s[6:7], 0, v[182:183]
	s_add_i32 m0, s15, 0xe000
	s_nop 0
	global_load_lds_dwordx4 v[168:169], off
	s_waitcnt vmcnt(8)
	s_waitcnt lgkmcnt(0)
	s_barrier
	s_setprio 1
	s_waitcnt lgkmcnt(0)
	v_mfma_f32_16x16x32_bf16 v[158:161], v[34:37], v[184:187], v[158:161]
	v_mfma_f32_16x16x32_bf16 v[154:157], v[42:45], v[184:187], v[154:157]
	v_mfma_f32_16x16x32_bf16 v[142:145], v[34:37], v[210:213], v[142:145]
	v_mfma_f32_16x16x32_bf16 v[138:141], v[42:45], v[210:213], v[138:141]
	v_mfma_f32_16x16x32_bf16 v[126:129], v[34:37], v[218:221], v[126:129]
	v_mfma_f32_16x16x32_bf16 v[122:125], v[42:45], v[218:221], v[122:125]
	v_mfma_f32_16x16x32_bf16 v[110:113], v[34:37], v[226:229], v[110:113]
	v_mfma_f32_16x16x32_bf16 v[106:109], v[42:45], v[226:229], v[106:109]
	v_mfma_f32_16x16x32_bf16 v[158:161], v[38:41], v[192:195], v[158:161]
	v_mfma_f32_16x16x32_bf16 v[154:157], v[46:49], v[192:195], v[154:157]
	v_mfma_f32_16x16x32_bf16 v[142:145], v[38:41], v[214:217], v[142:145]
	v_mfma_f32_16x16x32_bf16 v[138:141], v[46:49], v[214:217], v[138:141]
	v_mfma_f32_16x16x32_bf16 v[126:129], v[38:41], v[222:225], v[126:129]
	v_mfma_f32_16x16x32_bf16 v[122:125], v[46:49], v[222:225], v[122:125]
	v_mfma_f32_16x16x32_bf16 v[110:113], v[38:41], v[230:233], v[110:113]
	v_mfma_f32_16x16x32_bf16 v[106:109], v[46:49], v[230:233], v[106:109]
	v_mfma_f32_16x16x32_bf16 v[150:153], v[50:53], v[184:187], v[150:153]
	v_mfma_f32_16x16x32_bf16 v[146:149], v[58:61], v[184:187], v[146:149]
	v_mfma_f32_16x16x32_bf16 v[134:137], v[50:53], v[210:213], v[134:137]
	v_mfma_f32_16x16x32_bf16 v[130:133], v[58:61], v[210:213], v[130:133]
	v_mfma_f32_16x16x32_bf16 v[118:121], v[50:53], v[218:221], v[118:121]
	v_mfma_f32_16x16x32_bf16 v[114:117], v[58:61], v[218:221], v[114:117]
	v_mfma_f32_16x16x32_bf16 v[102:105], v[50:53], v[226:229], v[102:105]
	v_mfma_f32_16x16x32_bf16 v[98:101], v[58:61], v[226:229], v[98:101]
	v_mfma_f32_16x16x32_bf16 v[150:153], v[54:57], v[192:195], v[150:153]
	v_mfma_f32_16x16x32_bf16 v[146:149], v[62:65], v[192:195], v[146:149]
	v_mfma_f32_16x16x32_bf16 v[134:137], v[54:57], v[214:217], v[134:137]
	v_mfma_f32_16x16x32_bf16 v[130:133], v[62:65], v[214:217], v[130:133]
	v_mfma_f32_16x16x32_bf16 v[118:121], v[54:57], v[222:225], v[118:121]
	v_mfma_f32_16x16x32_bf16 v[114:117], v[62:65], v[222:225], v[114:117]
	v_mfma_f32_16x16x32_bf16 v[102:105], v[54:57], v[230:233], v[102:105]
	v_mfma_f32_16x16x32_bf16 v[98:101], v[62:65], v[230:233], v[98:101]
	s_setprio 0
	s_barrier
	s_add_i32 s6, s24, s14
	v_lshl_add_u64 v[168:169], s[10:11], 0, v[162:163]
	s_mov_b32 m0, s6
	ds_read_b128 v[184:187], v190 offset:16384
	ds_read_b128 v[192:195], v190 offset:17408
	ds_read_b128 v[210:213], v190 offset:18432
	ds_read_b128 v[214:217], v190 offset:19456
	ds_read_b128 v[218:221], v190 offset:20480
	ds_read_b128 v[222:225], v190 offset:21504
	ds_read_b128 v[226:229], v190 offset:22528
	ds_read_b128 v[230:233], v190 offset:23552
	global_load_lds_dwordx4 v[168:169], off
	s_add_i32 m0, s6, 0x2000
	s_add_u32 s6, s10, 0x160000
	v_lshl_add_u64 v[170:171], s[10:11], 0, v[178:179]
	s_addc_u32 s7, s11, 0
	s_add_i32 s24, s25, s14
	global_load_lds_dwordx4 v[170:171], off
	v_lshl_add_u64 v[172:173], s[6:7], 0, v[162:163]
	s_mov_b32 m0, s24
	v_lshl_add_u64 v[242:243], s[12:13], 0, v[178:179]
	global_load_lds_dwordx4 v[172:173], off
	v_lshl_add_u64 v[172:173], s[6:7], 0, v[178:179]
	s_add_i32 m0, s24, 0x2000
	s_nop 0
	global_load_lds_dwordx4 v[172:173], off
	v_lshl_add_u64 v[172:173], s[12:13], 0, v[162:163]
	s_mov_b32 m0, s15
	s_nop 0
	global_load_lds_dwordx4 v[172:173], off
	s_mov_b32 m0, s16
	s_nop 0
	global_load_lds_dwordx4 v[242:243], off
	s_waitcnt vmcnt(8)
	s_waitcnt lgkmcnt(0)
	s_barrier
; #define PG8_STAGE(bufoff, gbase, voff) do { _Pragma("unroll") for (int _i = 0; _i < 2; ++_i) \
;         __builtin_amdgcn_global_load_lds((const unsigned*)((const char*)(gbase) + (voff)[_i]), (PG8_LAS unsigned*)(lds + (bufoff) + ldsw + _i * 8192), 16, 0, 0); } while (0)
; #define PG8_LDA(dst, b, h) do { _Pragma("unroll") for (int m = 0; m < 4; ++m) _Pragma("unroll") for (int k = 0; k < 2; ++k) dst[m][k] = *(const PG8_LAS bf16x8*)(lds + PG8_SA(b, h) + aoff + m * 2048 + k * 1024); } while (0)
; #define PG8_LDB(dst, b, h) do { _Pragma("unroll") for (int n = 0; n < 2; ++n) _Pragma("unroll") for (int k = 0; k < 2; ++k) dst[n][k] = *(const PG8_LAS bf16x8*)(lds + PG8_SB(b, h) + boff + n * 2048 + k * 1024); } while (0)
; #define PG8_MMA(ai, bj, At, Bt) do { __builtin_amdgcn_s_setprio(1); _Pragma("unroll") for (int m = 0; m < 4; ++m) _Pragma("unroll") for (int n = 0; n < 2; ++n) _Pragma("unroll") for (int k = 0; k < 2; ++k) \
;         acc[ai][bj][m][n] = __builtin_amdgcn_mfma_f32_16x16x32_bf16(Bt[n][k], At[m][k], acc[ai][bj][m][n], 0, 0, 0); __builtin_amdgcn_s_setprio(0); } while (0)
; #define PG8_WAIT_V(n) asm volatile("s_waitcnt vmcnt(" #n ")" ::: "memory")
; #define PG8_WAIT_L(n) asm volatile("s_waitcnt lgkmcnt(" #n ")" ::: "memory")
; #define PG8_BAR __builtin_amdgcn_s_barrier()
; #define PG8_SCHED __builtin_amdgcn_sched_barrier(0)
; template <class Epi, class Sched, bool ALIGN_EPI = false, bool SP2 = false>
; __device__ __forceinline__ void gemm_phase(PG8_LAS unsigned char* lds, const Gemm g, const Sched& S, const Epi& E) {
;     ...
;             PG8_WAIT_V(8); PG8_WAIT_L(0); PG8_BAR; PG8_MMA(1, 0, At, B0); PG8_MMA(1, 1, At, B1); PG8_BAR; PG8_SCHED;
;             PG8_LDB(B0, 1, 0); PG8_LDB(B1, 1, 1); PG8_SCHED; PG8_LDA(At, 1, 0); PG8_STAGE(PG8_SA(0, 1), a2 + hstepA, voffA);
;             PG8_WAIT_V(8); PG8_WAIT_L(0); PG8_BAR; PG8_MMA(0, 0, At, B0); PG8_MMA(0, 1, At, B1); PG8_BAR; PG8_SCHED;
	s_setprio 1
	s_waitcnt lgkmcnt(0)
	v_mfma_f32_16x16x32_bf16 v[94:97], v[34:37], v[184:187], v[94:97]
	v_mfma_f32_16x16x32_bf16 v[90:93], v[42:45], v[184:187], v[90:93]
	v_mfma_f32_16x16x32_bf16 v[78:81], v[34:37], v[210:213], v[78:81]
	v_mfma_f32_16x16x32_bf16 v[74:77], v[42:45], v[210:213], v[74:77]
	v_mfma_f32_16x16x32_bf16 v[30:33], v[34:37], v[218:221], v[30:33]
	v_mfma_f32_16x16x32_bf16 v[26:29], v[42:45], v[218:221], v[26:29]
	v_mfma_f32_16x16x32_bf16 v[14:17], v[34:37], v[226:229], v[14:17]
	v_mfma_f32_16x16x32_bf16 v[10:13], v[42:45], v[226:229], v[10:13]
	v_mfma_f32_16x16x32_bf16 v[94:97], v[38:41], v[192:195], v[94:97]
	v_mfma_f32_16x16x32_bf16 v[90:93], v[46:49], v[192:195], v[90:93]
	v_mfma_f32_16x16x32_bf16 v[78:81], v[38:41], v[214:217], v[78:81]
	v_mfma_f32_16x16x32_bf16 v[74:77], v[46:49], v[214:217], v[74:77]
	v_mfma_f32_16x16x32_bf16 v[30:33], v[38:41], v[222:225], v[30:33]
	v_mfma_f32_16x16x32_bf16 v[26:29], v[46:49], v[222:225], v[26:29]
	v_mfma_f32_16x16x32_bf16 v[14:17], v[38:41], v[230:233], v[14:17]
	v_mfma_f32_16x16x32_bf16 v[10:13], v[46:49], v[230:233], v[10:13]
	v_mfma_f32_16x16x32_bf16 v[22:25], v[50:53], v[218:221], v[22:25]
	v_mfma_f32_16x16x32_bf16 v[18:21], v[58:61], v[218:221], v[18:21]
	v_mfma_f32_16x16x32_bf16 v[6:9], v[50:53], v[226:229], v[6:9]
	v_mfma_f32_16x16x32_bf16 v[2:5], v[58:61], v[226:229], v[2:5]
	v_mfma_f32_16x16x32_bf16 v[34:37], v[50:53], v[184:187], v[86:89]
	v_mfma_f32_16x16x32_bf16 v[38:41], v[58:61], v[184:187], v[82:85]
	v_mfma_f32_16x16x32_bf16 v[42:45], v[50:53], v[210:213], v[70:73]
	v_mfma_f32_16x16x32_bf16 v[46:49], v[58:61], v[210:213], v[66:69]
	v_mfma_f32_16x16x32_bf16 v[22:25], v[54:57], v[222:225], v[22:25]
	v_mfma_f32_16x16x32_bf16 v[18:21], v[62:65], v[222:225], v[18:21]
	v_mfma_f32_16x16x32_bf16 v[6:9], v[54:57], v[230:233], v[6:9]
	v_mfma_f32_16x16x32_bf16 v[2:5], v[62:65], v[230:233], v[2:5]
	v_mfma_f32_16x16x32_bf16 v[34:37], v[54:57], v[192:195], v[34:37]
	v_mfma_f32_16x16x32_bf16 v[38:41], v[62:65], v[192:195], v[38:41]
	v_mfma_f32_16x16x32_bf16 v[42:45], v[54:57], v[214:217], v[42:45]
	v_mfma_f32_16x16x32_bf16 v[46:49], v[62:65], v[214:217], v[46:49]
	s_setprio 0
	s_barrier
	s_add_i32 s24, 0, 0x18000
	s_add_i32 s25, 0, 0x1c000
	v_add_u32_e32 v62, s24, v188
	v_add_u32_e32 v66, s25, v188
	ds_read_b128 v[50:53], v62
	ds_read_b128 v[54:57], v62 offset:1024
	ds_read_b128 v[58:61], v62 offset:2048
	ds_read_b128 v[62:65], v62 offset:3072
	ds_read_b128 v[184:187], v66
	ds_read_b128 v[192:195], v66 offset:1024
	ds_read_b128 v[210:213], v66 offset:2048
	ds_read_b128 v[214:217], v66 offset:3072
	s_add_u32 s6, s12, 0x160000
	s_addc_u32 s7, s13, 0
	s_mov_b32 m0, s17
	v_lshl_add_u64 v[234:235], s[6:7], 0, v[162:163]
	ds_read_b128 v[66:69], v190 offset:32768
	ds_read_b128 v[70:73], v190 offset:33792
	ds_read_b128 v[82:85], v190 offset:34816
	ds_read_b128 v[86:89], v190 offset:35840
	ds_read_b128 v[218:221], v190 offset:36864
	ds_read_b128 v[222:225], v190 offset:37888
	ds_read_b128 v[226:229], v190 offset:38912
	ds_read_b128 v[230:233], v190 offset:39936
	global_load_lds_dwordx4 v[234:235], off
	v_lshl_add_u64 v[234:235], s[6:7], 0, v[178:179]
	s_mov_b32 m0, s18
	s_nop 0
	global_load_lds_dwordx4 v[234:235], off
	s_waitcnt vmcnt(8)
	s_waitcnt lgkmcnt(0)
	s_barrier
	s_setprio 1
	s_waitcnt lgkmcnt(0)
	v_mfma_f32_16x16x32_bf16 v[158:161], v[50:53], v[66:69], v[158:161]
	v_mfma_f32_16x16x32_bf16 v[154:157], v[58:61], v[66:69], v[154:157]
	v_mfma_f32_16x16x32_bf16 v[142:145], v[50:53], v[82:85], v[142:145]
	v_mfma_f32_16x16x32_bf16 v[138:141], v[58:61], v[82:85], v[138:141]
	v_mfma_f32_16x16x32_bf16 v[126:129], v[50:53], v[218:221], v[126:129]
	v_mfma_f32_16x16x32_bf16 v[122:125], v[58:61], v[218:221], v[122:125]
	v_mfma_f32_16x16x32_bf16 v[110:113], v[50:53], v[226:229], v[110:113]
	v_mfma_f32_16x16x32_bf16 v[106:109], v[58:61], v[226:229], v[106:109]
	v_mfma_f32_16x16x32_bf16 v[158:161], v[54:57], v[70:73], v[158:161]
	v_mfma_f32_16x16x32_bf16 v[154:157], v[62:65], v[70:73], v[154:157]
	v_mfma_f32_16x16x32_bf16 v[142:145], v[54:57], v[86:89], v[142:145]
	v_mfma_f32_16x16x32_bf16 v[138:141], v[62:65], v[86:89], v[138:141]
	v_mfma_f32_16x16x32_bf16 v[126:129], v[54:57], v[222:225], v[126:129]
	v_mfma_f32_16x16x32_bf16 v[122:125], v[62:65], v[222:225], v[122:125]
	v_mfma_f32_16x16x32_bf16 v[110:113], v[54:57], v[230:233], v[110:113]
	v_mfma_f32_16x16x32_bf16 v[106:109], v[62:65], v[230:233], v[106:109]
	v_mfma_f32_16x16x32_bf16 v[150:153], v[184:187], v[66:69], v[150:153]
	v_mfma_f32_16x16x32_bf16 v[66:69], v[210:213], v[66:69], v[146:149]
	v_mfma_f32_16x16x32_bf16 v[146:149], v[214:217], v[70:73], v[66:69]
	v_mfma_f32_16x16x32_bf16 v[66:69], v[184:187], v[82:85], v[134:137]
	v_mfma_f32_16x16x32_bf16 v[134:137], v[192:195], v[86:89], v[66:69]
	v_mfma_f32_16x16x32_bf16 v[66:69], v[210:213], v[82:85], v[130:133]
	v_mfma_f32_16x16x32_bf16 v[130:133], v[214:217], v[86:89], v[66:69]
	v_mfma_f32_16x16x32_bf16 v[66:69], v[184:187], v[218:221], v[118:121]
	v_mfma_f32_16x16x32_bf16 v[118:121], v[192:195], v[222:225], v[66:69]
	v_mfma_f32_16x16x32_bf16 v[66:69], v[210:213], v[218:221], v[114:117]
	v_mfma_f32_16x16x32_bf16 v[114:117], v[214:217], v[222:225], v[66:69]
	v_mfma_f32_16x16x32_bf16 v[66:69], v[184:187], v[226:229], v[102:105]
	v_mfma_f32_16x16x32_bf16 v[102:105], v[192:195], v[230:233], v[66:69]
	v_mfma_f32_16x16x32_bf16 v[66:69], v[210:213], v[226:229], v[98:101]
	v_mfma_f32_16x16x32_bf16 v[150:153], v[192:195], v[70:73], v[150:153]
	v_mfma_f32_16x16x32_bf16 v[98:101], v[214:217], v[230:233], v[66:69]
	s_setprio 0
	s_barrier
; #define PG8_STAGE(bufoff, gbase, voff) do { _Pragma("unroll") for (int _i = 0; _i < 2; ++_i) \
;         __builtin_amdgcn_global_load_lds((const unsigned*)((const char*)(gbase) + (voff)[_i]), (PG8_LAS unsigned*)(lds + (bufoff) + ldsw + _i * 8192), 16, 0, 0); } while (0)
; #define PG8_LDA(dst, b, h) do { _Pragma("unroll") for (int m = 0; m < 4; ++m) _Pragma("unroll") for (int k = 0; k < 2; ++k) dst[m][k] = *(const PG8_LAS bf16x8*)(lds + PG8_SA(b, h) + aoff + m * 2048 + k * 1024); } while (0)
; #define PG8_MMA(ai, bj, At, Bt) do { __builtin_amdgcn_s_setprio(1); _Pragma("unroll") for (int m = 0; m < 4; ++m) _Pragma("unroll") for (int n = 0; n < 2; ++n) _Pragma("unroll") for (int k = 0; k < 2; ++k) \
;         acc[ai][bj][m][n] = __builtin_amdgcn_mfma_f32_16x16x32_bf16(Bt[n][k], At[m][k], acc[ai][bj][m][n], 0, 0, 0); __builtin_amdgcn_s_setprio(0); } while (0)
; #define PG8_WAIT_V(n) asm volatile("s_waitcnt vmcnt(" #n ")" ::: "memory")
; #define PG8_WAIT_L(n) asm volatile("s_waitcnt lgkmcnt(" #n ")" ::: "memory")
; #define PG8_BAR __builtin_amdgcn_s_barrier()
; #define PG8_SCHED __builtin_amdgcn_sched_barrier(0)
; template <class Epi, class Sched, bool ALIGN_EPI = false, bool SP2 = false>
; __device__ __forceinline__ void gemm_phase(PG8_LAS unsigned char* lds, const Gemm g, const Sched& S, const Epi& E) {
;     ...
;         for (int t = 0; t < nt; t += 2) {
;     ...
;             PG8_LDA(At, 1, 1); PG8_STAGE(PG8_SB(1, 0), b3, voffB); PG8_STAGE(PG8_SB(1, 1), b3 + hstepB, voffB); PG8_STAGE(PG8_SA(1, 0), a3, voffA);
;             PG8_WAIT_V(8); PG8_WAIT_L(0); PG8_BAR; PG8_MMA(1, 0, At, B0); PG8_MMA(1, 1, At, B1); PG8_BAR; PG8_SCHED;
	s_add_i32 s6, s24, s14
	v_lshl_add_u64 v[82:83], v[168:169], 0, s[50:51]
	s_mov_b32 m0, s6
	s_nop 0
	ds_read_b128 v[66:69], v190 offset:49152
	ds_read_b128 v[70:73], v190 offset:50176
	ds_read_b128 v[218:221], v190 offset:51200
	ds_read_b128 v[222:225], v190 offset:52224
	ds_read_b128 v[226:229], v190 offset:53248
	ds_read_b128 v[230:233], v190 offset:54272
	ds_read_b128 v[234:237], v190 offset:55296
	ds_read_b128 v[238:241], v190 offset:56320
	global_load_lds_dwordx4 v[82:83], off
	s_add_i32 m0, s6, 0x2000
	s_add_u32 s6, s10, 0x160080
	v_lshl_add_u64 v[82:83], v[170:171], 0, s[50:51]
	s_addc_u32 s7, s11, 0
	s_add_i32 s10, s25, s14
	global_load_lds_dwordx4 v[82:83], off
	v_lshl_add_u64 v[82:83], s[6:7], 0, v[162:163]
	s_mov_b32 m0, s10
	s_nop 0
	global_load_lds_dwordx4 v[82:83], off
	v_lshl_add_u64 v[82:83], s[6:7], 0, v[178:179]
	s_add_i32 m0, s10, 0x2000
	s_nop 0
	global_load_lds_dwordx4 v[82:83], off
	v_lshl_add_u64 v[82:83], v[172:173], 0, s[50:51]
	s_mov_b32 m0, s19
	s_nop 0
	global_load_lds_dwordx4 v[82:83], off
	v_lshl_add_u64 v[82:83], v[242:243], 0, s[50:51]
	s_mov_b32 m0, s20
	s_nop 0
	global_load_lds_dwordx4 v[82:83], off
	s_waitcnt vmcnt(8)
	s_waitcnt lgkmcnt(0)
	s_barrier
	s_setprio 1
	s_waitcnt lgkmcnt(0)
	v_mfma_f32_16x16x32_bf16 v[82:85], v[50:53], v[66:69], v[94:97]
	v_mfma_f32_16x16x32_bf16 v[94:97], v[54:57], v[70:73], v[82:85]
	v_mfma_f32_16x16x32_bf16 v[82:85], v[58:61], v[66:69], v[90:93]
	v_mfma_f32_16x16x32_bf16 v[78:81], v[50:53], v[218:221], v[78:81]
	v_mfma_f32_16x16x32_bf16 v[74:77], v[58:61], v[218:221], v[74:77]
	v_mfma_f32_16x16x32_bf16 v[30:33], v[50:53], v[226:229], v[30:33]
	v_mfma_f32_16x16x32_bf16 v[26:29], v[58:61], v[226:229], v[26:29]
	v_mfma_f32_16x16x32_bf16 v[14:17], v[50:53], v[234:237], v[14:17]
	v_mfma_f32_16x16x32_bf16 v[10:13], v[58:61], v[234:237], v[10:13]
	v_mfma_f32_16x16x32_bf16 v[90:93], v[62:65], v[70:73], v[82:85]
	v_mfma_f32_16x16x32_bf16 v[78:81], v[54:57], v[222:225], v[78:81]
	v_mfma_f32_16x16x32_bf16 v[74:77], v[62:65], v[222:225], v[74:77]
	v_mfma_f32_16x16x32_bf16 v[30:33], v[54:57], v[230:233], v[30:33]
	v_mfma_f32_16x16x32_bf16 v[26:29], v[62:65], v[230:233], v[26:29]
	v_mfma_f32_16x16x32_bf16 v[14:17], v[54:57], v[238:241], v[14:17]
	v_mfma_f32_16x16x32_bf16 v[10:13], v[62:65], v[238:241], v[10:13]
	v_mfma_f32_16x16x32_bf16 v[34:37], v[184:187], v[66:69], v[34:37]
	v_mfma_f32_16x16x32_bf16 v[86:89], v[192:195], v[70:73], v[34:37]
	v_mfma_f32_16x16x32_bf16 v[34:37], v[210:213], v[66:69], v[38:41]
	v_mfma_f32_16x16x32_bf16 v[82:85], v[214:217], v[70:73], v[34:37]
	v_mfma_f32_16x16x32_bf16 v[34:37], v[184:187], v[218:221], v[42:45]
	v_mfma_f32_16x16x32_bf16 v[70:73], v[192:195], v[222:225], v[34:37]
	v_mfma_f32_16x16x32_bf16 v[34:37], v[210:213], v[218:221], v[46:49]
	v_mfma_f32_16x16x32_bf16 v[22:25], v[184:187], v[226:229], v[22:25]
	v_mfma_f32_16x16x32_bf16 v[18:21], v[210:213], v[226:229], v[18:21]
	v_mfma_f32_16x16x32_bf16 v[6:9], v[184:187], v[234:237], v[6:9]
	v_mfma_f32_16x16x32_bf16 v[2:5], v[210:213], v[234:237], v[2:5]
	v_mfma_f32_16x16x32_bf16 v[66:69], v[214:217], v[222:225], v[34:37]
	v_mfma_f32_16x16x32_bf16 v[22:25], v[192:195], v[230:233], v[22:25]
	v_mfma_f32_16x16x32_bf16 v[18:21], v[214:217], v[230:233], v[18:21]
	v_mfma_f32_16x16x32_bf16 v[6:9], v[192:195], v[238:241], v[6:9]
	v_mfma_f32_16x16x32_bf16 v[2:5], v[214:217], v[238:241], v[2:5]
	s_setprio 0
	s_barrier
	s_add_i32 s55, s55, 2
	s_add_u32 s37, s37, 0x100
	s_addc_u32 s54, s54, 0
	s_cmpk_gt_u32 s55, 0x55
	s_mov_b64 s[6:7], s[8:9]
	s_cbranch_scc0 .LBB0_2340
	s_and_b64 vcc, exec, s[44:45]
	s_cbranch_vccz .LBB0_2343
	s_barrier

; #define PG8_STAGE(bufoff, gbase, voff) do { _Pragma("unroll") for (int _i = 0; _i < 2; ++_i) \
;         __builtin_amdgcn_global_load_lds((const unsigned*)((const char*)(gbase) + (voff)[_i]), (PG8_LAS unsigned*)(lds + (bufoff) + ldsw + _i * 8192), 16, 0, 0); } while (0)
; #define PG8_LDA(dst, b, h) do { _Pragma("unroll") for (int m = 0; m < 4; ++m) _Pragma("unroll") for (int k = 0; k < 2; ++k) dst[m][k] = *(const PG8_LAS bf16x8*)(lds + PG8_SA(b, h) + aoff + m * 2048 + k * 1024); } while (0)
; #define PG8_LDB(dst, b, h) do { _Pragma("unroll") for (int n = 0; n < 2; ++n) _Pragma("unroll") for (int k = 0; k < 2; ++k) dst[n][k] = *(const PG8_LAS bf16x8*)(lds + PG8_SB(b, h) + boff + n * 2048 + k * 1024); } while (0)
; #define PG8_WAIT_V(n) asm volatile("s_waitcnt vmcnt(" #n ")" ::: "memory")
; #define PG8_WAIT_L(n) asm volatile("s_waitcnt lgkmcnt(" #n ")" ::: "memory")
; #define PG8_BAR __builtin_amdgcn_s_barrier()
; #define PG8_SCHED __builtin_amdgcn_sched_barrier(0)
; template <class Epi, class Sched, bool ALIGN_EPI = false, bool SP2 = false>
; __device__ __forceinline__ void gemm_phase(PG8_LAS unsigned char* lds, const Gemm g, const Sched& S, const Epi& E) {
;     ...
;         const char* nA = has_next ? (const char*)g.A + (size_t)nxt.pm * tstepA + ((size_t)(nxt.z / g.zdiv) * g.zA + (size_t)(nxt.z % g.zdiv) * g.zA2) * 2 : cA; const char* nB = has_next ? (const char*)g.Bt + (size_t)nxt.pn * tstepB + ((size_t)(nxt.z / g.zdiv) * g.zB + (size_t)(nxt.z % g.zdiv) * g.zB2) * 2 : cB;
;         for (int t = 0; t < nt; t += 2) {
;             const bool last = (t == nt - 2);
;             const char* a1 = cA + (size_t)(t + 1) * kstep;
;             const char* a2 = last ? nA : cA + (size_t)(t + 2) * kstep; const char* b2 = last ? nB : cB + (size_t)(t + 2) * kstep;
;             const char* a3 = a2 + kstep; const char* b3 = b2 + kstep;
;             if (last && has_next) S.a_ready(nxt);
;             if constexpr (SP2) {
;             PG8_LDB(B0, 0, 0); PG8_LDB(B1, 0, 1); PG8_SCHED; PG8_LDA(At, 0, 0); PG8_STAGE(PG8_SA(1, 1), a1 + hstepA, voffA);
;             PG8_WAIT_V(8); PG8_WAIT_L(0); PG8_BAR; PG8_MMA(0, 0, At, B0); PG8_MMA(0, 1, At, B1); PG8_BAR; PG8_SCHED;
;             PG8_LDA(At, 0, 1); PG8_STAGE(PG8_SB(0, 0), b2, voffB); PG8_STAGE(PG8_SB(0, 1), b2 + hstepB, voffB); PG8_STAGE(PG8_SA(0, 0), a2, voffA);
.LBB0_2360:
	s_add_u32 s25, s16, s24
	s_addc_u32 s28, s17, 0
	s_add_u32 s29, s25, 0x100
	s_addc_u32 s30, s28, 0
	s_and_b64 s[26:27], s[22:23], exec
	s_cselect_b32 s39, s5, s30
	s_cselect_b32 s38, s4, s29
	s_add_u32 s24, s6, s24
	s_addc_u32 s26, s7, 0
	s_add_u32 s24, s24, 0x100
	s_addc_u32 s26, s26, 0
	s_add_i32 s27, 0, 0x10000
	s_and_b64 s[22:23], s[22:23], exec
	s_cselect_b32 s41, s19, s26
	s_cselect_b32 s40, s18, s24
	s_add_i32 s23, 0, 0x14000
	s_add_u32 s44, s25, 0x160080
	s_addc_u32 s45, s28, 0
	s_add_i32 s28, s27, s34
	s_add_i32 m0, s46, 0xc000
	s_add_i32 s26, s46, 0xe000
	s_add_i32 s29, s28, 0x2000
	s_add_u32 s42, s40, 0x160000
	v_add_u32_e32 v90, s27, v1
	v_add_u32_e32 v106, s23, v1
	s_addc_u32 s43, s41, 0
	s_add_i32 s30, s23, s34
	ds_read_b128 v[78:81], v90
	ds_read_b128 v[82:85], v90 offset:1024
	ds_read_b128 v[86:89], v90 offset:2048
	ds_read_b128 v[90:93], v90 offset:3072
	ds_read_b128 v[94:97], v106
	ds_read_b128 v[98:101], v106 offset:1024
	ds_read_b128 v[102:105], v106 offset:2048
	ds_read_b128 v[106:109], v106 offset:3072
	s_add_i32 s31, s30, 0x2000
	s_add_i32 s93, 0, 0x18000
	s_add_i32 s95, 0, 0x1c000
	s_add_u32 s36, s38, 0x160000
	s_addc_u32 s37, s39, 0
	s_add_i32 s25, s93, s34
	s_add_i32 s24, s25, 0x2000
	s_add_u32 s22, s40, 0x160080
	s_addc_u32 s23, s41, 0
	s_add_i32 s27, s95, s34
	s_add_i32 s96, s27, 0x2000
	v_lshl_add_u64 v[142:143], s[44:45], 0, v[162:163]
	ds_read_b128 v[110:113], v77
	ds_read_b128 v[114:117], v77 offset:1024
	ds_read_b128 v[118:121], v77 offset:2048
	ds_read_b128 v[122:125], v77 offset:3072
	ds_read_b128 v[126:129], v77 offset:4096
	ds_read_b128 v[130:133], v77 offset:5120
	ds_read_b128 v[134:137], v77 offset:6144
	ds_read_b128 v[138:141], v77 offset:7168
	global_load_lds_dwordx4 v[142:143], off
	v_lshl_add_u64 v[142:143], s[44:45], 0, v[66:67]
	s_mov_b32 m0, s26
	s_nop 0
	global_load_lds_dwordx4 v[142:143], off
	s_waitcnt vmcnt(8)
	s_waitcnt lgkmcnt(0)
	s_barrier
	s_setprio 1
	s_waitcnt lgkmcnt(0)
	v_mfma_f32_16x16x32_bf16 v[62:65], v[78:81], v[110:113], v[62:65]
	v_mfma_f32_16x16x32_bf16 v[58:61], v[86:89], v[110:113], v[58:61]
	v_mfma_f32_16x16x32_bf16 v[54:57], v[78:81], v[118:121], v[54:57]
	v_mfma_f32_16x16x32_bf16 v[50:53], v[86:89], v[118:121], v[50:53]
	v_mfma_f32_16x16x32_bf16 v[46:49], v[78:81], v[126:129], v[46:49]
	v_mfma_f32_16x16x32_bf16 v[42:45], v[86:89], v[126:129], v[42:45]
	v_mfma_f32_16x16x32_bf16 v[30:33], v[78:81], v[134:137], v[30:33]
	v_mfma_f32_16x16x32_bf16 v[26:29], v[86:89], v[134:137], v[26:29]
	v_mfma_f32_16x16x32_bf16 v[62:65], v[82:85], v[114:117], v[62:65]
	v_mfma_f32_16x16x32_bf16 v[58:61], v[90:93], v[114:117], v[58:61]
	v_mfma_f32_16x16x32_bf16 v[54:57], v[82:85], v[122:125], v[54:57]
	v_mfma_f32_16x16x32_bf16 v[50:53], v[90:93], v[122:125], v[50:53]
	v_mfma_f32_16x16x32_bf16 v[46:49], v[82:85], v[130:133], v[46:49]
	v_mfma_f32_16x16x32_bf16 v[42:45], v[90:93], v[130:133], v[42:45]
	v_mfma_f32_16x16x32_bf16 v[30:33], v[82:85], v[138:141], v[30:33]
	v_mfma_f32_16x16x32_bf16 v[26:29], v[90:93], v[138:141], v[26:29]
	v_mfma_f32_16x16x32_bf16 v[38:41], v[94:97], v[110:113], v[38:41]
	v_mfma_f32_16x16x32_bf16 v[34:37], v[102:105], v[110:113], v[34:37]
	v_mfma_f32_16x16x32_bf16 v[22:25], v[94:97], v[118:121], v[22:25]
	v_mfma_f32_16x16x32_bf16 v[18:21], v[102:105], v[118:121], v[18:21]
	v_mfma_f32_16x16x32_bf16 v[14:17], v[94:97], v[126:129], v[14:17]
	v_mfma_f32_16x16x32_bf16 v[10:13], v[102:105], v[126:129], v[10:13]
	v_mfma_f32_16x16x32_bf16 v[6:9], v[94:97], v[134:137], v[6:9]
	v_mfma_f32_16x16x32_bf16 v[2:5], v[102:105], v[134:137], v[2:5]
	v_mfma_f32_16x16x32_bf16 v[38:41], v[98:101], v[114:117], v[38:41]
	v_mfma_f32_16x16x32_bf16 v[34:37], v[106:109], v[114:117], v[34:37]
	v_mfma_f32_16x16x32_bf16 v[22:25], v[98:101], v[122:125], v[22:25]
	v_mfma_f32_16x16x32_bf16 v[18:21], v[106:109], v[122:125], v[18:21]
	v_mfma_f32_16x16x32_bf16 v[14:17], v[98:101], v[130:133], v[14:17]
	v_mfma_f32_16x16x32_bf16 v[10:13], v[106:109], v[130:133], v[10:13]
	v_mfma_f32_16x16x32_bf16 v[6:9], v[98:101], v[138:141], v[6:9]
	v_mfma_f32_16x16x32_bf16 v[2:5], v[106:109], v[138:141], v[2:5]
	s_setprio 0
	s_barrier
	s_mov_b32 m0, s28
	v_lshl_add_u64 v[142:143], s[40:41], 0, v[162:163]
	global_load_lds_dwordx4 v[142:143], off
	v_lshl_add_u64 v[144:145], s[40:41], 0, v[66:67]
	s_mov_b32 m0, s29
	v_lshl_add_u64 v[78:79], s[42:43], 0, v[162:163]
	global_load_lds_dwordx4 v[144:145], off
	s_mov_b32 m0, s30
	v_lshl_add_u64 v[146:147], s[38:39], 0, v[162:163]
	global_load_lds_dwordx4 v[78:79], off
	v_lshl_add_u64 v[78:79], s[42:43], 0, v[66:67]
	s_mov_b32 m0, s31
	v_lshl_add_u64 v[148:149], s[38:39], 0, v[66:67]
	global_load_lds_dwordx4 v[78:79], off
	s_mov_b32 m0, s46
	s_nop 0
	global_load_lds_dwordx4 v[146:147], off
	s_mov_b32 m0, s47
	s_nop 0
	global_load_lds_dwordx4 v[148:149], off
	s_waitcnt vmcnt(8)
	s_waitcnt lgkmcnt(0)
	s_barrier
; #define PG8_STAGE(bufoff, gbase, voff) do { _Pragma("unroll") for (int _i = 0; _i < 2; ++_i) \
;         __builtin_amdgcn_global_load_lds((const unsigned*)((const char*)(gbase) + (voff)[_i]), (PG8_LAS unsigned*)(lds + (bufoff) + ldsw + _i * 8192), 16, 0, 0); } while (0)
; #define PG8_LDA(dst, b, h) do { _Pragma("unroll") for (int m = 0; m < 4; ++m) _Pragma("unroll") for (int k = 0; k < 2; ++k) dst[m][k] = *(const PG8_LAS bf16x8*)(lds + PG8_SA(b, h) + aoff + m * 2048 + k * 1024); } while (0)
; #define PG8_LDB(dst, b, h) do { _Pragma("unroll") for (int n = 0; n < 2; ++n) _Pragma("unroll") for (int k = 0; k < 2; ++k) dst[n][k] = *(const PG8_LAS bf16x8*)(lds + PG8_SB(b, h) + boff + n * 2048 + k * 1024); } while (0)
; #define PG8_MMA(ai, bj, At, Bt) do { __builtin_amdgcn_s_setprio(1); _Pragma("unroll") for (int m = 0; m < 4; ++m) _Pragma("unroll") for (int n = 0; n < 2; ++n) _Pragma("unroll") for (int k = 0; k < 2; ++k) \
;         acc[ai][bj][m][n] = __builtin_amdgcn_mfma_f32_16x16x32_bf16(Bt[n][k], At[m][k], acc[ai][bj][m][n], 0, 0, 0); __builtin_amdgcn_s_setprio(0); } while (0)
; #define PG8_WAIT_V(n) asm volatile("s_waitcnt vmcnt(" #n ")" ::: "memory")
; #define PG8_WAIT_L(n) asm volatile("s_waitcnt lgkmcnt(" #n ")" ::: "memory")
; #define PG8_BAR __builtin_amdgcn_s_barrier()
; #define PG8_SCHED __builtin_amdgcn_sched_barrier(0)
; template <class Epi, class Sched, bool ALIGN_EPI = false, bool SP2 = false>
; __device__ __forceinline__ void gemm_phase(PG8_LAS unsigned char* lds, const Gemm g, const Sched& S, const Epi& E) {
;     ...
;             PG8_WAIT_V(8); PG8_WAIT_L(0); PG8_BAR; PG8_MMA(1, 0, At, B0); PG8_MMA(1, 1, At, B1); PG8_BAR; PG8_SCHED;
;             PG8_LDB(B0, 1, 0); PG8_LDB(B1, 1, 1); PG8_SCHED; PG8_LDA(At, 1, 0); PG8_STAGE(PG8_SA(0, 1), a2 + hstepA, voffA);
;             PG8_WAIT_V(8); PG8_WAIT_L(0); PG8_BAR; PG8_MMA(0, 0, At, B0); PG8_MMA(0, 1, At, B1); PG8_BAR; PG8_SCHED;
;             PG8_LDA(At, 1, 1); PG8_STAGE(PG8_SB(1, 0), b3, voffB); PG8_STAGE(PG8_SB(1, 1), b3 + hstepB, voffB); PG8_STAGE(PG8_SA(1, 0), a3, voffA);
;             PG8_WAIT_V(8); PG8_WAIT_L(0); PG8_BAR; PG8_MMA(1, 0, At, B0); PG8_MMA(1, 1, At, B1); PG8_BAR; PG8_SCHED;
	s_setprio 1
	s_setprio 0
	s_barrier
	v_add_u32_e32 v90, s93, v1
	v_add_u32_e32 v106, s95, v1
	ds_read_b128 v[78:81], v90
	ds_read_b128 v[82:85], v90 offset:1024
	ds_read_b128 v[86:89], v90 offset:2048
	ds_read_b128 v[90:93], v90 offset:3072
	ds_read_b128 v[94:97], v106
	ds_read_b128 v[98:101], v106 offset:1024
	ds_read_b128 v[102:105], v106 offset:2048
	ds_read_b128 v[106:109], v106 offset:3072
	s_mov_b32 m0, s54
	v_lshl_add_u64 v[150:151], s[36:37], 0, v[162:163]
	ds_read_b128 v[110:113], v77 offset:32768
	ds_read_b128 v[114:117], v77 offset:33792
	ds_read_b128 v[118:121], v77 offset:34816
	ds_read_b128 v[122:125], v77 offset:35840
	ds_read_b128 v[126:129], v77 offset:36864
	ds_read_b128 v[130:133], v77 offset:37888
	ds_read_b128 v[134:137], v77 offset:38912
	ds_read_b128 v[138:141], v77 offset:39936
	global_load_lds_dwordx4 v[150:151], off
	v_lshl_add_u64 v[150:151], s[36:37], 0, v[66:67]
	s_mov_b32 m0, s55
	s_nop 0
	global_load_lds_dwordx4 v[150:151], off
	s_waitcnt vmcnt(8)
	s_waitcnt lgkmcnt(0)
	s_barrier
	s_setprio 1
	s_waitcnt lgkmcnt(0)
	v_mfma_f32_16x16x32_bf16 v[62:65], v[78:81], v[110:113], v[62:65]
	v_mfma_f32_16x16x32_bf16 v[58:61], v[86:89], v[110:113], v[58:61]
	v_mfma_f32_16x16x32_bf16 v[54:57], v[78:81], v[118:121], v[54:57]
	v_mfma_f32_16x16x32_bf16 v[50:53], v[86:89], v[118:121], v[50:53]
	v_mfma_f32_16x16x32_bf16 v[46:49], v[78:81], v[126:129], v[46:49]
	v_mfma_f32_16x16x32_bf16 v[42:45], v[86:89], v[126:129], v[42:45]
	v_mfma_f32_16x16x32_bf16 v[30:33], v[78:81], v[134:137], v[30:33]
	v_mfma_f32_16x16x32_bf16 v[26:29], v[86:89], v[134:137], v[26:29]
	v_mfma_f32_16x16x32_bf16 v[62:65], v[82:85], v[114:117], v[62:65]
	v_mfma_f32_16x16x32_bf16 v[58:61], v[90:93], v[114:117], v[58:61]
	v_mfma_f32_16x16x32_bf16 v[54:57], v[82:85], v[122:125], v[54:57]
	v_mfma_f32_16x16x32_bf16 v[50:53], v[90:93], v[122:125], v[50:53]
	v_mfma_f32_16x16x32_bf16 v[46:49], v[82:85], v[130:133], v[46:49]
	v_mfma_f32_16x16x32_bf16 v[42:45], v[90:93], v[130:133], v[42:45]
	v_mfma_f32_16x16x32_bf16 v[30:33], v[82:85], v[138:141], v[30:33]
	v_mfma_f32_16x16x32_bf16 v[26:29], v[90:93], v[138:141], v[26:29]
	v_mfma_f32_16x16x32_bf16 v[38:41], v[94:97], v[110:113], v[38:41]
	v_mfma_f32_16x16x32_bf16 v[34:37], v[102:105], v[110:113], v[34:37]
	v_mfma_f32_16x16x32_bf16 v[22:25], v[94:97], v[118:121], v[22:25]
	v_mfma_f32_16x16x32_bf16 v[18:21], v[102:105], v[118:121], v[18:21]
	v_mfma_f32_16x16x32_bf16 v[14:17], v[94:97], v[126:129], v[14:17]
	v_mfma_f32_16x16x32_bf16 v[10:13], v[102:105], v[126:129], v[10:13]
	v_mfma_f32_16x16x32_bf16 v[6:9], v[94:97], v[134:137], v[6:9]
	v_mfma_f32_16x16x32_bf16 v[2:5], v[102:105], v[134:137], v[2:5]
	v_mfma_f32_16x16x32_bf16 v[38:41], v[98:101], v[114:117], v[38:41]
	v_mfma_f32_16x16x32_bf16 v[34:37], v[106:109], v[114:117], v[34:37]
	v_mfma_f32_16x16x32_bf16 v[22:25], v[98:101], v[122:125], v[22:25]
	v_mfma_f32_16x16x32_bf16 v[18:21], v[106:109], v[122:125], v[18:21]
	v_mfma_f32_16x16x32_bf16 v[14:17], v[98:101], v[130:133], v[14:17]
	v_mfma_f32_16x16x32_bf16 v[10:13], v[106:109], v[130:133], v[10:13]
	v_mfma_f32_16x16x32_bf16 v[6:9], v[98:101], v[138:141], v[6:9]
	v_mfma_f32_16x16x32_bf16 v[2:5], v[106:109], v[138:141], v[2:5]
	s_setprio 0
	s_barrier
	s_mov_b32 m0, s25
	v_lshl_add_u64 v[78:79], v[142:143], 0, s[50:51]
	global_load_lds_dwordx4 v[78:79], off
	v_lshl_add_u64 v[78:79], v[144:145], 0, s[50:51]
	s_mov_b32 m0, s24
	s_nop 0
	global_load_lds_dwordx4 v[78:79], off
	v_lshl_add_u64 v[78:79], s[22:23], 0, v[162:163]
	s_mov_b32 m0, s27
	s_nop 0
	global_load_lds_dwordx4 v[78:79], off
	v_lshl_add_u64 v[78:79], s[22:23], 0, v[66:67]
	s_mov_b32 m0, s96
	s_nop 0
	global_load_lds_dwordx4 v[78:79], off
	v_lshl_add_u64 v[78:79], v[146:147], 0, s[50:51]
	s_mov_b32 m0, s56
	s_nop 0
	global_load_lds_dwordx4 v[78:79], off
	v_lshl_add_u64 v[78:79], v[148:149], 0, s[50:51]
	s_mov_b32 m0, s57
	s_nop 0
	global_load_lds_dwordx4 v[78:79], off
	s_waitcnt vmcnt(8)
	s_waitcnt lgkmcnt(0)
	s_barrier
	s_setprio 1
	s_setprio 0
	s_barrier
	s_movk_i32 s24, 0x100
	s_andn2_b64 vcc, exec, s[20:21]
	s_mov_b64 s[22:23], -1
	s_mov_b64 s[20:21], 0
	s_cbranch_vccz .LBB0_2360
	s_and_b64 vcc, exec, s[10:11]
	s_cbranch_vccz .LBB0_2363
	s_barrier
